# core: ds_reads issued right after barrier, DMA issue interleaved between MFMAs
# speedup vs baseline: 1.0876x; 1.0192x over previous
; #define MFMA32(a, b, c) __builtin_amdgcn_mfma_f32_32x32x16_bf16((a), (b), (c), 0, 0, 0)
; #define GA_LOAD(pr_) do { _Pragma("unroll") for (int i = 0; i < 4; ++i) ra[i] = *(const u32x4*)(Ab + (i * 32) * lda + (pr_) * 64); } while (0)
; #define GB_LOAD(kt_) do { const bfr* bk_ = Bb + (kt_) * NB * 32; \
;     _Pragma("unroll") for (int i = 0; i < 4; ++i) rb[i] = *(const u32x4*)(bk_ + (i * 64) * 32); } while (0)
; #define G_STORE(kt_) do { bfr* as_ = S0 + ((kt_) & 1) * GSTAGE; bfr* bs_ = as_ + 128 * 40; \
;     if (apar == ((kt_) & 1)) { _Pragma("unroll") for (int i = 0; i < 4; ++i) *(u32x4*)(as_ + asoff + i * 32 * 40) = ra[i]; } \
;     _Pragma("unroll") for (int i = 0; i < 4; ++i) *(u32x4*)(bs_ + bsoff + i * 64 * 40) = rb[i]; } while (0)
; template <int lda>
; DI void gemm_mainloop(const bfr* __restrict__ A, const bfr* __restrict__ Bt, int NB, int K, int m0, int n0, char* smem, f32x16 (&acc)[2][4]) {
;     ...
;   for (int kt = 0; kt < nk; ++kt) {
;     if (kt + 1 < nk) G_STORE(kt + 1);
;     if (kt + 2 < nk) {
;       GB_LOAD(kt + 2);
;       if ((kt & 1) == 0) GA_LOAD((kt >> 1) + 1);
;     }
;     const bfr* As = S0 + (kt & 1) * GSTAGE;
;     const bfr* Bs = As + 128 * 40;
; #pragma unroll
;     for (int ks = 0; ks < 2; ++ks) {
;       bf16x8 af[2], bfg[4];
; #pragma unroll
;       for (int i = 0; i < 2; ++i) af[i] = *(const bf16x8*)(As + (wr * 64 + i * 32 + r) * 40 + ks * 16 + hl * 8);
; #pragma unroll
;       for (int j = 0; j < 4; ++j) bfg[j] = *(const bf16x8*)(Bs + (wc * 128 + j * 32 + r) * 40 + ks * 16 + hl * 8);
; #pragma unroll
;       for (int i = 0; i < 2; ++i)
; #pragma unroll
;         for (int j = 0; j < 4; ++j) acc[i][j] = MFMA32(af[i], bfg[j], acc[i][j]);
;     }
;     __syncthreads();
;   }
.Lp1v_loop:
	s_waitcnt vmcnt(6)
	s_barrier
	s_mul_i32 s74, s71, 0x6000
	s_add_u32 s75, s74, 0x2000
	s_cmp_eq_u32 s71, 2
	s_cselect_b32 s75, 0x10000, s75
	v_add_u32_e32 v184, s74, v180
	v_add_u32_e32 v186, s75, v182
	v_add_u32_e32 v185, s74, v181
	v_add_u32_e32 v187, s75, v183
	ds_read_b128 v[128:131], v184
	ds_read_b128 v[144:147], v186
	ds_read_b128 v[148:151], v186 offset:2048
	ds_read_b128 v[152:155], v186 offset:4096
	ds_read_b128 v[156:159], v186 offset:6144
	ds_read_b128 v[132:135], v184 offset:2048
	ds_read_b128 v[136:139], v185
	ds_read_b128 v[164:167], v187
	ds_read_b128 v[168:171], v187 offset:2048
	ds_read_b128 v[172:175], v187 offset:4096
	ds_read_b128 v[176:179], v187 offset:6144
	ds_read_b128 v[140:143], v185 offset:2048
	s_add_u32 s71, s71, 1
	s_cmp_eq_u32 s71, 3
	s_cselect_b32 s71, 0, s71
	s_waitcnt lgkmcnt(10)
	v_mfma_f32_32x32x16_bf16 v[112:127], v[128:131], v[144:147], v[112:127]
	s_mul_i32 s74, s70, 0x6000
	s_add_u32 s75, s74, s68
	s_mov_b32 m0, s75
	s_add_u32 s76, s74, 0x2000
	s_cmp_eq_u32 s70, 2
	s_cselect_b32 s76, 0x10000, s76
	global_load_lds_dwordx4 v160, s[64:65]
	s_waitcnt lgkmcnt(9)
	v_mfma_f32_32x32x16_bf16 v[96:111], v[128:131], v[148:151], v[96:111]
	s_add_u32 m0, s75, 0x400
	s_add_u32 s76, s76, s69
	global_load_lds_dwordx4 v162, s[64:65]
	s_waitcnt lgkmcnt(8)
	v_mfma_f32_32x32x16_bf16 v[80:95], v[128:131], v[152:155], v[80:95]
	s_mov_b32 m0, s76
	s_add_u32 s64, s64, 64
	s_addc_u32 s65, s65, 0
	global_load_lds_dwordx4 v163, s[66:67]
	s_waitcnt lgkmcnt(7)
	v_mfma_f32_32x32x16_bf16 v[64:79], v[128:131], v[156:159], v[64:79]
	global_load_lds_dwordx4 v163, s[66:67] offset:1024
	s_waitcnt lgkmcnt(6)
	v_mfma_f32_32x32x16_bf16 v[48:63], v[132:135], v[144:147], v[48:63]
	global_load_lds_dwordx4 v163, s[66:67] offset:2048
	v_mfma_f32_32x32x16_bf16 v[32:47], v[132:135], v[148:151], v[32:47]
	global_load_lds_dwordx4 v163, s[66:67] offset:3072
	s_add_u32 s66, s66, 0x10000
	s_addc_u32 s67, s67, 0
	v_mfma_f32_32x32x16_bf16 v[16:31], v[132:135], v[152:155], v[16:31]
	s_add_u32 s70, s70, 1
	s_cmp_eq_u32 s70, 3
	s_cselect_b32 s70, 0, s70
	v_mfma_f32_32x32x16_bf16 v[0:15], v[132:135], v[156:159], v[0:15]
	s_waitcnt lgkmcnt(4)
	v_mfma_f32_32x32x16_bf16 v[112:127], v[136:139], v[164:167], v[112:127]
	s_waitcnt lgkmcnt(3)
	v_mfma_f32_32x32x16_bf16 v[96:111], v[136:139], v[168:171], v[96:111]
	s_waitcnt lgkmcnt(2)
	v_mfma_f32_32x32x16_bf16 v[80:95], v[136:139], v[172:175], v[80:95]
	s_waitcnt lgkmcnt(1)
	v_mfma_f32_32x32x16_bf16 v[64:79], v[136:139], v[176:179], v[64:79]
	s_waitcnt lgkmcnt(0)
	v_mfma_f32_32x32x16_bf16 v[48:63], v[140:143], v[164:167], v[48:63]
	v_mfma_f32_32x32x16_bf16 v[32:47], v[140:143], v[168:171], v[32:47]
	v_mfma_f32_32x32x16_bf16 v[16:31], v[140:143], v[172:175], v[16:31]
	v_mfma_f32_32x32x16_bf16 v[0:15], v[140:143], v[176:179], v[0:15]
	s_add_u32 s72, s72, 1
	s_cmp_lt_u32 s72, 30
	s_cbranch_scc1 .Lp1v_loop
	s_waitcnt vmcnt(6)
	s_barrier
	s_mul_i32 s74, s71, 0x6000
	s_add_u32 s75, s74, 0x2000
	s_cmp_eq_u32 s71, 2
	s_cselect_b32 s75, 0x10000, s75
	v_add_u32_e32 v184, s74, v180
	v_add_u32_e32 v186, s75, v182
	v_add_u32_e32 v185, s74, v181
	v_add_u32_e32 v187, s75, v183
	ds_read_b128 v[128:131], v184
	ds_read_b128 v[144:147], v186
	ds_read_b128 v[148:151], v186 offset:2048
	ds_read_b128 v[152:155], v186 offset:4096
	ds_read_b128 v[156:159], v186 offset:6144
	ds_read_b128 v[132:135], v184 offset:2048
	ds_read_b128 v[136:139], v185
	ds_read_b128 v[164:167], v187
	ds_read_b128 v[168:171], v187 offset:2048
	ds_read_b128 v[172:175], v187 offset:4096
	ds_read_b128 v[176:179], v187 offset:6144
	ds_read_b128 v[140:143], v185 offset:2048
	s_add_u32 s71, s71, 1
	s_cmp_eq_u32 s71, 3
	s_cselect_b32 s71, 0, s71
	s_waitcnt lgkmcnt(10)
	v_mfma_f32_32x32x16_bf16 v[112:127], v[128:131], v[144:147], v[112:127]
	s_waitcnt lgkmcnt(9)
	v_mfma_f32_32x32x16_bf16 v[96:111], v[128:131], v[148:151], v[96:111]
	s_waitcnt lgkmcnt(8)
	v_mfma_f32_32x32x16_bf16 v[80:95], v[128:131], v[152:155], v[80:95]
	s_waitcnt lgkmcnt(7)
	v_mfma_f32_32x32x16_bf16 v[64:79], v[128:131], v[156:159], v[64:79]
	s_waitcnt lgkmcnt(6)
	v_mfma_f32_32x32x16_bf16 v[48:63], v[132:135], v[144:147], v[48:63]
	v_mfma_f32_32x32x16_bf16 v[32:47], v[132:135], v[148:151], v[32:47]
	v_mfma_f32_32x32x16_bf16 v[16:31], v[132:135], v[152:155], v[16:31]
	v_mfma_f32_32x32x16_bf16 v[0:15], v[132:135], v[156:159], v[0:15]
	s_waitcnt lgkmcnt(4)
	v_mfma_f32_32x32x16_bf16 v[112:127], v[136:139], v[164:167], v[112:127]
	s_waitcnt lgkmcnt(3)
	v_mfma_f32_32x32x16_bf16 v[96:111], v[136:139], v[168:171], v[96:111]
	s_waitcnt lgkmcnt(2)
	v_mfma_f32_32x32x16_bf16 v[80:95], v[136:139], v[172:175], v[80:95]
	s_waitcnt lgkmcnt(1)
	v_mfma_f32_32x32x16_bf16 v[64:79], v[136:139], v[176:179], v[64:79]
	s_waitcnt lgkmcnt(0)
	v_mfma_f32_32x32x16_bf16 v[48:63], v[140:143], v[164:167], v[48:63]
	v_mfma_f32_32x32x16_bf16 v[32:47], v[140:143], v[168:171], v[32:47]
	v_mfma_f32_32x32x16_bf16 v[16:31], v[140:143], v[172:175], v[16:31]
	v_mfma_f32_32x32x16_bf16 v[0:15], v[140:143], v[176:179], v[0:15]
	s_waitcnt vmcnt(0)
	s_barrier
; #define MFMA32(a, b, c) __builtin_amdgcn_mfma_f32_32x32x16_bf16((a), (b), (c), 0, 0, 0)
; DI int crow(int reg, int h) { return (reg & 3) + 8 * (reg >> 2) + 4 * h; }
; template <int lda>
; DI void gemm_mainloop(const bfr* __restrict__ A, const bfr* __restrict__ Bt, int NB, int K, int m0, int n0, char* smem, f32x16 (&acc)[2][4]) {
;     ...
;     for (int ks = 0; ks < 2; ++ks) {
;       bf16x8 af[2], bfg[4];
; #pragma unroll
;       for (int i = 0; i < 2; ++i) af[i] = *(const bf16x8*)(As + (wr * 64 + i * 32 + r) * 40 + ks * 16 + hl * 8);
; #pragma unroll
;       for (int j = 0; j < 4; ++j) bfg[j] = *(const bf16x8*)(Bs + (wc * 128 + j * 32 + r) * 40 + ks * 16 + hl * 8);
; #pragma unroll
;       for (int i = 0; i < 2; ++i)
; #pragma unroll
;         for (int j = 0; j < 4; ++j) acc[i][j] = MFMA32(af[i], bfg[j], acc[i][j]);
;     }
; template <int lda, class Epi>
; DI void gemm_tile(const bfr* __restrict__ A, const bfr* __restrict__ Bt, int NB, int K, int m0, int n0, char* smem, Epi epi) {
;     ...
; #pragma unroll
;   for (int i = 0; i < 2; ++i)
; #pragma unroll
;     for (int j = 0; j < 4; ++j)
; #pragma unroll
;       for (int q = 0; q < 16; ++q) {
;         int row = m0 + wr * 64 + i * 32 + crow(q, hl);
;         int col = n0 + wc * 128 + j * 32 + r;
;         epi(row, col, acc[i][j][q]);
;       }
	s_mul_i32 s74, s71, 0x6000
	s_add_u32 s75, s74, 0x2000
	s_cmp_eq_u32 s71, 2
	s_cselect_b32 s75, 0x10000, s75
	v_add_u32_e32 v184, s74, v180
	v_add_u32_e32 v186, s75, v182
	v_add_u32_e32 v185, s74, v181
	v_add_u32_e32 v187, s75, v183
	ds_read_b128 v[128:131], v184
	ds_read_b128 v[144:147], v186
	ds_read_b128 v[148:151], v186 offset:2048
	ds_read_b128 v[152:155], v186 offset:4096
	ds_read_b128 v[156:159], v186 offset:6144
	ds_read_b128 v[132:135], v184 offset:2048
	ds_read_b128 v[136:139], v185
	ds_read_b128 v[164:167], v187
	ds_read_b128 v[168:171], v187 offset:2048
	ds_read_b128 v[172:175], v187 offset:4096
	ds_read_b128 v[176:179], v187 offset:6144
	ds_read_b128 v[140:143], v185 offset:2048
	s_add_u32 s71, s71, 1
	s_cmp_eq_u32 s71, 3
	s_cselect_b32 s71, 0, s71
	s_waitcnt lgkmcnt(10)
	v_mfma_f32_32x32x16_bf16 v[112:127], v[128:131], v[144:147], v[112:127]
	s_waitcnt lgkmcnt(9)
	v_mfma_f32_32x32x16_bf16 v[96:111], v[128:131], v[148:151], v[96:111]
	s_waitcnt lgkmcnt(8)
	v_mfma_f32_32x32x16_bf16 v[80:95], v[128:131], v[152:155], v[80:95]
	s_waitcnt lgkmcnt(7)
	v_mfma_f32_32x32x16_bf16 v[64:79], v[128:131], v[156:159], v[64:79]
	s_waitcnt lgkmcnt(6)
	v_mfma_f32_32x32x16_bf16 v[48:63], v[132:135], v[144:147], v[48:63]
	v_mfma_f32_32x32x16_bf16 v[32:47], v[132:135], v[148:151], v[32:47]
	v_mfma_f32_32x32x16_bf16 v[16:31], v[132:135], v[152:155], v[16:31]
	v_mfma_f32_32x32x16_bf16 v[0:15], v[132:135], v[156:159], v[0:15]
	s_waitcnt lgkmcnt(4)
	v_mfma_f32_32x32x16_bf16 v[112:127], v[136:139], v[164:167], v[112:127]
	s_waitcnt lgkmcnt(3)
	v_mfma_f32_32x32x16_bf16 v[96:111], v[136:139], v[168:171], v[96:111]
	s_waitcnt lgkmcnt(2)
	v_mfma_f32_32x32x16_bf16 v[80:95], v[136:139], v[172:175], v[80:95]
	s_waitcnt lgkmcnt(1)
	v_mfma_f32_32x32x16_bf16 v[64:79], v[136:139], v[176:179], v[64:79]
	s_waitcnt lgkmcnt(0)
	v_mfma_f32_32x32x16_bf16 v[48:63], v[140:143], v[164:167], v[48:63]
	v_mfma_f32_32x32x16_bf16 v[32:47], v[140:143], v[168:171], v[32:47]
	v_mfma_f32_32x32x16_bf16 v[16:31], v[140:143], v[172:175], v[16:31]
	v_mfma_f32_32x32x16_bf16 v[0:15], v[140:143], v[176:179], v[0:15]
	s_nop 7
	v_readlane_b32 s64, v188, 0
	v_readlane_b32 s65, v188, 1
	v_readlane_b32 s66, v188, 2
	v_readlane_b32 s67, v188, 3
	v_readlane_b32 s68, v188, 4
	v_readlane_b32 s69, v188, 5
	v_readlane_b32 s70, v188, 6
	v_readlane_b32 s71, v188, 7
	v_readlane_b32 s72, v188, 8
	v_readlane_b32 s73, v188, 9
	v_readlane_b32 s74, v188, 10
	v_readlane_b32 s75, v188, 11
	v_readlane_b32 s76, v188, 12
	v_readlane_b32 s77, v188, 13
	v_readlane_b32 s78, v188, 14
	v_readlane_b32 s79, v188, 15
	s_nop 7
	s_waitcnt vmcnt(1)
	s_nop 0
	s_nop 0
	s_nop 0
	s_waitcnt vmcnt(0)
	s_nop 0
	v_add_u32_e32 v140, v171, v173
	s_nop 0
	v_add_u32_e32 v160, v171, v172
	s_nop 0
	s_nop 0
	s_nop 0
	s_nop 0
	s_nop 0
	s_nop 0
	s_nop 0
	s_nop 0
	s_nop 0
	s_nop 0
	s_nop 0
	s_waitcnt lgkmcnt(0)
	s_nop 0
	s_nop 0
	s_lshl_b32 s0, s2, 2
	s_add_u32 s30, s33, s0
	s_addc_u32 s31, s38, 0
	s_lshl_b32 s0, s2, 1
	s_add_u32 s0, s6, s0
	s_nop 0
	s_addc_u32 s1, s7, 0
	s_nop 0
	s_nop 0
	s_nop 0
	s_nop 0
	s_nop 0
	s_nop 0
	s_nop 0
	s_nop 0
	s_nop 0
	s_waitcnt lgkmcnt(3)
	s_nop 0
	s_nop 0
	v_mov_b32_e32 v152, v196
	s_nop 0
	s_nop 0
	s_nop 0
	s_nop 0
	s_nop 0
	s_nop 0
	s_nop 0
	s_waitcnt lgkmcnt(0)
	s_nop 0
	s_nop 0
	v_ashrrev_i32_e32 v153, 1, v152
	v_and_b32_e32 v153, 0xffffffc0, v153
	v_and_b32_e32 v155, 31, v152
	v_add_u32_e32 v173, s58, v153
	v_lshrrev_b32_e32 v153, 3, v152
	v_lshlrev_b32_e32 v152, 1, v152
	v_and_b32_e32 v152, 0x80, v152
	v_or_b32_e32 v170, s57, v152
	v_or_b32_e32 v152, v170, v155
	v_lshlrev_b32_e32 v175, 8, v170
	s_nop 0
	v_lshlrev_b32_e32 v170, 10, v173
	v_and_b32_e32 v174, 4, v153
	v_and_b32_e32 v172, 0xfffc0000, v170
	v_lshlrev_b32_e32 v170, 5, v173
	v_lshlrev_b32_e32 v160, 2, v152
	v_lshlrev_b32_e32 v197, 3, v155
	v_and_b32_e32 v170, 0x1800, v170
	v_lshlrev_b32_e32 v228, 6, v174
	v_lshl_add_u64 v[152:153], s[30:31], 0, v[160:161]
	v_or_b32_e32 v160, v175, v197
	s_nop 0
	v_or3_b32 v229, v228, v170, v172
	v_or_b32_e32 v231, 10, v174
	v_or_b32_e32 v156, v229, v160
	v_ashrrev_i32_e32 v157, 31, v156
	v_or_b32_e32 v230, 1, v174
	v_or_b32_e32 v154, v173, v174
	v_lshl_add_u64 v[226:227], v[156:157], 1, s[0:1]
	s_nop 0
	v_or_b32_e32 v188, 2, v174
	v_or_b32_e32 v191, 9, v174
	v_or_b32_e32 v158, v173, v188
	v_or_b32_e32 v189, 3, v174
	v_ashrrev_i32_e32 v159, 31, v158
	v_or_b32_e32 v162, v173, v189
	v_or_b32_e32 v190, 8, v174
	s_nop 0
	v_or_b32_e32 v178, 11, v174
	v_or_b32_e32 v170, v173, v178
	v_ashrrev_i32_e32 v171, 31, v170
	v_or_b32_e32 v156, v173, v230
	v_lshlrev_b64 v[158:159], 12, v[158:159]
	v_ashrrev_i32_e32 v163, 31, v162
	v_or_b32_e32 v164, v173, v190
	s_nop 0
	v_lshlrev_b64 v[170:171], 12, v[170:171]
	v_ashrrev_i32_e32 v155, 31, v154
	v_ashrrev_i32_e32 v157, 31, v156
	v_lshl_add_u64 v[158:159], v[152:153], 0, v[158:159]
	v_lshlrev_b64 v[162:163], 12, v[162:163]
	v_ashrrev_i32_e32 v165, 31, v164
	v_lshl_add_u64 v[170:171], v[152:153], 0, v[170:171]
	s_nop 0
	v_or_b32_e32 v179, 16, v174
	v_lshlrev_b64 v[154:155], 12, v[154:155]
	v_lshlrev_b64 v[156:157], 12, v[156:157]
	global_store_dword v[158:159], v114, off
	v_lshl_add_u64 v[162:163], v[152:153], 0, v[162:163]
	v_lshlrev_b64 v[164:165], 12, v[164:165]
	global_store_dword v[170:171], v119, off
	s_nop 0
	v_or_b32_e32 v166, v173, v191
	v_or_b32_e32 v168, v173, v231
	v_ashrrev_i32_e32 v167, 31, v166
	v_ashrrev_i32_e32 v169, 31, v168
	v_lshlrev_b64 v[166:167], 12, v[166:167]
	v_lshlrev_b64 v[168:169], 12, v[168:169]
	v_lshl_add_u64 v[166:167], v[152:153], 0, v[166:167]
	v_lshl_add_u64 v[168:169], v[152:153], 0, v[168:169]
	global_store_dword v[166:167], v117, off
; DI bfr f2bf(float a) { return (bfr)(pack2(a, 0.f) & 0xffffu); }
; DI int crow(int reg, int h) { return (reg & 3) + 8 * (reg >> 2) + 4 * h; }
; template <int lda, class Epi>
; DI void gemm_tile(const bfr* __restrict__ A, const bfr* __restrict__ Bt, int NB, int K, int m0, int n0, char* smem, Epi epi) {
;     ...
; #pragma unroll
;   for (int i = 0; i < 2; ++i)
; #pragma unroll
;     for (int j = 0; j < 4; ++j)
; #pragma unroll
;       for (int q = 0; q < 16; ++q) {
;         int row = m0 + wr * 64 + i * 32 + crow(q, hl);
;         int col = n0 + wc * 128 + j * 32 + r;
;         epi(row, col, acc[i][j][q]);
;       }
; DI void phase_gemm_in_even(const Params& p, char* smem) {
;     ...
;                   [=](int row, int col, float v) {
;                     o[(size_t)row * 1024 + col] = v;
;                     const int ml = row & 15;
;                     const int rowpart = (row >> 8) * 262144 + ((row & 255) >> 4) * 512 + ((ml >> 2) & 1) * 256 + (((ml >> 3) << 2) | (ml & 3));
;                     const int colpart = (col >> 8) * 65536 + ((col & 255) >> 5) * 8192 + (col & 31) * 8;
;                     vt[rowpart + colpart] = f2bf(v);
;                   });
	global_store_dword v[168:169], v118, off
	v_cvt_pk_bf16_f32 v119, v118, v119
	v_cvt_pk_bf16_f32 v118, v116, v117
	v_cvt_pk_bf16_f32 v117, v114, v115
	v_or_b32_e32 v114, v173, v179
	v_lshl_add_u64 v[154:155], v[152:153], 0, v[154:155]
	v_lshl_add_u64 v[156:157], v[152:153], 0, v[156:157]
	global_store_dword v[162:163], v115, off
	v_lshl_add_u64 v[164:165], v[152:153], 0, v[164:165]
	v_ashrrev_i32_e32 v115, 31, v114
	global_store_dword v[154:155], v112, off
	global_store_dword v[156:157], v113, off
	global_store_dword v[164:165], v116, off
	v_cvt_pk_bf16_f32 v116, v112, v113
	v_lshlrev_b64 v[112:113], 12, v[114:115]
	v_lshlrev_b32_e32 v114, 5, v114
	v_or_b32_e32 v172, v172, v228
	s_nop 0
	v_and_or_b32 v180, v114, s49, v172
	v_or_b32_e32 v114, v180, v160
	v_ashrrev_i32_e32 v115, 31, v114
	global_store_dwordx4 v[226:227], v[116:119], off
	v_lshl_add_u64 v[114:115], v[114:115], 1, s[0:1]
	v_or_b32_e32 v181, 17, v174
	v_cvt_pk_bf16_f32 v116, v120, s0
	global_store_short v[114:115], v116, off
	v_or_b32_e32 v116, v173, v181
	v_ashrrev_i32_e32 v117, 31, v116
	v_lshlrev_b64 v[114:115], 12, v[116:117]
	v_lshlrev_b32_e32 v116, 5, v116
	v_and_or_b32 v182, v116, s49, v172
	v_or_b32_e32 v116, v182, v160
	v_ashrrev_i32_e32 v117, 31, v116
	v_cvt_pk_bf16_f32 v118, v121, s0
	v_lshl_add_u64 v[116:117], v[116:117], 1, s[0:1]
	v_or_b32_e32 v183, 18, v174
	global_store_short v[116:117], v118, off offset:2
	v_or_b32_e32 v118, v173, v183
	v_ashrrev_i32_e32 v119, 31, v118
	v_lshlrev_b64 v[116:117], 12, v[118:119]
	v_lshlrev_b32_e32 v118, 5, v118
	s_nop 0
	v_and_or_b32 v184, v118, s49, v172
	v_or_b32_e32 v118, v184, v160
	v_lshl_add_u64 v[112:113], v[152:153], 0, v[112:113]
	v_ashrrev_i32_e32 v119, 31, v118
	global_store_dword v[112:113], v120, off
	v_cvt_pk_bf16_f32 v120, v122, s0
	v_lshl_add_u64 v[118:119], v[118:119], 1, s[0:1]
	v_or_b32_e32 v185, 19, v174
	v_lshl_add_u64 v[114:115], v[152:153], 0, v[114:115]
	global_store_short v[118:119], v120, off offset:4
	v_or_b32_e32 v120, v173, v185
	global_store_dword v[114:115], v121, off
	v_ashrrev_i32_e32 v121, 31, v120
	v_lshlrev_b64 v[118:119], 12, v[120:121]
	v_lshlrev_b32_e32 v120, 5, v120
	v_and_or_b32 v186, v120, s49, v172
	v_or_b32_e32 v120, v186, v160
	v_lshl_add_u64 v[116:117], v[152:153], 0, v[116:117]
	v_ashrrev_i32_e32 v121, 31, v120
	global_store_dword v[116:117], v122, off
	v_cvt_pk_bf16_f32 v122, v123, s0
	v_lshl_add_u64 v[120:121], v[120:121], 1, s[0:1]
	v_or_b32_e32 v187, 24, v174
	v_lshl_add_u64 v[118:119], v[152:153], 0, v[118:119]
	global_store_short v[120:121], v122, off offset:6
	v_or_b32_e32 v122, v173, v187
	s_nop 0
	global_store_dword v[118:119], v123, off
	v_ashrrev_i32_e32 v123, 31, v122
	v_lshlrev_b64 v[120:121], 12, v[122:123]
	v_lshlrev_b32_e32 v122, 5, v122
	v_lshl_add_u64 v[120:121], v[152:153], 0, v[120:121]
	global_store_dword v[120:121], v124, off
	v_cvt_pk_bf16_f32 v124, v124, s0
	s_nop 0
	s_nop 0
	s_nop 0
	v_and_or_b32 v192, v122, s49, v172
	v_or_b32_e32 v122, v192, v160
	v_ashrrev_i32_e32 v123, 31, v122
	v_or_b32_e32 v193, 25, v174
	v_lshl_add_u64 v[122:123], v[122:123], 1, s[0:1]
	v_or_b32_e32 v176, v173, v193
	global_store_short v[122:123], v124, off offset:8
	s_nop 0
	v_ashrrev_i32_e32 v177, 31, v176
	v_lshlrev_b32_e32 v124, 5, v176
	v_lshlrev_b64 v[122:123], 12, v[176:177]
	v_and_or_b32 v177, v124, s49, v172
	v_lshl_add_u64 v[122:123], v[152:153], 0, v[122:123]
	v_or_b32_e32 v124, v177, v160
	global_store_dword v[122:123], v125, off
	s_nop 0
	v_cvt_pk_bf16_f32 v176, v125, s0
	v_ashrrev_i32_e32 v125, 31, v124
	v_lshl_add_u64 v[124:125], v[124:125], 1, s[0:1]
	global_store_short v[124:125], v176, off offset:10
	s_nop 0
	s_nop 6
	global_store_dword v[154:155], v96, off offset:128
	s_nop 0
	v_or_b32_e32 v146, 26, v174
	v_or_b32_e32 v144, v173, v146
	v_ashrrev_i32_e32 v145, 31, v144
	v_lshlrev_b64 v[124:125], 12, v[144:145]
	v_lshl_add_u64 v[124:125], v[152:153], 0, v[124:125]
	v_or_b32_e32 v145, 27, v174
	global_store_dword v[124:125], v126, off
	s_nop 0
	v_lshlrev_b32_e32 v136, 5, v144
	v_and_or_b32 v144, v136, s49, v172
	v_or_b32_e32 v136, v144, v160
	v_ashrrev_i32_e32 v137, 31, v136
	v_cvt_pk_bf16_f32 v126, v126, s0
	v_lshl_add_u64 v[136:137], v[136:137], 1, s[0:1]
	v_or_b32_e32 v138, v173, v145
	s_nop 0
	global_store_short v[136:137], v126, off offset:12
	v_ashrrev_i32_e32 v139, 31, v138
	v_lshlrev_b32_e32 v126, 5, v138
	v_lshlrev_b64 v[136:137], 12, v[138:139]
	v_and_or_b32 v139, v126, s49, v172
	v_lshl_add_u64 v[136:137], v[152:153], 0, v[136:137]
	v_or_b32_e32 v126, v139, v160
	s_nop 0
	global_store_dword v[136:137], v127, off
	v_cvt_pk_bf16_f32 v138, v127, s0
	v_ashrrev_i32_e32 v127, 31, v126
	v_lshl_add_u64 v[126:127], v[126:127], 1, s[0:1]
	global_store_short v[126:127], v138, off offset:14
	v_or_b32_e32 v126, 0x2000, v175
	v_and_or_b32 v126, v126, s50, v197
	s_nop 0
	global_store_dword v[156:157], v97, off offset:128
	global_store_dword v[158:159], v98, off offset:128
	global_store_dword v[162:163], v99, off offset:128
	global_store_dword v[164:165], v100, off offset:128
	global_store_dword v[166:167], v101, off offset:128
	global_store_dword v[168:169], v102, off offset:128
	global_store_dword v[170:171], v103, off offset:128
	v_cvt_pk_bf16_f32 v103, v102, v103
	v_cvt_pk_bf16_f32 v102, v100, v101
	v_cvt_pk_bf16_f32 v100, v96, v97
	v_or_b32_e32 v96, v126, v180
	v_ashrrev_i32_e32 v97, 31, v96
	v_cvt_pk_bf16_f32 v101, v98, v99
	s_nop 0
	v_cvt_pk_bf16_f32 v98, v104, s0
	v_lshl_add_u64 v[96:97], v[96:97], 1, s[0:1]
	s_nop 0
	s_nop 0
	v_or_b32_e32 v128, v126, v229
	v_ashrrev_i32_e32 v129, 31, v128
	v_lshl_add_u64 v[128:129], v[128:129], 1, s[0:1]
; DI bfr f2bf(float a) { return (bfr)(pack2(a, 0.f) & 0xffffu); }
; DI int crow(int reg, int h) { return (reg & 3) + 8 * (reg >> 2) + 4 * h; }
; template <int lda, class Epi>
; DI void gemm_tile(const bfr* __restrict__ A, const bfr* __restrict__ Bt, int NB, int K, int m0, int n0, char* smem, Epi epi) {
;     ...
; #pragma unroll
;   for (int i = 0; i < 2; ++i)
; #pragma unroll
;     for (int j = 0; j < 4; ++j)
; #pragma unroll
;       for (int q = 0; q < 16; ++q) {
;         int row = m0 + wr * 64 + i * 32 + crow(q, hl);
;         int col = n0 + wc * 128 + j * 32 + r;
;         epi(row, col, acc[i][j][q]);
;       }
; DI void phase_gemm_in_even(const Params& p, char* smem) {
;     ...
;                   [=](int row, int col, float v) {
;                     o[(size_t)row * 1024 + col] = v;
;                     const int ml = row & 15;
;                     const int rowpart = (row >> 8) * 262144 + ((row & 255) >> 4) * 512 + ((ml >> 2) & 1) * 256 + (((ml >> 3) << 2) | (ml & 3));
;                     const int colpart = (col >> 8) * 65536 + ((col & 255) >> 5) * 8192 + (col & 31) * 8;
;                     vt[rowpart + colpart] = f2bf(v);
;                   });
	global_store_dwordx4 v[128:129], v[100:103], off
	global_store_dword v[112:113], v104, off offset:128
	global_store_short v[96:97], v98, off
	global_store_dword v[114:115], v105, off offset:128
	v_or_b32_e32 v96, v126, v182
	v_ashrrev_i32_e32 v97, 31, v96
	v_cvt_pk_bf16_f32 v98, v105, s0
	v_lshl_add_u64 v[96:97], v[96:97], 1, s[0:1]
	global_store_short v[96:97], v98, off offset:2
	global_store_dword v[116:117], v106, off offset:128
	v_or_b32_e32 v96, v126, v184
	v_ashrrev_i32_e32 v97, 31, v96
	v_cvt_pk_bf16_f32 v98, v106, s0
	v_lshl_add_u64 v[96:97], v[96:97], 1, s[0:1]
	global_store_short v[96:97], v98, off offset:4
	global_store_dword v[118:119], v107, off offset:128
	v_or_b32_e32 v96, v126, v186
	v_ashrrev_i32_e32 v97, 31, v96
	v_cvt_pk_bf16_f32 v98, v107, s0
	v_lshl_add_u64 v[96:97], v[96:97], 1, s[0:1]
	global_store_short v[96:97], v98, off offset:6
	global_store_dword v[120:121], v108, off offset:128
	v_or_b32_e32 v96, v126, v192
	v_ashrrev_i32_e32 v97, 31, v96
	v_cvt_pk_bf16_f32 v98, v108, s0
	v_lshl_add_u64 v[96:97], v[96:97], 1, s[0:1]
	global_store_short v[96:97], v98, off offset:8
	global_store_dword v[122:123], v109, off offset:128
	v_or_b32_e32 v96, v126, v177
	v_ashrrev_i32_e32 v97, 31, v96
	v_cvt_pk_bf16_f32 v98, v109, s0
	v_lshl_add_u64 v[96:97], v[96:97], 1, s[0:1]
	global_store_short v[96:97], v98, off offset:10
	global_store_dword v[124:125], v110, off offset:128
	v_or_b32_e32 v96, v126, v144
	v_ashrrev_i32_e32 v97, 31, v96
	v_cvt_pk_bf16_f32 v98, v110, s0
	v_lshl_add_u64 v[96:97], v[96:97], 1, s[0:1]
	global_store_short v[96:97], v98, off offset:12
	global_store_dword v[136:137], v111, off offset:128
	v_or_b32_e32 v96, v126, v139
	v_ashrrev_i32_e32 v97, 31, v96
	v_cvt_pk_bf16_f32 v98, v111, s0
	v_lshl_add_u64 v[96:97], v[96:97], 1, s[0:1]
	global_store_short v[96:97], v98, off offset:14
	v_or_b32_e32 v96, 0x4000, v175
	v_and_or_b32 v96, v96, s51, v197
	global_store_dword v[154:155], v80, off offset:256
	v_or_b32_e32 v98, v96, v229
	global_store_dword v[156:157], v81, off offset:256
	global_store_dword v[158:159], v82, off offset:256
	global_store_dword v[162:163], v83, off offset:256
	global_store_dword v[164:165], v84, off offset:256
	global_store_dword v[166:167], v85, off offset:256
	global_store_dword v[168:169], v86, off offset:256
	global_store_dword v[170:171], v87, off offset:256
	v_cvt_pk_bf16_f32 v87, v86, v87
	v_cvt_pk_bf16_f32 v86, v84, v85
	v_cvt_pk_bf16_f32 v84, v80, v81
	v_or_b32_e32 v80, v96, v180
	v_ashrrev_i32_e32 v99, 31, v98
	v_ashrrev_i32_e32 v81, 31, v80
	v_lshl_add_u64 v[98:99], v[98:99], 1, s[0:1]
	v_cvt_pk_bf16_f32 v85, v82, v83
	v_cvt_pk_bf16_f32 v82, v88, s0
	v_lshl_add_u64 v[80:81], v[80:81], 1, s[0:1]
	global_store_dwordx4 v[98:99], v[84:87], off
	global_store_dword v[112:113], v88, off offset:256
	global_store_short v[80:81], v82, off
	global_store_dword v[114:115], v89, off offset:256
	v_or_b32_e32 v80, v96, v182
	v_ashrrev_i32_e32 v81, 31, v80
	v_cvt_pk_bf16_f32 v82, v89, s0
	v_lshl_add_u64 v[80:81], v[80:81], 1, s[0:1]
	global_store_short v[80:81], v82, off offset:2
	global_store_dword v[116:117], v90, off offset:256
	v_or_b32_e32 v80, v96, v184
	v_ashrrev_i32_e32 v81, 31, v80
	v_cvt_pk_bf16_f32 v82, v90, s0
	v_lshl_add_u64 v[80:81], v[80:81], 1, s[0:1]
	global_store_short v[80:81], v82, off offset:4
	global_store_dword v[118:119], v91, off offset:256
	v_or_b32_e32 v80, v96, v186
	v_ashrrev_i32_e32 v81, 31, v80
	v_cvt_pk_bf16_f32 v82, v91, s0
	v_lshl_add_u64 v[80:81], v[80:81], 1, s[0:1]
	global_store_short v[80:81], v82, off offset:6
	global_store_dword v[120:121], v92, off offset:256
	v_or_b32_e32 v80, v96, v192
	v_ashrrev_i32_e32 v81, 31, v80
	v_cvt_pk_bf16_f32 v82, v92, s0
	v_lshl_add_u64 v[80:81], v[80:81], 1, s[0:1]
	global_store_short v[80:81], v82, off offset:8
	global_store_dword v[122:123], v93, off offset:256
	v_or_b32_e32 v80, v96, v177
	v_ashrrev_i32_e32 v81, 31, v80
	v_cvt_pk_bf16_f32 v82, v93, s0
	v_lshl_add_u64 v[80:81], v[80:81], 1, s[0:1]
	global_store_short v[80:81], v82, off offset:10
	global_store_dword v[124:125], v94, off offset:256
	v_or_b32_e32 v80, v96, v144
	v_ashrrev_i32_e32 v81, 31, v80
	v_cvt_pk_bf16_f32 v82, v94, s0
	v_lshl_add_u64 v[80:81], v[80:81], 1, s[0:1]
	global_store_short v[80:81], v82, off offset:12
	global_store_dword v[136:137], v95, off offset:256
	v_or_b32_e32 v80, v96, v139
	v_ashrrev_i32_e32 v81, 31, v80
	v_cvt_pk_bf16_f32 v82, v95, s0
	v_lshl_add_u64 v[80:81], v[80:81], 1, s[0:1]
	global_store_short v[80:81], v82, off offset:14
	v_or_b32_e32 v80, 0x6000, v175
	v_and_or_b32 v82, v80, s52, v197
	global_store_dword v[154:155], v64, off offset:384
	v_or_b32_e32 v80, v82, v229
	global_store_dword v[156:157], v65, off offset:384
	global_store_dword v[158:159], v66, off offset:384
	global_store_dword v[162:163], v67, off offset:384
	global_store_dword v[164:165], v68, off offset:384
	global_store_dword v[166:167], v69, off offset:384
	global_store_dword v[168:169], v70, off offset:384
	global_store_dword v[170:171], v71, off offset:384
	v_cvt_pk_bf16_f32 v71, v70, v71
	v_cvt_pk_bf16_f32 v70, v68, v69
	v_cvt_pk_bf16_f32 v68, v64, v65
	v_or_b32_e32 v64, v82, v180
	v_ashrrev_i32_e32 v81, 31, v80
	v_ashrrev_i32_e32 v65, 31, v64
	v_lshl_add_u64 v[80:81], v[80:81], 1, s[0:1]
	v_cvt_pk_bf16_f32 v69, v66, v67
	v_cvt_pk_bf16_f32 v66, v72, s0
	v_lshl_add_u64 v[64:65], v[64:65], 1, s[0:1]
	global_store_dwordx4 v[80:81], v[68:71], off
	global_store_dword v[112:113], v72, off offset:384
	global_store_short v[64:65], v66, off
	global_store_dword v[114:115], v73, off offset:384
	v_or_b32_e32 v64, v82, v182
	v_ashrrev_i32_e32 v65, 31, v64
	v_cvt_pk_bf16_f32 v66, v73, s0
; DI bfr f2bf(float a) { return (bfr)(pack2(a, 0.f) & 0xffffu); }
; DI int crow(int reg, int h) { return (reg & 3) + 8 * (reg >> 2) + 4 * h; }
; template <int lda, class Epi>
; DI void gemm_tile(const bfr* __restrict__ A, const bfr* __restrict__ Bt, int NB, int K, int m0, int n0, char* smem, Epi epi) {
;     ...
; #pragma unroll
;   for (int i = 0; i < 2; ++i)
; #pragma unroll
;     for (int j = 0; j < 4; ++j)
; #pragma unroll
;       for (int q = 0; q < 16; ++q) {
;         int row = m0 + wr * 64 + i * 32 + crow(q, hl);
;         int col = n0 + wc * 128 + j * 32 + r;
;         epi(row, col, acc[i][j][q]);
;       }
; DI void phase_gemm_in_even(const Params& p, char* smem) {
;     ...
;                   [=](int row, int col, float v) {
;                     o[(size_t)row * 1024 + col] = v;
;                     const int ml = row & 15;
;                     const int rowpart = (row >> 8) * 262144 + ((row & 255) >> 4) * 512 + ((ml >> 2) & 1) * 256 + (((ml >> 3) << 2) | (ml & 3));
;                     const int colpart = (col >> 8) * 65536 + ((col & 255) >> 5) * 8192 + (col & 31) * 8;
;                     vt[rowpart + colpart] = f2bf(v);
;                   });
	v_lshl_add_u64 v[64:65], v[64:65], 1, s[0:1]
	global_store_short v[64:65], v66, off offset:2
	global_store_dword v[116:117], v74, off offset:384
	v_or_b32_e32 v64, v82, v184
	v_ashrrev_i32_e32 v65, 31, v64
	v_cvt_pk_bf16_f32 v66, v74, s0
	v_lshl_add_u64 v[64:65], v[64:65], 1, s[0:1]
	global_store_short v[64:65], v66, off offset:4
	global_store_dword v[118:119], v75, off offset:384
	v_or_b32_e32 v64, v82, v186
	v_ashrrev_i32_e32 v65, 31, v64
	v_cvt_pk_bf16_f32 v66, v75, s0
	v_lshl_add_u64 v[64:65], v[64:65], 1, s[0:1]
	global_store_short v[64:65], v66, off offset:6
	global_store_dword v[120:121], v76, off offset:384
	v_or_b32_e32 v64, v82, v192
	v_ashrrev_i32_e32 v65, 31, v64
	v_cvt_pk_bf16_f32 v66, v76, s0
	v_lshl_add_u64 v[64:65], v[64:65], 1, s[0:1]
	global_store_short v[64:65], v66, off offset:8
	global_store_dword v[122:123], v77, off offset:384
	v_or_b32_e32 v64, v82, v177
	v_ashrrev_i32_e32 v65, 31, v64
	v_cvt_pk_bf16_f32 v66, v77, s0
	v_lshl_add_u64 v[64:65], v[64:65], 1, s[0:1]
	global_store_short v[64:65], v66, off offset:10
	global_store_dword v[124:125], v78, off offset:384
	v_or_b32_e32 v64, v82, v144
	v_ashrrev_i32_e32 v65, 31, v64
	v_cvt_pk_bf16_f32 v66, v78, s0
	v_lshl_add_u64 v[64:65], v[64:65], 1, s[0:1]
	global_store_short v[64:65], v66, off offset:12
	global_store_dword v[136:137], v79, off offset:384
	v_or_b32_e32 v64, v82, v139
	v_ashrrev_i32_e32 v65, 31, v64
	v_cvt_pk_bf16_f32 v66, v79, s0
	v_lshl_add_u64 v[64:65], v[64:65], 1, s[0:1]
	v_or_b32_e32 v83, 32, v173
	global_store_short v[64:65], v66, off offset:14
	v_lshlrev_b32_e32 v66, 5, v83
	v_and_or_b32 v86, v66, s53, v172
	v_or_b32_e32 v66, v86, v160
	v_or_b32_e32 v68, v83, v188
	v_or_b32_e32 v74, v83, v191
	v_or_b32_e32 v76, v83, v231
	v_or_b32_e32 v78, v83, v178
	v_ashrrev_i32_e32 v67, 31, v66
	v_ashrrev_i32_e32 v69, 31, v68
	v_or_b32_e32 v70, v83, v189
	v_ashrrev_i32_e32 v75, 31, v74
	v_ashrrev_i32_e32 v77, 31, v76
	v_ashrrev_i32_e32 v79, 31, v78
	v_or_b32_e32 v64, v83, v174
	v_lshl_add_u64 v[80:81], v[66:67], 1, s[0:1]
	v_or_b32_e32 v66, v83, v230
	v_lshlrev_b64 v[68:69], 12, v[68:69]
	v_ashrrev_i32_e32 v71, 31, v70
	v_or_b32_e32 v72, v83, v190
	v_lshlrev_b64 v[74:75], 12, v[74:75]
	v_lshlrev_b64 v[76:77], 12, v[76:77]
	v_lshlrev_b64 v[78:79], 12, v[78:79]
	v_ashrrev_i32_e32 v65, 31, v64
	v_ashrrev_i32_e32 v67, 31, v66
	v_lshl_add_u64 v[68:69], v[152:153], 0, v[68:69]
	v_lshlrev_b64 v[70:71], 12, v[70:71]
	v_ashrrev_i32_e32 v73, 31, v72
	v_lshl_add_u64 v[74:75], v[152:153], 0, v[74:75]
	v_lshl_add_u64 v[76:77], v[152:153], 0, v[76:77]
	v_lshl_add_u64 v[78:79], v[152:153], 0, v[78:79]
	v_lshlrev_b64 v[64:65], 12, v[64:65]
	v_lshlrev_b64 v[66:67], 12, v[66:67]
	global_store_dword v[68:69], v50, off
	v_lshl_add_u64 v[70:71], v[152:153], 0, v[70:71]
	v_lshlrev_b64 v[72:73], 12, v[72:73]
	global_store_dword v[74:75], v53, off
	global_store_dword v[76:77], v54, off
	global_store_dword v[78:79], v55, off
	v_cvt_pk_bf16_f32 v55, v54, v55
	v_cvt_pk_bf16_f32 v54, v52, v53
	v_cvt_pk_bf16_f32 v53, v50, v51
	v_or_b32_e32 v50, v83, v179
	v_lshl_add_u64 v[64:65], v[152:153], 0, v[64:65]
	v_lshl_add_u64 v[66:67], v[152:153], 0, v[66:67]
	global_store_dword v[70:71], v51, off
	v_lshl_add_u64 v[72:73], v[152:153], 0, v[72:73]
	v_ashrrev_i32_e32 v51, 31, v50
	global_store_dword v[64:65], v48, off
	global_store_dword v[66:67], v49, off
	global_store_dword v[72:73], v52, off
	v_cvt_pk_bf16_f32 v52, v48, v49
	v_lshlrev_b64 v[48:49], 12, v[50:51]
	v_lshlrev_b32_e32 v50, 5, v50
	v_and_or_b32 v87, v50, s54, v172
	v_or_b32_e32 v50, v87, v160
	v_ashrrev_i32_e32 v51, 31, v50
	global_store_dwordx4 v[80:81], v[52:55], off
	v_lshl_add_u64 v[50:51], v[50:51], 1, s[0:1]
	v_lshl_add_u64 v[48:49], v[152:153], 0, v[48:49]
	v_cvt_pk_bf16_f32 v52, v56, s0
	global_store_short v[50:51], v52, off
	v_or_b32_e32 v52, v83, v181
	v_ashrrev_i32_e32 v53, 31, v52
	v_lshlrev_b64 v[50:51], 12, v[52:53]
	v_lshlrev_b32_e32 v52, 5, v52
	v_and_or_b32 v88, v52, s54, v172
	v_or_b32_e32 v52, v88, v160
	v_ashrrev_i32_e32 v53, 31, v52
	v_cvt_pk_bf16_f32 v54, v57, s0
	v_lshl_add_u64 v[52:53], v[52:53], 1, s[0:1]
	global_store_short v[52:53], v54, off offset:2
	v_or_b32_e32 v54, v83, v183
	v_ashrrev_i32_e32 v55, 31, v54
	v_lshlrev_b64 v[52:53], 12, v[54:55]
	v_lshlrev_b32_e32 v54, 5, v54
	v_and_or_b32 v89, v54, s54, v172
	v_or_b32_e32 v54, v89, v160
	v_ashrrev_i32_e32 v55, 31, v54
	global_store_dword v[48:49], v56, off
	v_cvt_pk_bf16_f32 v56, v58, s0
	v_lshl_add_u64 v[54:55], v[54:55], 1, s[0:1]
	v_lshl_add_u64 v[50:51], v[152:153], 0, v[50:51]
	global_store_short v[54:55], v56, off offset:4
	v_or_b32_e32 v56, v83, v185
	global_store_dword v[50:51], v57, off
	v_ashrrev_i32_e32 v57, 31, v56
	v_lshlrev_b64 v[54:55], 12, v[56:57]
	v_lshlrev_b32_e32 v56, 5, v56
	v_and_or_b32 v90, v56, s54, v172
	v_or_b32_e32 v56, v90, v160
	v_lshl_add_u64 v[52:53], v[152:153], 0, v[52:53]
	v_ashrrev_i32_e32 v57, 31, v56
	global_store_dword v[52:53], v58, off
	v_cvt_pk_bf16_f32 v58, v59, s0
	v_lshl_add_u64 v[56:57], v[56:57], 1, s[0:1]
	v_lshl_add_u64 v[54:55], v[152:153], 0, v[54:55]
	global_store_short v[56:57], v58, off offset:6
	v_or_b32_e32 v58, v83, v187
	global_store_dword v[54:55], v59, off
	v_ashrrev_i32_e32 v59, 31, v58
	v_lshlrev_b64 v[56:57], 12, v[58:59]
	v_lshlrev_b32_e32 v58, 5, v58
	v_and_or_b32 v91, v58, s54, v172
	v_or_b32_e32 v58, v91, v160
	v_lshl_add_u64 v[56:57], v[152:153], 0, v[56:57]
	v_ashrrev_i32_e32 v59, 31, v58
	global_store_dword v[56:57], v60, off
	v_cvt_pk_bf16_f32 v60, v60, s0
	v_lshl_add_u64 v[58:59], v[58:59], 1, s[0:1]
	v_or_b32_e32 v80, v83, v193
	global_store_short v[58:59], v60, off offset:8
; DI bfr f2bf(float a) { return (bfr)(pack2(a, 0.f) & 0xffffu); }
; DI int crow(int reg, int h) { return (reg & 3) + 8 * (reg >> 2) + 4 * h; }
; template <int lda, class Epi>
; DI void gemm_tile(const bfr* __restrict__ A, const bfr* __restrict__ Bt, int NB, int K, int m0, int n0, char* smem, Epi epi) {
;     ...
; #pragma unroll
;   for (int i = 0; i < 2; ++i)
; #pragma unroll
;     for (int j = 0; j < 4; ++j)
; #pragma unroll
;       for (int q = 0; q < 16; ++q) {
;         int row = m0 + wr * 64 + i * 32 + crow(q, hl);
;         int col = n0 + wc * 128 + j * 32 + r;
;         epi(row, col, acc[i][j][q]);
;       }
; DI void phase_gemm_in_even(const Params& p, char* smem) {
;     ...
;                   [=](int row, int col, float v) {
;                     o[(size_t)row * 1024 + col] = v;
;                     const int ml = row & 15;
;                     const int rowpart = (row >> 8) * 262144 + ((row & 255) >> 4) * 512 + ((ml >> 2) & 1) * 256 + (((ml >> 3) << 2) | (ml & 3));
;                     const int colpart = (col >> 8) * 65536 + ((col & 255) >> 5) * 8192 + (col & 31) * 8;
;                     vt[rowpart + colpart] = f2bf(v);
;                   });
	v_ashrrev_i32_e32 v81, 31, v80
	v_lshlrev_b32_e32 v60, 5, v80
	v_lshlrev_b64 v[58:59], 12, v[80:81]
	v_and_or_b32 v92, v60, s54, v172
	v_lshl_add_u64 v[58:59], v[152:153], 0, v[58:59]
	v_or_b32_e32 v60, v92, v160
	global_store_dword v[58:59], v61, off
	v_cvt_pk_bf16_f32 v80, v61, s0
	v_ashrrev_i32_e32 v61, 31, v60
	v_lshl_add_u64 v[60:61], v[60:61], 1, s[0:1]
	global_store_short v[60:61], v80, off offset:10
	v_or_b32_e32 v80, v83, v146
	v_ashrrev_i32_e32 v81, 31, v80
	v_lshlrev_b64 v[60:61], 12, v[80:81]
	v_lshlrev_b32_e32 v80, 5, v80
	v_and_or_b32 v93, v80, s54, v172
	v_or_b32_e32 v80, v93, v160
	v_lshl_add_u64 v[60:61], v[152:153], 0, v[60:61]
	v_ashrrev_i32_e32 v81, 31, v80
	global_store_dword v[60:61], v62, off
	v_cvt_pk_bf16_f32 v62, v62, s0
	v_lshl_add_u64 v[80:81], v[80:81], 1, s[0:1]
	v_or_b32_e32 v84, v83, v145
	global_store_short v[80:81], v62, off offset:12
	v_ashrrev_i32_e32 v85, 31, v84
	v_lshlrev_b32_e32 v62, 5, v84
	v_lshlrev_b64 v[80:81], 12, v[84:85]
	v_and_or_b32 v84, v62, s54, v172
	v_lshl_add_u64 v[80:81], v[152:153], 0, v[80:81]
	v_or_b32_e32 v62, v84, v160
	global_store_dword v[80:81], v63, off
	v_cvt_pk_bf16_f32 v83, v63, s0
	v_ashrrev_i32_e32 v63, 31, v62
	v_lshl_add_u64 v[62:63], v[62:63], 1, s[0:1]
	global_store_short v[62:63], v83, off offset:14
	global_store_dword v[64:65], v32, off offset:128
	v_or_b32_e32 v62, v126, v86
	global_store_dword v[66:67], v33, off offset:128
	global_store_dword v[68:69], v34, off offset:128
	global_store_dword v[70:71], v35, off offset:128
	global_store_dword v[72:73], v36, off offset:128
	global_store_dword v[74:75], v37, off offset:128
	global_store_dword v[76:77], v38, off offset:128
	global_store_dword v[78:79], v39, off offset:128
	v_cvt_pk_bf16_f32 v39, v38, v39
	v_cvt_pk_bf16_f32 v38, v36, v37
	v_cvt_pk_bf16_f32 v36, v32, v33
	v_or_b32_e32 v32, v87, v126
	v_ashrrev_i32_e32 v63, 31, v62
	v_ashrrev_i32_e32 v33, 31, v32
	v_lshl_add_u64 v[62:63], v[62:63], 1, s[0:1]
	v_cvt_pk_bf16_f32 v37, v34, v35
	v_cvt_pk_bf16_f32 v34, v40, s0
	v_lshl_add_u64 v[32:33], v[32:33], 1, s[0:1]
	global_store_dwordx4 v[62:63], v[36:39], off
	global_store_dword v[48:49], v40, off offset:128
	global_store_short v[32:33], v34, off
	global_store_dword v[50:51], v41, off offset:128
	v_or_b32_e32 v32, v88, v126
	v_ashrrev_i32_e32 v33, 31, v32
	v_cvt_pk_bf16_f32 v34, v41, s0
	v_lshl_add_u64 v[32:33], v[32:33], 1, s[0:1]
	global_store_short v[32:33], v34, off offset:2
	global_store_dword v[52:53], v42, off offset:128
	v_or_b32_e32 v32, v89, v126
	v_ashrrev_i32_e32 v33, 31, v32
	v_cvt_pk_bf16_f32 v34, v42, s0
	v_lshl_add_u64 v[32:33], v[32:33], 1, s[0:1]
	global_store_short v[32:33], v34, off offset:4
	global_store_dword v[54:55], v43, off offset:128
	v_or_b32_e32 v32, v90, v126
	v_ashrrev_i32_e32 v33, 31, v32
	v_cvt_pk_bf16_f32 v34, v43, s0
	v_lshl_add_u64 v[32:33], v[32:33], 1, s[0:1]
	global_store_short v[32:33], v34, off offset:6
	global_store_dword v[56:57], v44, off offset:128
	v_or_b32_e32 v32, v91, v126
	v_ashrrev_i32_e32 v33, 31, v32
	v_cvt_pk_bf16_f32 v34, v44, s0
	v_lshl_add_u64 v[32:33], v[32:33], 1, s[0:1]
	global_store_short v[32:33], v34, off offset:8
	global_store_dword v[58:59], v45, off offset:128
	v_or_b32_e32 v32, v92, v126
	v_ashrrev_i32_e32 v33, 31, v32
	v_cvt_pk_bf16_f32 v34, v45, s0
	v_lshl_add_u64 v[32:33], v[32:33], 1, s[0:1]
	global_store_short v[32:33], v34, off offset:10
	global_store_dword v[60:61], v46, off offset:128
	v_or_b32_e32 v32, v93, v126
	v_ashrrev_i32_e32 v33, 31, v32
	v_cvt_pk_bf16_f32 v34, v46, s0
	v_lshl_add_u64 v[32:33], v[32:33], 1, s[0:1]
	global_store_short v[32:33], v34, off offset:12
	global_store_dword v[80:81], v47, off offset:128
	v_or_b32_e32 v32, v84, v126
	v_ashrrev_i32_e32 v33, 31, v32
	v_cvt_pk_bf16_f32 v34, v47, s0
	v_lshl_add_u64 v[32:33], v[32:33], 1, s[0:1]
	global_store_short v[32:33], v34, off offset:14
	global_store_dword v[64:65], v16, off offset:256
	v_or_b32_e32 v32, v96, v86
	global_store_dword v[66:67], v17, off offset:256
	global_store_dword v[68:69], v18, off offset:256
	global_store_dword v[70:71], v19, off offset:256
	global_store_dword v[72:73], v20, off offset:256
	global_store_dword v[74:75], v21, off offset:256
	global_store_dword v[76:77], v22, off offset:256
	global_store_dword v[78:79], v23, off offset:256
	v_cvt_pk_bf16_f32 v23, v22, v23
	v_cvt_pk_bf16_f32 v22, v20, v21
	v_cvt_pk_bf16_f32 v20, v16, v17
	v_or_b32_e32 v16, v87, v96
	v_ashrrev_i32_e32 v33, 31, v32
; DI bfr f2bf(float a) { return (bfr)(pack2(a, 0.f) & 0xffffu); }
; DI int crow(int reg, int h) { return (reg & 3) + 8 * (reg >> 2) + 4 * h; }
; template <int lda, class Epi>
; DI void gemm_tile(const bfr* __restrict__ A, const bfr* __restrict__ Bt, int NB, int K, int m0, int n0, char* smem, Epi epi) {
;     ...
; #pragma unroll
;   for (int i = 0; i < 2; ++i)
; #pragma unroll
;     for (int j = 0; j < 4; ++j)
; #pragma unroll
;       for (int q = 0; q < 16; ++q) {
;         int row = m0 + wr * 64 + i * 32 + crow(q, hl);
;         int col = n0 + wc * 128 + j * 32 + r;
;         epi(row, col, acc[i][j][q]);
;       }
; DI void phase_gemm_in_even(const Params& p, char* smem) {
;     ...
;                   [=](int row, int col, float v) {
;                     o[(size_t)row * 1024 + col] = v;
;                     const int ml = row & 15;
;                     const int rowpart = (row >> 8) * 262144 + ((row & 255) >> 4) * 512 + ((ml >> 2) & 1) * 256 + (((ml >> 3) << 2) | (ml & 3));
;                     const int colpart = (col >> 8) * 65536 + ((col & 255) >> 5) * 8192 + (col & 31) * 8;
;                     vt[rowpart + colpart] = f2bf(v);
;                   });
	v_ashrrev_i32_e32 v17, 31, v16
	v_lshl_add_u64 v[32:33], v[32:33], 1, s[0:1]
	v_cvt_pk_bf16_f32 v21, v18, v19
	v_cvt_pk_bf16_f32 v18, v24, s0
	v_lshl_add_u64 v[16:17], v[16:17], 1, s[0:1]
	global_store_dwordx4 v[32:33], v[20:23], off
	global_store_dword v[48:49], v24, off offset:256
	global_store_short v[16:17], v18, off
	global_store_dword v[50:51], v25, off offset:256
	v_or_b32_e32 v16, v88, v96
	v_ashrrev_i32_e32 v17, 31, v16
	v_cvt_pk_bf16_f32 v18, v25, s0
	v_lshl_add_u64 v[16:17], v[16:17], 1, s[0:1]
	global_store_short v[16:17], v18, off offset:2
	global_store_dword v[52:53], v26, off offset:256
	v_or_b32_e32 v16, v89, v96
	v_ashrrev_i32_e32 v17, 31, v16
	v_cvt_pk_bf16_f32 v18, v26, s0
	v_lshl_add_u64 v[16:17], v[16:17], 1, s[0:1]
	global_store_short v[16:17], v18, off offset:4
	global_store_dword v[54:55], v27, off offset:256
	v_or_b32_e32 v16, v90, v96
	v_ashrrev_i32_e32 v17, 31, v16
	v_cvt_pk_bf16_f32 v18, v27, s0
	v_lshl_add_u64 v[16:17], v[16:17], 1, s[0:1]
	global_store_short v[16:17], v18, off offset:6
	global_store_dword v[56:57], v28, off offset:256
	v_or_b32_e32 v16, v91, v96
	v_ashrrev_i32_e32 v17, 31, v16
	v_cvt_pk_bf16_f32 v18, v28, s0
	v_lshl_add_u64 v[16:17], v[16:17], 1, s[0:1]
	global_store_short v[16:17], v18, off offset:8
	global_store_dword v[58:59], v29, off offset:256
	v_or_b32_e32 v16, v92, v96
	v_ashrrev_i32_e32 v17, 31, v16
	v_cvt_pk_bf16_f32 v18, v29, s0
	v_lshl_add_u64 v[16:17], v[16:17], 1, s[0:1]
	global_store_short v[16:17], v18, off offset:10
	global_store_dword v[60:61], v30, off offset:256
	v_or_b32_e32 v16, v93, v96
	v_ashrrev_i32_e32 v17, 31, v16
	v_cvt_pk_bf16_f32 v18, v30, s0
	v_lshl_add_u64 v[16:17], v[16:17], 1, s[0:1]
	global_store_short v[16:17], v18, off offset:12
	global_store_dword v[80:81], v31, off offset:256
	v_or_b32_e32 v16, v84, v96
	v_ashrrev_i32_e32 v17, 31, v16
	v_cvt_pk_bf16_f32 v18, v31, s0
	v_lshl_add_u64 v[16:17], v[16:17], 1, s[0:1]
	global_store_short v[16:17], v18, off offset:14
	global_store_dword v[64:65], v0, off offset:384
	v_or_b32_e32 v16, v82, v86
	global_store_dword v[66:67], v1, off offset:384
	global_store_dword v[68:69], v2, off offset:384
	global_store_dword v[70:71], v3, off offset:384
	global_store_dword v[72:73], v4, off offset:384
	global_store_dword v[74:75], v5, off offset:384
	global_store_dword v[76:77], v6, off offset:384
	global_store_dword v[78:79], v7, off offset:384
	v_cvt_pk_bf16_f32 v7, v6, v7
	v_cvt_pk_bf16_f32 v6, v4, v5
	v_cvt_pk_bf16_f32 v4, v0, v1
	v_or_b32_e32 v0, v87, v82
	v_ashrrev_i32_e32 v17, 31, v16
	v_ashrrev_i32_e32 v1, 31, v0
	v_lshl_add_u64 v[16:17], v[16:17], 1, s[0:1]
	v_cvt_pk_bf16_f32 v5, v2, v3
	v_cvt_pk_bf16_f32 v2, v8, s0
	v_lshl_add_u64 v[0:1], v[0:1], 1, s[0:1]
	global_store_dwordx4 v[16:17], v[4:7], off
	global_store_dword v[48:49], v8, off offset:384
	global_store_short v[0:1], v2, off
	global_store_dword v[50:51], v9, off offset:384
	v_or_b32_e32 v0, v88, v82
	v_ashrrev_i32_e32 v1, 31, v0
	v_cvt_pk_bf16_f32 v2, v9, s0
	v_lshl_add_u64 v[0:1], v[0:1], 1, s[0:1]
	global_store_short v[0:1], v2, off offset:2
	global_store_dword v[52:53], v10, off offset:384
	v_or_b32_e32 v0, v89, v82
	v_ashrrev_i32_e32 v1, 31, v0
	v_cvt_pk_bf16_f32 v2, v10, s0
	v_lshl_add_u64 v[0:1], v[0:1], 1, s[0:1]
	global_store_short v[0:1], v2, off offset:4
	global_store_dword v[54:55], v11, off offset:384
	v_or_b32_e32 v0, v90, v82
	v_ashrrev_i32_e32 v1, 31, v0
	v_cvt_pk_bf16_f32 v2, v11, s0
	v_lshl_add_u64 v[0:1], v[0:1], 1, s[0:1]
	global_store_short v[0:1], v2, off offset:6
	global_store_dword v[56:57], v12, off offset:384
	v_or_b32_e32 v0, v91, v82
	v_ashrrev_i32_e32 v1, 31, v0
	v_cvt_pk_bf16_f32 v2, v12, s0
	v_lshl_add_u64 v[0:1], v[0:1], 1, s[0:1]
	global_store_short v[0:1], v2, off offset:8
	global_store_dword v[58:59], v13, off offset:384
	v_or_b32_e32 v0, v92, v82
	v_ashrrev_i32_e32 v1, 31, v0
	v_cvt_pk_bf16_f32 v2, v13, s0
	v_lshl_add_u64 v[0:1], v[0:1], 1, s[0:1]
	global_store_short v[0:1], v2, off offset:10
	global_store_dword v[60:61], v14, off offset:384
	v_or_b32_e32 v0, v93, v82
	v_ashrrev_i32_e32 v1, 31, v0
	v_cvt_pk_bf16_f32 v2, v14, s0
	v_lshl_add_u64 v[0:1], v[0:1], 1, s[0:1]
	global_store_short v[0:1], v2, off offset:12
	global_store_dword v[80:81], v15, off offset:384
	v_or_b32_e32 v0, v84, v82
	v_ashrrev_i32_e32 v1, 31, v0
	v_cvt_pk_bf16_f32 v2, v15, s0
	v_lshl_add_u64 v[0:1], v[0:1], 1, s[0:1]
	global_store_short v[0:1], v2, off offset:14
	s_mov_b64 s[0:1], 0

; #define MFMA32(a, b, c) __builtin_amdgcn_mfma_f32_32x32x16_bf16((a), (b), (c), 0, 0, 0)
; #define GA_LOAD(pr_) do { _Pragma("unroll") for (int i = 0; i < 4; ++i) ra[i] = *(const u32x4*)(Ab + (i * 32) * lda + (pr_) * 64); } while (0)
; #define GB_LOAD(kt_) do { const bfr* bk_ = Bb + (kt_) * NB * 32; \
;     _Pragma("unroll") for (int i = 0; i < 4; ++i) rb[i] = *(const u32x4*)(bk_ + (i * 64) * 32); } while (0)
; #define G_STORE(kt_) do { bfr* as_ = S0 + ((kt_) & 1) * GSTAGE; bfr* bs_ = as_ + 128 * 40; \
;     if (apar == ((kt_) & 1)) { _Pragma("unroll") for (int i = 0; i < 4; ++i) *(u32x4*)(as_ + asoff + i * 32 * 40) = ra[i]; } \
;     _Pragma("unroll") for (int i = 0; i < 4; ++i) *(u32x4*)(bs_ + bsoff + i * 64 * 40) = rb[i]; } while (0)
; template <int lda>
; DI void gemm_mainloop(const bfr* __restrict__ A, const bfr* __restrict__ Bt, int NB, int K, int m0, int n0, char* smem, f32x16 (&acc)[2][4]) {
;     ...
;   for (int kt = 0; kt < nk; ++kt) {
;     if (kt + 1 < nk) G_STORE(kt + 1);
;     if (kt + 2 < nk) {
;       GB_LOAD(kt + 2);
;       if ((kt & 1) == 0) GA_LOAD((kt >> 1) + 1);
;     }
;     const bfr* As = S0 + (kt & 1) * GSTAGE;
;     const bfr* Bs = As + 128 * 40;
; #pragma unroll
;     for (int ks = 0; ks < 2; ++ks) {
;       bf16x8 af[2], bfg[4];
; #pragma unroll
;       for (int i = 0; i < 2; ++i) af[i] = *(const bf16x8*)(As + (wr * 64 + i * 32 + r) * 40 + ks * 16 + hl * 8);
; #pragma unroll
;       for (int j = 0; j < 4; ++j) bfg[j] = *(const bf16x8*)(Bs + (wc * 128 + j * 32 + r) * 40 + ks * 16 + hl * 8);
; #pragma unroll
;       for (int i = 0; i < 2; ++i)
; #pragma unroll
;         for (int j = 0; j < 4; ++j) acc[i][j] = MFMA32(af[i], bfg[j], acc[i][j]);
;     }
;     __syncthreads();
;   }
.Lp1k_loop:
	s_waitcnt vmcnt(6)
	s_barrier
	s_mul_i32 s74, s71, 0x6000
	s_add_u32 s75, s74, 0x2000
	s_cmp_eq_u32 s71, 2
	s_cselect_b32 s75, 0x10000, s75
	v_add_u32_e32 v184, s74, v180
	v_add_u32_e32 v186, s75, v182
	v_add_u32_e32 v185, s74, v181
	v_add_u32_e32 v187, s75, v183
	ds_read_b128 v[128:131], v184
	ds_read_b128 v[144:147], v186
	ds_read_b128 v[148:151], v186 offset:2048
	ds_read_b128 v[152:155], v186 offset:4096
	ds_read_b128 v[156:159], v186 offset:6144
	ds_read_b128 v[132:135], v184 offset:2048
	ds_read_b128 v[136:139], v185
	ds_read_b128 v[164:167], v187
	ds_read_b128 v[168:171], v187 offset:2048
	ds_read_b128 v[172:175], v187 offset:4096
	ds_read_b128 v[176:179], v187 offset:6144
	ds_read_b128 v[140:143], v185 offset:2048
	s_add_u32 s71, s71, 1
	s_cmp_eq_u32 s71, 3
	s_cselect_b32 s71, 0, s71
	s_waitcnt lgkmcnt(10)
	v_mfma_f32_32x32x16_bf16 v[112:127], v[128:131], v[144:147], v[112:127]
	s_mul_i32 s74, s70, 0x6000
	s_add_u32 s75, s74, s68
	s_mov_b32 m0, s75
	s_add_u32 s76, s74, 0x2000
	s_cmp_eq_u32 s70, 2
	s_cselect_b32 s76, 0x10000, s76
	global_load_lds_dwordx4 v160, s[64:65]
	s_waitcnt lgkmcnt(9)
	v_mfma_f32_32x32x16_bf16 v[96:111], v[128:131], v[148:151], v[96:111]
	s_add_u32 m0, s75, 0x400
	s_add_u32 s76, s76, s69
	global_load_lds_dwordx4 v162, s[64:65]
	s_waitcnt lgkmcnt(8)
	v_mfma_f32_32x32x16_bf16 v[80:95], v[128:131], v[152:155], v[80:95]
	s_mov_b32 m0, s76
	s_add_u32 s64, s64, 64
	s_addc_u32 s65, s65, 0
	global_load_lds_dwordx4 v163, s[66:67]
	s_waitcnt lgkmcnt(7)
	v_mfma_f32_32x32x16_bf16 v[64:79], v[128:131], v[156:159], v[64:79]
	global_load_lds_dwordx4 v163, s[66:67] offset:1024
	s_waitcnt lgkmcnt(6)
	v_mfma_f32_32x32x16_bf16 v[48:63], v[132:135], v[144:147], v[48:63]
	global_load_lds_dwordx4 v163, s[66:67] offset:2048
	v_mfma_f32_32x32x16_bf16 v[32:47], v[132:135], v[148:151], v[32:47]
	global_load_lds_dwordx4 v163, s[66:67] offset:3072
	s_add_u32 s66, s66, 0x10000
	s_addc_u32 s67, s67, 0
	v_mfma_f32_32x32x16_bf16 v[16:31], v[132:135], v[152:155], v[16:31]
	s_add_u32 s70, s70, 1
	s_cmp_eq_u32 s70, 3
	s_cselect_b32 s70, 0, s70
	v_mfma_f32_32x32x16_bf16 v[0:15], v[132:135], v[156:159], v[0:15]
	s_waitcnt lgkmcnt(4)
	v_mfma_f32_32x32x16_bf16 v[112:127], v[136:139], v[164:167], v[112:127]
	s_waitcnt lgkmcnt(3)
	v_mfma_f32_32x32x16_bf16 v[96:111], v[136:139], v[168:171], v[96:111]
	s_waitcnt lgkmcnt(2)
	v_mfma_f32_32x32x16_bf16 v[80:95], v[136:139], v[172:175], v[80:95]
	s_waitcnt lgkmcnt(1)
	v_mfma_f32_32x32x16_bf16 v[64:79], v[136:139], v[176:179], v[64:79]
	s_waitcnt lgkmcnt(0)
	v_mfma_f32_32x32x16_bf16 v[48:63], v[140:143], v[164:167], v[48:63]
	v_mfma_f32_32x32x16_bf16 v[32:47], v[140:143], v[168:171], v[32:47]
	v_mfma_f32_32x32x16_bf16 v[16:31], v[140:143], v[172:175], v[16:31]
	v_mfma_f32_32x32x16_bf16 v[0:15], v[140:143], v[176:179], v[0:15]
	s_add_u32 s72, s72, 1
	s_cmp_lt_u32 s72, 30
	s_cbranch_scc1 .Lp1k_loop
	s_waitcnt vmcnt(6)
	s_barrier
; #define MFMA32(a, b, c) __builtin_amdgcn_mfma_f32_32x32x16_bf16((a), (b), (c), 0, 0, 0)
; template <int lda>
; DI void gemm_mainloop(const bfr* __restrict__ A, const bfr* __restrict__ Bt, int NB, int K, int m0, int n0, char* smem, f32x16 (&acc)[2][4]) {
;     ...
;     for (int ks = 0; ks < 2; ++ks) {
;       bf16x8 af[2], bfg[4];
; #pragma unroll
;       for (int i = 0; i < 2; ++i) af[i] = *(const bf16x8*)(As + (wr * 64 + i * 32 + r) * 40 + ks * 16 + hl * 8);
; #pragma unroll
;       for (int j = 0; j < 4; ++j) bfg[j] = *(const bf16x8*)(Bs + (wc * 128 + j * 32 + r) * 40 + ks * 16 + hl * 8);
; #pragma unroll
;       for (int i = 0; i < 2; ++i)
; #pragma unroll
;         for (int j = 0; j < 4; ++j) acc[i][j] = MFMA32(af[i], bfg[j], acc[i][j]);
;     }
	s_mul_i32 s74, s71, 0x6000
	s_add_u32 s75, s74, 0x2000
	s_cmp_eq_u32 s71, 2
	s_cselect_b32 s75, 0x10000, s75
	v_add_u32_e32 v184, s74, v180
	v_add_u32_e32 v186, s75, v182
	v_add_u32_e32 v185, s74, v181
	v_add_u32_e32 v187, s75, v183
	ds_read_b128 v[128:131], v184
	ds_read_b128 v[144:147], v186
	ds_read_b128 v[148:151], v186 offset:2048
	ds_read_b128 v[152:155], v186 offset:4096
	ds_read_b128 v[156:159], v186 offset:6144
	ds_read_b128 v[132:135], v184 offset:2048
	ds_read_b128 v[136:139], v185
	ds_read_b128 v[164:167], v187
	ds_read_b128 v[168:171], v187 offset:2048
	ds_read_b128 v[172:175], v187 offset:4096
	ds_read_b128 v[176:179], v187 offset:6144
	ds_read_b128 v[140:143], v185 offset:2048
	s_add_u32 s71, s71, 1
	s_cmp_eq_u32 s71, 3
	s_cselect_b32 s71, 0, s71
	s_waitcnt lgkmcnt(10)
	v_mfma_f32_32x32x16_bf16 v[112:127], v[128:131], v[144:147], v[112:127]
	s_waitcnt lgkmcnt(9)
	v_mfma_f32_32x32x16_bf16 v[96:111], v[128:131], v[148:151], v[96:111]
	s_waitcnt lgkmcnt(8)
	v_mfma_f32_32x32x16_bf16 v[80:95], v[128:131], v[152:155], v[80:95]
	s_waitcnt lgkmcnt(7)
	v_mfma_f32_32x32x16_bf16 v[64:79], v[128:131], v[156:159], v[64:79]
	s_waitcnt lgkmcnt(6)
	v_mfma_f32_32x32x16_bf16 v[48:63], v[132:135], v[144:147], v[48:63]
	v_mfma_f32_32x32x16_bf16 v[32:47], v[132:135], v[148:151], v[32:47]
	v_mfma_f32_32x32x16_bf16 v[16:31], v[132:135], v[152:155], v[16:31]
	v_mfma_f32_32x32x16_bf16 v[0:15], v[132:135], v[156:159], v[0:15]
	s_waitcnt lgkmcnt(4)
	v_mfma_f32_32x32x16_bf16 v[112:127], v[136:139], v[164:167], v[112:127]
	s_waitcnt lgkmcnt(3)
	v_mfma_f32_32x32x16_bf16 v[96:111], v[136:139], v[168:171], v[96:111]
	s_waitcnt lgkmcnt(2)
	v_mfma_f32_32x32x16_bf16 v[80:95], v[136:139], v[172:175], v[80:95]
	s_waitcnt lgkmcnt(1)
	v_mfma_f32_32x32x16_bf16 v[64:79], v[136:139], v[176:179], v[64:79]
	s_waitcnt lgkmcnt(0)
	v_mfma_f32_32x32x16_bf16 v[48:63], v[140:143], v[164:167], v[48:63]
	v_mfma_f32_32x32x16_bf16 v[32:47], v[140:143], v[168:171], v[32:47]
	v_mfma_f32_32x32x16_bf16 v[16:31], v[140:143], v[172:175], v[16:31]
	v_mfma_f32_32x32x16_bf16 v[0:15], v[140:143], v[176:179], v[0:15]
	s_waitcnt vmcnt(0)
	s_barrier
	s_mul_i32 s74, s71, 0x6000
	s_add_u32 s75, s74, 0x2000
	s_cmp_eq_u32 s71, 2
	s_cselect_b32 s75, 0x10000, s75
	v_add_u32_e32 v184, s74, v180
	v_add_u32_e32 v186, s75, v182
	v_add_u32_e32 v185, s74, v181
	v_add_u32_e32 v187, s75, v183
	ds_read_b128 v[128:131], v184
	ds_read_b128 v[144:147], v186
	ds_read_b128 v[148:151], v186 offset:2048
	ds_read_b128 v[152:155], v186 offset:4096
	ds_read_b128 v[156:159], v186 offset:6144
	ds_read_b128 v[132:135], v184 offset:2048
	ds_read_b128 v[136:139], v185
	ds_read_b128 v[164:167], v187
	ds_read_b128 v[168:171], v187 offset:2048
	ds_read_b128 v[172:175], v187 offset:4096
	ds_read_b128 v[176:179], v187 offset:6144
	ds_read_b128 v[140:143], v185 offset:2048
	s_add_u32 s71, s71, 1
	s_cmp_eq_u32 s71, 3
	s_cselect_b32 s71, 0, s71
	s_waitcnt lgkmcnt(10)
	v_mfma_f32_32x32x16_bf16 v[112:127], v[128:131], v[144:147], v[112:127]
	s_waitcnt lgkmcnt(9)
	v_mfma_f32_32x32x16_bf16 v[96:111], v[128:131], v[148:151], v[96:111]
	s_waitcnt lgkmcnt(8)
	v_mfma_f32_32x32x16_bf16 v[80:95], v[128:131], v[152:155], v[80:95]
	s_waitcnt lgkmcnt(7)
	v_mfma_f32_32x32x16_bf16 v[64:79], v[128:131], v[156:159], v[64:79]
	s_waitcnt lgkmcnt(6)
	v_mfma_f32_32x32x16_bf16 v[48:63], v[132:135], v[144:147], v[48:63]
	v_mfma_f32_32x32x16_bf16 v[32:47], v[132:135], v[148:151], v[32:47]
	v_mfma_f32_32x32x16_bf16 v[16:31], v[132:135], v[152:155], v[16:31]
	v_mfma_f32_32x32x16_bf16 v[0:15], v[132:135], v[156:159], v[0:15]
	s_waitcnt lgkmcnt(4)
	v_mfma_f32_32x32x16_bf16 v[112:127], v[136:139], v[164:167], v[112:127]
	s_waitcnt lgkmcnt(3)
	v_mfma_f32_32x32x16_bf16 v[96:111], v[136:139], v[168:171], v[96:111]
	s_waitcnt lgkmcnt(2)
	v_mfma_f32_32x32x16_bf16 v[80:95], v[136:139], v[172:175], v[80:95]
	s_waitcnt lgkmcnt(1)
	v_mfma_f32_32x32x16_bf16 v[64:79], v[136:139], v[176:179], v[64:79]
	s_waitcnt lgkmcnt(0)
	v_mfma_f32_32x32x16_bf16 v[48:63], v[140:143], v[164:167], v[48:63]
	v_mfma_f32_32x32x16_bf16 v[32:47], v[140:143], v[168:171], v[32:47]
	v_mfma_f32_32x32x16_bf16 v[16:31], v[140:143], v[172:175], v[16:31]
	v_mfma_f32_32x32x16_bf16 v[0:15], v[140:143], v[176:179], v[0:15]
	s_nop 7
	v_readlane_b32 s64, v188, 0
	v_readlane_b32 s65, v188, 1
	v_readlane_b32 s66, v188, 2
	v_readlane_b32 s67, v188, 3
	v_readlane_b32 s68, v188, 4
	v_readlane_b32 s69, v188, 5
	v_readlane_b32 s70, v188, 6
	v_readlane_b32 s71, v188, 7
	v_readlane_b32 s72, v188, 8
	v_readlane_b32 s73, v188, 9
	v_readlane_b32 s74, v188, 10
	v_readlane_b32 s75, v188, 11
	v_readlane_b32 s76, v188, 12
	v_readlane_b32 s77, v188, 13
	v_readlane_b32 s78, v188, 14
	v_readlane_b32 s79, v188, 15
	s_nop 7
	s_branch .Lp1k_tail

; #define MFMA32(a, b, c) __builtin_amdgcn_mfma_f32_32x32x16_bf16((a), (b), (c), 0, 0, 0)
; #define GA_LOAD(pr_) do { _Pragma("unroll") for (int i = 0; i < 4; ++i) ra[i] = *(const u32x4*)(Ab + (i * 32) * lda + (pr_) * 64); } while (0)
; #define GB_LOAD(kt_) do { const bfr* bk_ = Bb + (kt_) * NB * 32; \
;     _Pragma("unroll") for (int i = 0; i < 4; ++i) rb[i] = *(const u32x4*)(bk_ + (i * 64) * 32); } while (0)
; #define G_STORE(kt_) do { bfr* as_ = S0 + ((kt_) & 1) * GSTAGE; bfr* bs_ = as_ + 128 * 40; \
;     if (apar == ((kt_) & 1)) { _Pragma("unroll") for (int i = 0; i < 4; ++i) *(u32x4*)(as_ + asoff + i * 32 * 40) = ra[i]; } \
;     _Pragma("unroll") for (int i = 0; i < 4; ++i) *(u32x4*)(bs_ + bsoff + i * 64 * 40) = rb[i]; } while (0)
; template <int lda>
; DI void gemm_mainloop(const bfr* __restrict__ A, const bfr* __restrict__ Bt, int NB, int K, int m0, int n0, char* smem, f32x16 (&acc)[2][4]) {
;     ...
;   for (int kt = 0; kt < nk; ++kt) {
;     if (kt + 1 < nk) G_STORE(kt + 1);
;     if (kt + 2 < nk) {
;       GB_LOAD(kt + 2);
;       if ((kt & 1) == 0) GA_LOAD((kt >> 1) + 1);
;     }
;     const bfr* As = S0 + (kt & 1) * GSTAGE;
;     const bfr* Bs = As + 128 * 40;
; #pragma unroll
;     for (int ks = 0; ks < 2; ++ks) {
;       bf16x8 af[2], bfg[4];
; #pragma unroll
;       for (int i = 0; i < 2; ++i) af[i] = *(const bf16x8*)(As + (wr * 64 + i * 32 + r) * 40 + ks * 16 + hl * 8);
; #pragma unroll
;       for (int j = 0; j < 4; ++j) bfg[j] = *(const bf16x8*)(Bs + (wc * 128 + j * 32 + r) * 40 + ks * 16 + hl * 8);
; #pragma unroll
;       for (int i = 0; i < 2; ++i)
; #pragma unroll
;         for (int j = 0; j < 4; ++j) acc[i][j] = MFMA32(af[i], bfg[j], acc[i][j]);
;     }
;     __syncthreads();
;   }
.Lp1e_loop:
	s_waitcnt vmcnt(6)
	s_barrier
	s_mul_i32 s74, s71, 0x6000
	s_add_u32 s75, s74, 0x2000
	s_cmp_eq_u32 s71, 2
	s_cselect_b32 s75, 0x10000, s75
	v_add_u32_e32 v184, s74, v180
	v_add_u32_e32 v186, s75, v182
	v_add_u32_e32 v185, s74, v181
	v_add_u32_e32 v187, s75, v183
	ds_read_b128 v[128:131], v184
	ds_read_b128 v[144:147], v186
	ds_read_b128 v[148:151], v186 offset:2048
	ds_read_b128 v[152:155], v186 offset:4096
	ds_read_b128 v[156:159], v186 offset:6144
	ds_read_b128 v[132:135], v184 offset:2048
	ds_read_b128 v[136:139], v185
	ds_read_b128 v[164:167], v187
	ds_read_b128 v[168:171], v187 offset:2048
	ds_read_b128 v[172:175], v187 offset:4096
	ds_read_b128 v[176:179], v187 offset:6144
	ds_read_b128 v[140:143], v185 offset:2048
	s_add_u32 s71, s71, 1
	s_cmp_eq_u32 s71, 3
	s_cselect_b32 s71, 0, s71
	s_waitcnt lgkmcnt(10)
	v_mfma_f32_32x32x16_bf16 v[112:127], v[128:131], v[144:147], v[112:127]
	s_mul_i32 s74, s70, 0x6000
	s_add_u32 s75, s74, s68
	s_mov_b32 m0, s75
	s_add_u32 s76, s74, 0x2000
	s_cmp_eq_u32 s70, 2
	s_cselect_b32 s76, 0x10000, s76
	global_load_lds_dwordx4 v160, s[64:65]
	s_waitcnt lgkmcnt(9)
	v_mfma_f32_32x32x16_bf16 v[96:111], v[128:131], v[148:151], v[96:111]
	s_add_u32 m0, s75, 0x400
	s_add_u32 s76, s76, s69
	global_load_lds_dwordx4 v162, s[64:65]
	s_waitcnt lgkmcnt(8)
	v_mfma_f32_32x32x16_bf16 v[80:95], v[128:131], v[152:155], v[80:95]
	s_mov_b32 m0, s76
	s_add_u32 s64, s64, 64
	s_addc_u32 s65, s65, 0
	global_load_lds_dwordx4 v163, s[66:67]
	s_waitcnt lgkmcnt(7)
	v_mfma_f32_32x32x16_bf16 v[64:79], v[128:131], v[156:159], v[64:79]
	global_load_lds_dwordx4 v163, s[66:67] offset:1024
	s_waitcnt lgkmcnt(6)
	v_mfma_f32_32x32x16_bf16 v[48:63], v[132:135], v[144:147], v[48:63]
	global_load_lds_dwordx4 v163, s[66:67] offset:2048
	v_mfma_f32_32x32x16_bf16 v[32:47], v[132:135], v[148:151], v[32:47]
	global_load_lds_dwordx4 v163, s[66:67] offset:3072
	s_add_u32 s66, s66, 0x3a000
	s_addc_u32 s67, s67, 0
	v_mfma_f32_32x32x16_bf16 v[16:31], v[132:135], v[152:155], v[16:31]
	s_add_u32 s70, s70, 1
	s_cmp_eq_u32 s70, 3
	s_cselect_b32 s70, 0, s70
	v_mfma_f32_32x32x16_bf16 v[0:15], v[132:135], v[156:159], v[0:15]
	s_waitcnt lgkmcnt(4)
	v_mfma_f32_32x32x16_bf16 v[112:127], v[136:139], v[164:167], v[112:127]
	s_waitcnt lgkmcnt(3)
	v_mfma_f32_32x32x16_bf16 v[96:111], v[136:139], v[168:171], v[96:111]
	s_waitcnt lgkmcnt(2)
	v_mfma_f32_32x32x16_bf16 v[80:95], v[136:139], v[172:175], v[80:95]
	s_waitcnt lgkmcnt(1)
	v_mfma_f32_32x32x16_bf16 v[64:79], v[136:139], v[176:179], v[64:79]
	s_waitcnt lgkmcnt(0)
	v_mfma_f32_32x32x16_bf16 v[48:63], v[140:143], v[164:167], v[48:63]
	v_mfma_f32_32x32x16_bf16 v[32:47], v[140:143], v[168:171], v[32:47]
	v_mfma_f32_32x32x16_bf16 v[16:31], v[140:143], v[172:175], v[16:31]
	v_mfma_f32_32x32x16_bf16 v[0:15], v[140:143], v[176:179], v[0:15]
	s_add_u32 s72, s72, 1
	s_cmp_lt_u32 s72, 30
	s_cbranch_scc1 .Lp1e_loop
	s_waitcnt vmcnt(6)
	s_barrier
; #define MFMA32(a, b, c) __builtin_amdgcn_mfma_f32_32x32x16_bf16((a), (b), (c), 0, 0, 0)
; template <int lda>
; DI void gemm_mainloop(const bfr* __restrict__ A, const bfr* __restrict__ Bt, int NB, int K, int m0, int n0, char* smem, f32x16 (&acc)[2][4]) {
;     ...
;     for (int ks = 0; ks < 2; ++ks) {
;       bf16x8 af[2], bfg[4];
; #pragma unroll
;       for (int i = 0; i < 2; ++i) af[i] = *(const bf16x8*)(As + (wr * 64 + i * 32 + r) * 40 + ks * 16 + hl * 8);
; #pragma unroll
;       for (int j = 0; j < 4; ++j) bfg[j] = *(const bf16x8*)(Bs + (wc * 128 + j * 32 + r) * 40 + ks * 16 + hl * 8);
; #pragma unroll
;       for (int i = 0; i < 2; ++i)
; #pragma unroll
;         for (int j = 0; j < 4; ++j) acc[i][j] = MFMA32(af[i], bfg[j], acc[i][j]);
;     }
	s_mul_i32 s74, s71, 0x6000
	s_add_u32 s75, s74, 0x2000
	s_cmp_eq_u32 s71, 2
	s_cselect_b32 s75, 0x10000, s75
	v_add_u32_e32 v184, s74, v180
	v_add_u32_e32 v186, s75, v182
	v_add_u32_e32 v185, s74, v181
	v_add_u32_e32 v187, s75, v183
	ds_read_b128 v[128:131], v184
	ds_read_b128 v[144:147], v186
	ds_read_b128 v[148:151], v186 offset:2048
	ds_read_b128 v[152:155], v186 offset:4096
	ds_read_b128 v[156:159], v186 offset:6144
	ds_read_b128 v[132:135], v184 offset:2048
	ds_read_b128 v[136:139], v185
	ds_read_b128 v[164:167], v187
	ds_read_b128 v[168:171], v187 offset:2048
	ds_read_b128 v[172:175], v187 offset:4096
	ds_read_b128 v[176:179], v187 offset:6144
	ds_read_b128 v[140:143], v185 offset:2048
	s_add_u32 s71, s71, 1
	s_cmp_eq_u32 s71, 3
	s_cselect_b32 s71, 0, s71
	s_waitcnt lgkmcnt(10)
	v_mfma_f32_32x32x16_bf16 v[112:127], v[128:131], v[144:147], v[112:127]
	s_waitcnt lgkmcnt(9)
	v_mfma_f32_32x32x16_bf16 v[96:111], v[128:131], v[148:151], v[96:111]
	s_waitcnt lgkmcnt(8)
	v_mfma_f32_32x32x16_bf16 v[80:95], v[128:131], v[152:155], v[80:95]
	s_waitcnt lgkmcnt(7)
	v_mfma_f32_32x32x16_bf16 v[64:79], v[128:131], v[156:159], v[64:79]
	s_waitcnt lgkmcnt(6)
	v_mfma_f32_32x32x16_bf16 v[48:63], v[132:135], v[144:147], v[48:63]
	v_mfma_f32_32x32x16_bf16 v[32:47], v[132:135], v[148:151], v[32:47]
	v_mfma_f32_32x32x16_bf16 v[16:31], v[132:135], v[152:155], v[16:31]
	v_mfma_f32_32x32x16_bf16 v[0:15], v[132:135], v[156:159], v[0:15]
	s_waitcnt lgkmcnt(4)
	v_mfma_f32_32x32x16_bf16 v[112:127], v[136:139], v[164:167], v[112:127]
	s_waitcnt lgkmcnt(3)
	v_mfma_f32_32x32x16_bf16 v[96:111], v[136:139], v[168:171], v[96:111]
	s_waitcnt lgkmcnt(2)
	v_mfma_f32_32x32x16_bf16 v[80:95], v[136:139], v[172:175], v[80:95]
	s_waitcnt lgkmcnt(1)
	v_mfma_f32_32x32x16_bf16 v[64:79], v[136:139], v[176:179], v[64:79]
	s_waitcnt lgkmcnt(0)
	v_mfma_f32_32x32x16_bf16 v[48:63], v[140:143], v[164:167], v[48:63]
	v_mfma_f32_32x32x16_bf16 v[32:47], v[140:143], v[168:171], v[32:47]
	v_mfma_f32_32x32x16_bf16 v[16:31], v[140:143], v[172:175], v[16:31]
	v_mfma_f32_32x32x16_bf16 v[0:15], v[140:143], v[176:179], v[0:15]
	s_waitcnt vmcnt(0)
	s_barrier
	s_mul_i32 s74, s71, 0x6000
	s_add_u32 s75, s74, 0x2000
	s_cmp_eq_u32 s71, 2
	s_cselect_b32 s75, 0x10000, s75
	v_add_u32_e32 v184, s74, v180
	v_add_u32_e32 v186, s75, v182
	v_add_u32_e32 v185, s74, v181
	v_add_u32_e32 v187, s75, v183
	ds_read_b128 v[128:131], v184
	ds_read_b128 v[144:147], v186
	ds_read_b128 v[148:151], v186 offset:2048
	ds_read_b128 v[152:155], v186 offset:4096
	ds_read_b128 v[156:159], v186 offset:6144
	ds_read_b128 v[132:135], v184 offset:2048
	ds_read_b128 v[136:139], v185
	ds_read_b128 v[164:167], v187
	ds_read_b128 v[168:171], v187 offset:2048
	ds_read_b128 v[172:175], v187 offset:4096
	ds_read_b128 v[176:179], v187 offset:6144
	ds_read_b128 v[140:143], v185 offset:2048
	s_add_u32 s71, s71, 1
	s_cmp_eq_u32 s71, 3
	s_cselect_b32 s71, 0, s71
	s_waitcnt lgkmcnt(10)
	v_mfma_f32_32x32x16_bf16 v[112:127], v[128:131], v[144:147], v[112:127]
	s_waitcnt lgkmcnt(9)
	v_mfma_f32_32x32x16_bf16 v[96:111], v[128:131], v[148:151], v[96:111]
	s_waitcnt lgkmcnt(8)
	v_mfma_f32_32x32x16_bf16 v[80:95], v[128:131], v[152:155], v[80:95]
	s_waitcnt lgkmcnt(7)
	v_mfma_f32_32x32x16_bf16 v[64:79], v[128:131], v[156:159], v[64:79]
	s_waitcnt lgkmcnt(6)
	v_mfma_f32_32x32x16_bf16 v[48:63], v[132:135], v[144:147], v[48:63]
	v_mfma_f32_32x32x16_bf16 v[32:47], v[132:135], v[148:151], v[32:47]
	v_mfma_f32_32x32x16_bf16 v[16:31], v[132:135], v[152:155], v[16:31]
	v_mfma_f32_32x32x16_bf16 v[0:15], v[132:135], v[156:159], v[0:15]
	s_waitcnt lgkmcnt(4)
	v_mfma_f32_32x32x16_bf16 v[112:127], v[136:139], v[164:167], v[112:127]
	s_waitcnt lgkmcnt(3)
	v_mfma_f32_32x32x16_bf16 v[96:111], v[136:139], v[168:171], v[96:111]
	s_waitcnt lgkmcnt(2)
	v_mfma_f32_32x32x16_bf16 v[80:95], v[136:139], v[172:175], v[80:95]
	s_waitcnt lgkmcnt(1)
	v_mfma_f32_32x32x16_bf16 v[64:79], v[136:139], v[176:179], v[64:79]
	s_waitcnt lgkmcnt(0)
	v_mfma_f32_32x32x16_bf16 v[48:63], v[140:143], v[164:167], v[48:63]
	v_mfma_f32_32x32x16_bf16 v[32:47], v[140:143], v[168:171], v[32:47]
	v_mfma_f32_32x32x16_bf16 v[16:31], v[140:143], v[172:175], v[16:31]
	v_mfma_f32_32x32x16_bf16 v[0:15], v[140:143], v[176:179], v[0:15]
	s_nop 7
	v_readlane_b32 s64, v188, 0
	v_readlane_b32 s65, v188, 1
	v_readlane_b32 s66, v188, 2
	v_readlane_b32 s67, v188, 3
	v_readlane_b32 s68, v188, 4
	v_readlane_b32 s69, v188, 5
	v_readlane_b32 s70, v188, 6
	v_readlane_b32 s71, v188, 7
	v_readlane_b32 s72, v188, 8
	v_readlane_b32 s73, v188, 9
	v_readlane_b32 s74, v188, 10
	v_readlane_b32 s75, v188, 11
	v_readlane_b32 s76, v188, 12
	v_readlane_b32 s77, v188, 13
	v_readlane_b32 s78, v188, 14
	v_readlane_b32 s79, v188, 15
	s_nop 7
	s_branch .LBB0_118

; #define MFMA32(a, b, c) __builtin_amdgcn_mfma_f32_32x32x16_bf16((a), (b), (c), 0, 0, 0)
; #define GA_LOAD(pr_) do { _Pragma("unroll") for (int i = 0; i < 4; ++i) ra[i] = *(const u32x4*)(Ab + (i * 32) * lda + (pr_) * 64); } while (0)
; #define GB_LOAD(kt_) do { const bfr* bk_ = Bb + (kt_) * NB * 32; \
;     _Pragma("unroll") for (int i = 0; i < 4; ++i) rb[i] = *(const u32x4*)(bk_ + (i * 64) * 32); } while (0)
; #define G_STORE(kt_) do { bfr* as_ = S0 + ((kt_) & 1) * GSTAGE; bfr* bs_ = as_ + 128 * 40; \
;     if (apar == ((kt_) & 1)) { _Pragma("unroll") for (int i = 0; i < 4; ++i) *(u32x4*)(as_ + asoff + i * 32 * 40) = ra[i]; } \
;     _Pragma("unroll") for (int i = 0; i < 4; ++i) *(u32x4*)(bs_ + bsoff + i * 64 * 40) = rb[i]; } while (0)
; template <int lda>
; DI void gemm_mainloop(const bfr* __restrict__ A, const bfr* __restrict__ Bt, int NB, int K, int m0, int n0, char* smem, f32x16 (&acc)[2][4]) {
;     ...
;   for (int kt = 0; kt < nk; ++kt) {
;     if (kt + 1 < nk) G_STORE(kt + 1);
;     if (kt + 2 < nk) {
;       GB_LOAD(kt + 2);
;       if ((kt & 1) == 0) GA_LOAD((kt >> 1) + 1);
;     }
;     const bfr* As = S0 + (kt & 1) * GSTAGE;
;     const bfr* Bs = As + 128 * 40;
; #pragma unroll
;     for (int ks = 0; ks < 2; ++ks) {
;       bf16x8 af[2], bfg[4];
; #pragma unroll
;       for (int i = 0; i < 2; ++i) af[i] = *(const bf16x8*)(As + (wr * 64 + i * 32 + r) * 40 + ks * 16 + hl * 8);
; #pragma unroll
;       for (int j = 0; j < 4; ++j) bfg[j] = *(const bf16x8*)(Bs + (wc * 128 + j * 32 + r) * 40 + ks * 16 + hl * 8);
; #pragma unroll
;       for (int i = 0; i < 2; ++i)
; #pragma unroll
;         for (int j = 0; j < 4; ++j) acc[i][j] = MFMA32(af[i], bfg[j], acc[i][j]);
;     }
;     __syncthreads();
;   }
.Lp6_loop:
	s_waitcnt vmcnt(6)
	s_barrier
	s_mul_i32 s74, s71, 0x6000
	s_add_u32 s75, s74, 0x2000
	s_cmp_eq_u32 s71, 2
	s_cselect_b32 s75, 0x10000, s75
	v_add_u32_e32 v183, s74, v179
	v_add_u32_e32 v185, s75, v181
	v_add_u32_e32 v184, s74, v180
	v_add_u32_e32 v186, s75, v182
	ds_read_b128 v[128:131], v183
	ds_read_b128 v[144:147], v185
	ds_read_b128 v[148:151], v185 offset:2048
	ds_read_b128 v[152:155], v185 offset:4096
	ds_read_b128 v[156:159], v185 offset:6144
	ds_read_b128 v[132:135], v183 offset:2048
	ds_read_b128 v[136:139], v184
	ds_read_b128 v[160:163], v186
	ds_read_b128 v[164:167], v186 offset:2048
	ds_read_b128 v[168:171], v186 offset:4096
	ds_read_b128 v[172:175], v186 offset:6144
	ds_read_b128 v[140:143], v184 offset:2048
	s_add_u32 s71, s71, 1
	s_cmp_eq_u32 s71, 3
	s_cselect_b32 s71, 0, s71
	s_waitcnt lgkmcnt(10)
	v_mfma_f32_32x32x16_bf16 v[112:127], v[128:131], v[144:147], v[112:127]
	s_mul_i32 s74, s70, 0x6000
	s_add_u32 s75, s74, s68
	s_mov_b32 m0, s75
	s_add_u32 s76, s74, 0x2000
	s_cmp_eq_u32 s70, 2
	s_cselect_b32 s76, 0x10000, s76
	global_load_lds_dwordx4 v176, s[64:65]
	s_waitcnt lgkmcnt(9)
	v_mfma_f32_32x32x16_bf16 v[96:111], v[128:131], v[148:151], v[96:111]
	s_add_u32 m0, s75, 0x400
	s_add_u32 s76, s76, s69
	global_load_lds_dwordx4 v177, s[64:65]
	s_waitcnt lgkmcnt(8)
	v_mfma_f32_32x32x16_bf16 v[80:95], v[128:131], v[152:155], v[80:95]
	s_mov_b32 m0, s76
	s_add_u32 s64, s64, 64
	s_addc_u32 s65, s65, 0
	global_load_lds_dwordx4 v178, s[66:67]
	s_waitcnt lgkmcnt(7)
	v_mfma_f32_32x32x16_bf16 v[64:79], v[128:131], v[156:159], v[64:79]
	global_load_lds_dwordx4 v178, s[66:67] offset:1024
	s_waitcnt lgkmcnt(6)
	v_mfma_f32_32x32x16_bf16 v[48:63], v[132:135], v[144:147], v[48:63]
	global_load_lds_dwordx4 v178, s[66:67] offset:2048
	v_mfma_f32_32x32x16_bf16 v[32:47], v[132:135], v[148:151], v[32:47]
	global_load_lds_dwordx4 v178, s[66:67] offset:3072
	s_add_u32 s66, s66, 0x10000
	s_addc_u32 s67, s67, 0
	v_mfma_f32_32x32x16_bf16 v[16:31], v[132:135], v[152:155], v[16:31]
	s_add_u32 s70, s70, 1
	s_cmp_eq_u32 s70, 3
	s_cselect_b32 s70, 0, s70
	v_mfma_f32_32x32x16_bf16 v[0:15], v[132:135], v[156:159], v[0:15]
	s_waitcnt lgkmcnt(4)
	v_mfma_f32_32x32x16_bf16 v[112:127], v[136:139], v[160:163], v[112:127]
	s_waitcnt lgkmcnt(3)
	v_mfma_f32_32x32x16_bf16 v[96:111], v[136:139], v[164:167], v[96:111]
	s_waitcnt lgkmcnt(2)
	v_mfma_f32_32x32x16_bf16 v[80:95], v[136:139], v[168:171], v[80:95]
	s_waitcnt lgkmcnt(1)
	v_mfma_f32_32x32x16_bf16 v[64:79], v[136:139], v[172:175], v[64:79]
	s_waitcnt lgkmcnt(0)
	v_mfma_f32_32x32x16_bf16 v[48:63], v[140:143], v[160:163], v[48:63]
	v_mfma_f32_32x32x16_bf16 v[32:47], v[140:143], v[164:167], v[32:47]
	v_mfma_f32_32x32x16_bf16 v[16:31], v[140:143], v[168:171], v[16:31]
	v_mfma_f32_32x32x16_bf16 v[0:15], v[140:143], v[172:175], v[0:15]
	s_add_u32 s72, s72, 1
	s_cmp_lt_u32 s72, 30
	s_cbranch_scc1 .Lp6_loop
	s_waitcnt vmcnt(6)
	s_barrier
	s_mul_i32 s74, s71, 0x6000
	s_add_u32 s75, s74, 0x2000
	s_cmp_eq_u32 s71, 2
	s_cselect_b32 s75, 0x10000, s75
	v_add_u32_e32 v183, s74, v179
	v_add_u32_e32 v185, s75, v181
	v_add_u32_e32 v184, s74, v180
	v_add_u32_e32 v186, s75, v182
	ds_read_b128 v[128:131], v183
	ds_read_b128 v[144:147], v185
	ds_read_b128 v[148:151], v185 offset:2048
	ds_read_b128 v[152:155], v185 offset:4096
	ds_read_b128 v[156:159], v185 offset:6144
	ds_read_b128 v[132:135], v183 offset:2048
	ds_read_b128 v[136:139], v184
	ds_read_b128 v[160:163], v186
	ds_read_b128 v[164:167], v186 offset:2048
	ds_read_b128 v[168:171], v186 offset:4096
	ds_read_b128 v[172:175], v186 offset:6144
	ds_read_b128 v[140:143], v184 offset:2048
	s_add_u32 s71, s71, 1
	s_cmp_eq_u32 s71, 3
	s_cselect_b32 s71, 0, s71
	s_waitcnt lgkmcnt(10)
	v_mfma_f32_32x32x16_bf16 v[112:127], v[128:131], v[144:147], v[112:127]
	s_waitcnt lgkmcnt(9)
	v_mfma_f32_32x32x16_bf16 v[96:111], v[128:131], v[148:151], v[96:111]
	s_waitcnt lgkmcnt(8)
	v_mfma_f32_32x32x16_bf16 v[80:95], v[128:131], v[152:155], v[80:95]
	s_waitcnt lgkmcnt(7)
	v_mfma_f32_32x32x16_bf16 v[64:79], v[128:131], v[156:159], v[64:79]
	s_waitcnt lgkmcnt(6)
	v_mfma_f32_32x32x16_bf16 v[48:63], v[132:135], v[144:147], v[48:63]
	v_mfma_f32_32x32x16_bf16 v[32:47], v[132:135], v[148:151], v[32:47]
	v_mfma_f32_32x32x16_bf16 v[16:31], v[132:135], v[152:155], v[16:31]
	v_mfma_f32_32x32x16_bf16 v[0:15], v[132:135], v[156:159], v[0:15]
	s_waitcnt lgkmcnt(4)
	v_mfma_f32_32x32x16_bf16 v[112:127], v[136:139], v[160:163], v[112:127]
	s_waitcnt lgkmcnt(3)
	v_mfma_f32_32x32x16_bf16 v[96:111], v[136:139], v[164:167], v[96:111]
	s_waitcnt lgkmcnt(2)
	v_mfma_f32_32x32x16_bf16 v[80:95], v[136:139], v[168:171], v[80:95]
	s_waitcnt lgkmcnt(1)
	v_mfma_f32_32x32x16_bf16 v[64:79], v[136:139], v[172:175], v[64:79]
	s_waitcnt lgkmcnt(0)
	v_mfma_f32_32x32x16_bf16 v[48:63], v[140:143], v[160:163], v[48:63]
	v_mfma_f32_32x32x16_bf16 v[32:47], v[140:143], v[164:167], v[32:47]
	v_mfma_f32_32x32x16_bf16 v[16:31], v[140:143], v[168:171], v[16:31]
	v_mfma_f32_32x32x16_bf16 v[0:15], v[140:143], v[172:175], v[0:15]
	s_waitcnt vmcnt(0)
	s_barrier
; DI int crow(int reg, int h) { return (reg & 3) + 8 * (reg >> 2) + 4 * h; }
; template <bool FIRST, bool HAS_H>
; DI void phase_gemm_resid(const Params& p, const bfr* A, const bfr* Wt, const float* gnext, float* ss, char* smem) {
;     ...
;     gemm_mainloop<1024>(A, Wt, 1024, 1024, m0, n0, smem, acc);
;     int tid2 = threadIdx.x;
;     asm volatile("" : "+v"(tid2));
;     const int lane = tid2 & 63, wid = tid2 >> 6, wr = wid >> 1, wc = wid & 1, r = lane & 31, hl = lane >> 5;
;     const float* xsrc = FIRST ? p.x_prompt : X;
;     const int rbase = m0 + wr * 64 + 4 * hl, cbase = n0 + wc * 128 + r;
; #pragma unroll
;     for (int i = 0; i < 2; ++i) {
; #pragma unroll
;       for (int qh = 0; qh < 2; ++qh) {
;         float rs[8];
; #pragma unroll
;         for (int q = 0; q < 8; ++q) rs[q] = 0.f;
; #pragma unroll
;         for (int jh = 0; jh < 2; ++jh) {
;           float xo[2][8];
; #pragma unroll
;           for (int jj = 0; jj < 2; ++jj)
; #pragma unroll
;             for (int q = 0; q < 8; ++q)
;               xo[jj][q] = xsrc[(rbase + i * 32 + crow(qh * 8 + q, 0)) * 1024 + cbase + (jh * 2 + jj) * 32];
	s_mul_i32 s74, s71, 0x6000
	s_add_u32 s75, s74, 0x2000
	s_cmp_eq_u32 s71, 2
	s_cselect_b32 s75, 0x10000, s75
	v_add_u32_e32 v183, s74, v179
	v_add_u32_e32 v185, s75, v181
	v_add_u32_e32 v184, s74, v180
	v_add_u32_e32 v186, s75, v182
	ds_read_b128 v[128:131], v183
	ds_read_b128 v[144:147], v185
	ds_read_b128 v[148:151], v185 offset:2048
	ds_read_b128 v[152:155], v185 offset:4096
	ds_read_b128 v[156:159], v185 offset:6144
	ds_read_b128 v[132:135], v183 offset:2048
	ds_read_b128 v[136:139], v184
	ds_read_b128 v[160:163], v186
	ds_read_b128 v[164:167], v186 offset:2048
	ds_read_b128 v[168:171], v186 offset:4096
	ds_read_b128 v[172:175], v186 offset:6144
	ds_read_b128 v[140:143], v184 offset:2048
	s_add_u32 s71, s71, 1
	s_cmp_eq_u32 s71, 3
	s_cselect_b32 s71, 0, s71
	s_waitcnt lgkmcnt(10)
	v_mfma_f32_32x32x16_bf16 v[112:127], v[128:131], v[144:147], v[112:127]
	s_waitcnt lgkmcnt(9)
	v_mfma_f32_32x32x16_bf16 v[96:111], v[128:131], v[148:151], v[96:111]
	s_waitcnt lgkmcnt(8)
	v_mfma_f32_32x32x16_bf16 v[80:95], v[128:131], v[152:155], v[80:95]
	s_waitcnt lgkmcnt(7)
	v_mfma_f32_32x32x16_bf16 v[64:79], v[128:131], v[156:159], v[64:79]
	s_waitcnt lgkmcnt(6)
	v_mfma_f32_32x32x16_bf16 v[48:63], v[132:135], v[144:147], v[48:63]
	v_mfma_f32_32x32x16_bf16 v[32:47], v[132:135], v[148:151], v[32:47]
	v_mfma_f32_32x32x16_bf16 v[16:31], v[132:135], v[152:155], v[16:31]
	v_mfma_f32_32x32x16_bf16 v[0:15], v[132:135], v[156:159], v[0:15]
	s_waitcnt lgkmcnt(4)
	v_mfma_f32_32x32x16_bf16 v[112:127], v[136:139], v[160:163], v[112:127]
	s_waitcnt lgkmcnt(3)
	v_mfma_f32_32x32x16_bf16 v[96:111], v[136:139], v[164:167], v[96:111]
	s_waitcnt lgkmcnt(2)
	v_mfma_f32_32x32x16_bf16 v[80:95], v[136:139], v[168:171], v[80:95]
	s_waitcnt lgkmcnt(1)
	v_mfma_f32_32x32x16_bf16 v[64:79], v[136:139], v[172:175], v[64:79]
	s_waitcnt lgkmcnt(0)
	v_mfma_f32_32x32x16_bf16 v[48:63], v[140:143], v[160:163], v[48:63]
	v_mfma_f32_32x32x16_bf16 v[32:47], v[140:143], v[164:167], v[32:47]
	v_mfma_f32_32x32x16_bf16 v[16:31], v[140:143], v[168:171], v[16:31]
	v_mfma_f32_32x32x16_bf16 v[0:15], v[140:143], v[172:175], v[0:15]
	s_nop 7
	v_readlane_b32 s64, v187, 0
	v_readlane_b32 s65, v187, 1
	v_readlane_b32 s66, v187, 2
	v_readlane_b32 s67, v187, 3
	v_readlane_b32 s68, v187, 4
	v_readlane_b32 s69, v187, 5
	v_readlane_b32 s70, v187, 6
	v_readlane_b32 s71, v187, 7
	v_readlane_b32 s72, v187, 8
	v_readlane_b32 s73, v187, 9
	v_readlane_b32 s74, v187, 10
	v_readlane_b32 s75, v187, 11
	v_readlane_b32 s76, v187, 12
	v_readlane_b32 s77, v187, 13
	v_readlane_b32 s78, v187, 14
	v_readlane_b32 s79, v187, 15
	s_nop 7
	s_waitcnt vmcnt(1)
	s_nop 0
	s_nop 0
	s_nop 0
	s_waitcnt vmcnt(0)
	s_nop 0
	v_add_u32_e32 v136, v169, v171
	s_nop 0
	v_add_u32_e32 v188, v169, v170
	s_nop 0
	s_nop 0
	s_nop 0
	s_nop 0
	s_nop 0
	s_nop 0
	s_nop 0
	s_nop 0
	s_nop 0
	s_nop 0
	s_nop 0
	s_waitcnt lgkmcnt(0)
	s_nop 0
	s_nop 0
	s_nop 0
	s_nop 0
	s_nop 0
	s_nop 0
	s_nop 0
	s_nop 0
	s_nop 0
	s_nop 0
	s_nop 0
	s_nop 0
	s_nop 0
	s_nop 0
	s_nop 0
	s_nop 0
	s_nop 0
	s_nop 0
	v_mov_b32_e32 v188, v196
	s_waitcnt lgkmcnt(0)
	s_nop 0
	s_nop 0
	v_ashrrev_i32_e32 v190, 1, v188
	v_and_b32_e32 v190, 0xffffffc0, v190
	v_and_b32_e32 v225, 31, v188
	v_add_u32_e32 v190, s40, v190
	v_lshrrev_b32_e32 v191, 3, v188
	v_lshlrev_b32_e32 v188, 1, v188
	v_and_or_b32 v224, v191, 4, v190
	v_and_b32_e32 v188, 0x80, v188
	v_or3_b32 v197, s39, v188, v225
	v_lshlrev_b32_e32 v199, 10, v224
	v_or_b32_e32 v190, v199, v197
	v_ashrrev_i32_e32 v191, 31, v190
	v_lshlrev_b64 v[192:193], 2, v[190:191]
	s_nop 0
	v_lshl_add_u64 v[194:195], s[18:19], 0, v[192:193]
	global_load_dword v188, v[194:195], off
	v_or_b32_e32 v198, 32, v197
	v_or_b32_e32 v226, 0x2400, v199
	v_or_b32_e32 v228, 0x2800, v199
	v_or_b32_e32 v229, 0x2c00, v199
	v_lshl_add_u64 v[192:193], s[16:17], 0, v[192:193]
	s_nop 0
	v_or_b32_e32 v216, 0x400, v199
	v_or_b32_e32 v194, v216, v197
	v_ashrrev_i32_e32 v195, 31, v194
	v_or_b32_e32 v217, 0x800, v199
	v_lshl_add_u64 v[212:213], v[194:195], 2, s[18:19]
	v_or_b32_e32 v214, v217, v197
	v_ashrrev_i32_e32 v195, 31, v199
	v_mov_b32_e32 v194, v190
	v_ashrrev_i32_e32 v215, 31, v214
	v_lshl_add_u64 v[194:195], v[194:195], 2, s[18:19]
	global_load_dword v218, v[194:195], off offset:128
	v_lshl_add_u64 v[214:215], v[214:215], 2, s[18:19]
	global_load_dword v219, v[212:213], off
	global_load_dword v220, v[214:215], off
	v_or_b32_e32 v212, v216, v198
	v_ashrrev_i32_e32 v213, 31, v212
	v_lshl_add_u64 v[212:213], v[212:213], 2, s[18:19]
	global_load_dword v222, v[212:213], off
	s_nop 0
	v_or_b32_e32 v221, 0xc00, v199
	v_or_b32_e32 v223, 0x2000, v199
	v_or_b32_e32 v214, v223, v197
	v_ashrrev_i32_e32 v215, 31, v214
	v_lshl_add_u64 v[214:215], v[214:215], 2, s[18:19]
	v_cmp_eq_u32_e32 vcc, 31, v225
	v_ashrrev_i32_e32 v225, 31, v224
	s_nop 0
	s_nop 0
	s_nop 0
	v_or_b32_e32 v200, v217, v198
	v_ashrrev_i32_e32 v201, 31, v200
	v_lshl_add_u64 v[200:201], v[200:201], 2, s[18:19]
	global_load_dword v227, v[200:201], off
	v_or_b32_e32 v212, v221, v197
	v_or_b32_e32 v200, v226, v197
	v_or_b32_e32 v202, v228, v197
	s_nop 0
	v_ashrrev_i32_e32 v213, 31, v212
	v_ashrrev_i32_e32 v201, 31, v200
	v_ashrrev_i32_e32 v203, 31, v202
	v_lshl_add_u64 v[212:213], v[212:213], 2, s[18:19]
	v_lshl_add_u64 v[200:201], v[200:201], 2, s[18:19]
	v_lshl_add_u64 v[202:203], v[202:203], 2, s[18:19]
	s_nop 0
	s_nop 0
	s_nop 0
	s_nop 0
	v_or_b32_e32 v204, v229, v197
	v_ashrrev_i32_e32 v205, 31, v204
	v_lshl_add_u64 v[204:205], v[204:205], 2, s[18:19]
	v_or_b32_e32 v206, v228, v198
	v_ashrrev_i32_e32 v207, 31, v206
	v_lshl_add_u64 v[206:207], v[206:207], 2, s[18:19]
	s_waitcnt vmcnt(0)
; DI bfr f2bf(float a) { return (bfr)(pack2(a, 0.f) & 0xffffu); }
; DI int crow(int reg, int h) { return (reg & 3) + 8 * (reg >> 2) + 4 * h; }
; template <bool FIRST, bool HAS_H>
; DI void phase_gemm_resid(const Params& p, const bfr* A, const bfr* Wt, const float* gnext, float* ss, char* smem) {
;     ...
;               xo[jj][q] = xsrc[(rbase + i * 32 + crow(qh * 8 + q, 0)) * 1024 + cbase + (jh * 2 + jj) * 32];
; #pragma unroll
;           for (int q = 0; q < 8; ++q) {
;             const int o = (rbase + i * 32 + crow(qh * 8 + q, 0)) * 1024 + cbase;
; #pragma unroll
;             for (int jj = 0; jj < 2; ++jj) {
;               const int j = jh * 2 + jj;
;               const float xn = xo[jj][q] + acc[i][j][qh * 8 + q];
;               X[o + j * 32] = xn;
;               if (HAS_H) Hn[o + j * 32] = f2bf(xn * gnext[cbase + j * 32]);
;               rs[q] += xn * xn;
;             }
;           }
	s_nop 3
	v_add_f32_e32 v98, v98, v227
	s_nop 0
	global_load_dword v210, v[212:213], off
	global_load_dword v211, v[214:215], off
	s_nop 0
	global_load_dword v212, v[200:201], off
	global_load_dword v213, v[202:203], off
	global_load_dword v214, v[204:205], off
	v_or_b32_e32 v200, v221, v198
	v_or_b32_e32 v202, v223, v198
	v_or_b32_e32 v204, v226, v198
	v_ashrrev_i32_e32 v201, 31, v200
	v_ashrrev_i32_e32 v203, 31, v202
	v_ashrrev_i32_e32 v205, 31, v204
	v_or_b32_e32 v208, v229, v198
	v_lshl_add_u64 v[200:201], v[200:201], 2, s[18:19]
	v_lshl_add_u64 v[202:203], v[202:203], 2, s[18:19]
	v_lshl_add_u64 v[204:205], v[204:205], 2, s[18:19]
	v_ashrrev_i32_e32 v209, 31, v208
	v_lshl_add_u64 v[208:209], v[208:209], 2, s[18:19]
	global_load_dword v200, v[200:201], off
	s_nop 0
	global_load_dword v201, v[202:203], off
	s_nop 0
	global_load_dword v202, v[204:205], off
	global_load_dword v203, v[206:207], off
	s_nop 0
	global_load_dword v204, v[208:209], off
	v_add_f32_e32 v205, v112, v188
	v_or_b32_e32 v112, 0x400, v190
	global_store_dword v[192:193], v205, off
	v_lshlrev_b32_e32 v188, 2, v197
	v_add_f32_e32 v207, v96, v218
	v_add_f32_e32 v209, v113, v219
	v_ashrrev_i32_e32 v113, 31, v112
	v_or_b32_e32 v96, 0x420, v190
	global_load_dword v206, v188, s[14:15]
	s_nop 0
	global_store_dword v[192:193], v207, off offset:128
	v_lshl_add_u64 v[112:113], v[112:113], 2, s[16:17]
	v_add_f32_e32 v185, v97, v222
	v_ashrrev_i32_e32 v97, 31, v96
	global_load_dword v208, v188, s[14:15] offset:128
	v_lshl_add_u64 v[96:97], v[96:97], 2, s[16:17]
	global_store_dword v[112:113], v209, off
	s_nop 0
	v_or_b32_e32 v172, 0x800, v190
	v_ashrrev_i32_e32 v173, 31, v172
	global_load_dword v184, v188, s[14:15]
	v_add_f32_e32 v177, v114, v220
	global_store_dword v[96:97], v185, off
	v_lshl_add_u64 v[96:97], v[172:173], 2, s[16:17]
	v_or_b32_e32 v174, 0x820, v190
	global_load_dword v176, v188, s[14:15] offset:128
	v_ashrrev_i32_e32 v175, 31, v174
	global_store_dword v[96:97], v177, off
	global_load_dword v178, v188, s[14:15]
	v_lshl_add_u64 v[96:97], v[174:175], 2, s[16:17]
	global_store_dword v[96:97], v98, off
	global_load_dword v179, v188, s[14:15] offset:128
	s_nop 0
	v_lshl_add_u64 v[158:159], v[172:173], 1, s[10:11]
	v_lshl_add_u64 v[96:97], v[224:225], 2, s[8:9]
	s_waitcnt vmcnt(21)
	v_add_f32_e32 v115, v115, v210
	s_nop 0
	s_waitcnt vmcnt(10)
	v_mul_f32_e32 v112, v205, v206
	s_nop 0
	v_cvt_pk_bf16_f32 v114, v112, s0
	v_lshl_add_u64 v[112:113], v[190:191], 1, s[10:11]
	global_store_short v[112:113], v114, off
	s_waitcnt vmcnt(9)
	v_mul_f32_e32 v114, v207, v208
	v_cvt_pk_bf16_f32 v114, v114, s0
	global_store_short v[112:113], v114, off offset:64
	s_nop 0
	v_or_b32_e32 v154, 0xc00, v190
	v_ashrrev_i32_e32 v155, 31, v154
	v_mul_f32_e32 v152, v98, v98
	s_waitcnt vmcnt(8)
	v_mul_f32_e32 v156, v209, v184
	v_cvt_pk_bf16_f32 v156, v156, s0
	global_store_short v[112:113], v156, off offset:2048
	v_mul_f32_e32 v114, v207, v207
	s_nop 0
	v_add_f32_e32 v169, v119, v214
	v_add_f32_e32 v171, v103, v204
	s_waitcnt vmcnt(5)
	v_mul_f32_e32 v157, v177, v178
	v_cvt_pk_bf16_f32 v157, v157, s0
	global_store_short v[158:159], v157, off
	s_waitcnt vmcnt(4)
	v_mul_f32_e32 v157, v98, v179
	v_cvt_pk_bf16_f32 v157, v157, s0
	v_lshl_add_u64 v[158:159], v[174:175], 1, s[10:11]
	s_nop 0
	global_store_short v[158:159], v157, off
	v_lshl_add_u64 v[158:159], v[154:155], 2, s[16:17]
	global_store_dword v[158:159], v115, off
	global_load_dword v153, v188, s[14:15]
	v_or_b32_e32 v158, 0xc20, v190
	v_ashrrev_i32_e32 v159, 31, v158
	v_add_f32_e32 v157, v99, v200
	v_lshl_add_u64 v[98:99], v[158:159], 2, s[16:17]
	global_store_dword v[98:99], v157, off
	s_nop 0
	global_load_dword v160, v188, s[14:15] offset:128
	v_add_f32_e32 v161, v100, v201
	v_add_f32_e32 v163, v117, v212
	v_add_f32_e32 v165, v118, v213
	v_add_f32_e32 v167, v102, v203
	v_mul_f32_e32 v156, v185, v176
	v_cvt_pk_bf16_f32 v156, v156, s0
	s_nop 0
	v_or_b32_e32 v148, 0x2000, v190
	v_ashrrev_i32_e32 v149, 31, v148
	v_add_f32_e32 v150, v116, v211
	v_lshl_add_u64 v[98:99], v[148:149], 2, s[16:17]
	global_store_dword v[98:99], v150, off
	global_load_dword v151, v188, s[14:15]
	v_or_b32_e32 v116, 0x2400, v190
	s_nop 0
	v_or_b32_e32 v140, 0x2020, v190
	v_ashrrev_i32_e32 v141, 31, v140
	v_lshl_add_u64 v[98:99], v[140:141], 2, s[16:17]
	global_store_dword v[98:99], v161, off
	global_load_dword v162, v188, s[14:15] offset:128
	v_ashrrev_i32_e32 v117, 31, v116
	v_lshl_add_u64 v[98:99], v[116:117], 2, s[16:17]
	v_or_b32_e32 v142, 0x2420, v190
	global_store_dword v[98:99], v163, off
	v_ashrrev_i32_e32 v143, 31, v142
	s_nop 0
	global_load_dword v146, v188, s[14:15]
	v_add_f32_e32 v147, v101, v202
	v_lshl_add_u64 v[98:99], v[142:143], 2, s[16:17]
	global_store_dword v[98:99], v147, off
	global_load_dword v164, v188, s[14:15] offset:128
	v_lshl_add_u64 v[116:117], v[116:117], 1, s[10:11]
	global_store_short v[112:113], v156, off offset:2112
	s_nop 0
	v_or_b32_e32 v136, 0x2800, v190
	v_ashrrev_i32_e32 v137, 31, v136
	v_lshl_add_u64 v[98:99], v[136:137], 2, s[16:17]
	global_store_dword v[98:99], v165, off
	global_load_dword v166, v188, s[14:15]
	v_mul_f32_e32 v156, v185, v185
	v_fmac_f32_e32 v114, v205, v205
	s_nop 0
	v_or_b32_e32 v128, 0x2820, v190
	v_ashrrev_i32_e32 v129, 31, v128
	v_lshl_add_u64 v[98:99], v[128:129], 2, s[16:17]
	global_store_dword v[98:99], v167, off
	global_load_dword v168, v188, s[14:15] offset:128
	v_or_b32_e32 v98, 0x2c00, v190
	v_ashrrev_i32_e32 v99, 31, v98
	v_lshl_add_u64 v[100:101], v[98:99], 2, s[16:17]
	global_store_dword v[100:101], v169, off
	global_load_dword v170, v188, s[14:15]
	v_or_b32_e32 v100, 0x2c20, v190
	v_ashrrev_i32_e32 v101, 31, v100
	v_lshl_add_u64 v[102:103], v[100:101], 2, s[16:17]
	global_store_dword v[102:103], v171, off
	v_or_b32_e32 v102, 64, v197
	v_or_b32_e32 v118, v216, v102
	v_or_b32_e32 v130, v217, v102
	v_or_b32_e32 v132, v221, v102
	v_or_b32_e32 v134, v223, v102
	v_ashrrev_i32_e32 v119, 31, v118
	v_ashrrev_i32_e32 v131, 31, v130
	v_ashrrev_i32_e32 v133, 31, v132
	v_ashrrev_i32_e32 v135, 31, v134
	v_or_b32_e32 v138, v226, v102
	v_or_b32_e32 v144, v228, v102
	v_lshl_add_u64 v[118:119], v[118:119], 2, s[18:19]
	v_lshl_add_u64 v[130:131], v[130:131], 2, s[18:19]
	v_lshl_add_u64 v[132:133], v[132:133], 2, s[18:19]
	v_lshl_add_u64 v[134:135], v[134:135], 2, s[18:19]
	v_ashrrev_i32_e32 v139, 31, v138
	v_ashrrev_i32_e32 v145, 31, v144
	s_waitcnt vmcnt(18)
; DI bfr f2bf(float a) { return (bfr)(pack2(a, 0.f) & 0xffffu); }
; DI int crow(int reg, int h) { return (reg & 3) + 8 * (reg >> 2) + 4 * h; }
; template <bool FIRST, bool HAS_H>
; DI void phase_gemm_resid(const Params& p, const bfr* A, const bfr* Wt, const float* gnext, float* ss, char* smem) {
;     ...
;               xo[jj][q] = xsrc[(rbase + i * 32 + crow(qh * 8 + q, 0)) * 1024 + cbase + (jh * 2 + jj) * 32];
; #pragma unroll
;           for (int q = 0; q < 8; ++q) {
;             const int o = (rbase + i * 32 + crow(qh * 8 + q, 0)) * 1024 + cbase;
; #pragma unroll
;             for (int jj = 0; jj < 2; ++jj) {
;               const int j = jh * 2 + jj;
;               const float xn = xo[jj][q] + acc[i][j][qh * 8 + q];
;               X[o + j * 32] = xn;
;               if (HAS_H) Hn[o + j * 32] = f2bf(xn * gnext[cbase + j * 32]);
;               rs[q] += xn * xn;
;             }
;           }
	v_mul_f32_e32 v103, v115, v153
	v_lshl_add_u64 v[138:139], v[138:139], 2, s[18:19]
	v_lshl_add_u64 v[144:145], v[144:145], 2, s[18:19]
	global_load_dword v172, v[194:195], off offset:256
	global_load_dword v173, v[118:119], off
	s_nop 0
	global_load_dword v130, v[130:131], off
	s_nop 0
	global_load_dword v131, v[132:133], off
	s_nop 0
	global_load_dword v132, v[134:135], off
	global_load_dword v133, v[138:139], off
	s_nop 0
	global_load_dword v134, v[144:145], off
	global_load_dword v135, v[194:195], off offset:384
	v_cvt_pk_bf16_f32 v103, v103, s0
	v_lshl_add_u64 v[118:119], v[154:155], 1, s[10:11]
	global_store_short v[118:119], v103, off
	v_or_b32_e32 v103, 0x60, v197
	v_or_b32_e32 v118, v216, v103
	v_ashrrev_i32_e32 v119, 31, v118
	v_lshl_add_u64 v[118:119], v[118:119], 2, s[18:19]
	global_load_dword v138, v[118:119], off
	s_waitcnt vmcnt(26)
	v_mul_f32_e32 v118, v157, v160
	v_cvt_pk_bf16_f32 v139, v118, s0
	v_lshl_add_u64 v[118:119], v[158:159], 1, s[10:11]
	global_store_short v[118:119], v139, off
	v_or_b32_e32 v118, v217, v103
	v_mul_f32_e32 v139, v157, v157
	v_ashrrev_i32_e32 v119, 31, v118
	v_fmac_f32_e32 v139, v115, v115
	s_waitcnt vmcnt(25)
	v_mul_f32_e32 v115, v150, v151
	v_lshl_add_u64 v[118:119], v[118:119], 2, s[18:19]
	v_cvt_pk_bf16_f32 v115, v115, s0
	global_load_dword v144, v[118:119], off
	v_lshl_add_u64 v[118:119], v[148:149], 1, s[10:11]
	global_store_short v[118:119], v115, off
	s_waitcnt vmcnt(25)
	v_mul_f32_e32 v115, v161, v162
	v_cvt_pk_bf16_f32 v115, v115, s0
	v_lshl_add_u64 v[118:119], v[140:141], 1, s[10:11]
	global_store_short v[118:119], v115, off
	v_or_b32_e32 v118, v221, v103
	v_ashrrev_i32_e32 v119, 31, v118
	v_lshl_add_u64 v[118:119], v[118:119], 2, s[18:19]
	global_load_dword v140, v[118:119], off
	s_waitcnt vmcnt(25)
	v_mul_f32_e32 v118, v163, v146
	v_cvt_pk_bf16_f32 v118, v118, s0
	global_store_short v[116:117], v118, off
	s_waitcnt vmcnt(24)
	v_mul_f32_e32 v116, v147, v164
	v_cvt_pk_bf16_f32 v118, v116, s0
	v_lshl_add_u64 v[116:117], v[142:143], 1, s[10:11]
	global_store_short v[116:117], v118, off
	v_or_b32_e32 v116, v223, v103
	v_ashrrev_i32_e32 v117, 31, v116
	v_lshl_add_u64 v[116:117], v[116:117], 2, s[18:19]
	global_load_dword v141, v[116:117], off
	s_waitcnt vmcnt(23)
	v_mul_f32_e32 v116, v165, v166
	v_cvt_pk_bf16_f32 v118, v116, s0
	v_lshl_add_u64 v[116:117], v[136:137], 1, s[10:11]
	global_store_short v[116:117], v118, off
	v_mul_f32_e32 v142, v147, v147
	global_load_dword v145, v188, s[14:15] offset:128
	v_mul_f32_e32 v115, v161, v161
	v_fmac_f32_e32 v115, v150, v150
	s_waitcnt vmcnt(23)
	v_mul_f32_e32 v116, v167, v168
	v_cvt_pk_bf16_f32 v118, v116, s0
	v_or_b32_e32 v116, v226, v103
	v_ashrrev_i32_e32 v117, 31, v116
	v_lshl_add_u64 v[116:117], v[116:117], 2, s[18:19]
	global_load_dword v136, v[116:117], off
	v_lshl_add_u64 v[116:117], v[128:129], 1, s[10:11]
	global_store_short v[116:117], v118, off
	v_or_b32_e32 v118, v228, v103
	s_waitcnt vmcnt(23)
	v_mul_f32_e32 v116, v169, v170
	v_ashrrev_i32_e32 v119, 31, v118
	v_cvt_pk_bf16_f32 v143, v116, s0
	v_or_b32_e32 v116, v229, v102
	v_lshl_add_u64 v[118:119], v[118:119], 2, s[18:19]
	global_load_dword v146, v[118:119], off
	v_ashrrev_i32_e32 v117, 31, v116
	v_or_b32_e32 v118, v229, v103
	v_lshl_add_u64 v[116:117], v[116:117], 2, s[18:19]
	v_ashrrev_i32_e32 v119, 31, v118
	v_lshl_add_u64 v[118:119], v[118:119], 2, s[18:19]
	global_load_dword v147, v[116:117], off
	global_load_dword v148, v[118:119], off
	v_fmac_f32_e32 v142, v163, v163
	v_mul_f32_e32 v137, v167, v167
	s_waitcnt vmcnt(24)
	v_add_f32_e32 v149, v80, v172
	global_store_dword v[192:193], v149, off offset:256
	v_or_b32_e32 v80, 0x440, v190
	global_load_dword v150, v188, s[14:15] offset:256
	s_waitcnt vmcnt(25)
	v_add_f32_e32 v153, v81, v173
	v_ashrrev_i32_e32 v81, 31, v80
	v_lshl_add_u64 v[80:81], v[80:81], 2, s[16:17]
	s_waitcnt vmcnt(19)
	v_add_f32_e32 v135, v64, v135
	v_or_b32_e32 v64, 0x460, v190
	global_store_dword v[192:193], v135, off offset:384
	global_load_dword v151, v188, s[14:15] offset:384
	v_add_f32_e32 v157, v82, v130
	global_store_dword v[80:81], v153, off
	global_load_dword v154, v188, s[14:15] offset:256
	v_or_b32_e32 v82, 0xc40, v190
	s_waitcnt vmcnt(21)
	v_add_f32_e32 v138, v65, v138
	v_ashrrev_i32_e32 v65, 31, v64
	v_lshl_add_u64 v[64:65], v[64:65], 2, s[16:17]
	global_store_dword v[64:65], v138, off
	v_or_b32_e32 v64, 0x840, v190
	v_ashrrev_i32_e32 v65, 31, v64
	v_lshl_add_u64 v[80:81], v[64:65], 2, s[16:17]
	global_load_dword v155, v188, s[14:15] offset:384
	v_add_f32_e32 v160, v83, v131
	global_store_dword v[80:81], v157, off
	v_or_b32_e32 v80, 0x860, v190
	v_ashrrev_i32_e32 v81, 31, v80
	global_load_dword v158, v188, s[14:15] offset:256
	s_waitcnt vmcnt(23)
	v_add_f32_e32 v144, v66, v144
	v_lshl_add_u64 v[116:117], v[80:81], 2, s[16:17]
	v_ashrrev_i32_e32 v83, 31, v82
	v_or_b32_e32 v66, 0xc60, v190
	global_store_dword v[116:117], v144, off
	v_lshl_add_u64 v[116:117], v[82:83], 2, s[16:17]
	global_load_dword v159, v188, s[14:15] offset:384
	v_add_f32_e32 v163, v84, v132
	global_store_dword v[116:117], v160, off
	s_waitcnt vmcnt(23)
	v_add_f32_e32 v140, v67, v140
	v_ashrrev_i32_e32 v67, 31, v66
	v_lshl_add_u64 v[116:117], v[66:67], 2, s[16:17]
	global_load_dword v161, v188, s[14:15] offset:256
	v_or_b32_e32 v84, 0x2440, v190
	global_store_dword v[116:117], v140, off
	v_or_b32_e32 v116, 0x2040, v190
	v_ashrrev_i32_e32 v117, 31, v116
	v_lshl_add_u64 v[118:119], v[116:117], 2, s[16:17]
	global_load_dword v162, v188, s[14:15] offset:384
	v_add_f32_e32 v166, v85, v133
	global_store_dword v[118:119], v163, off
	v_or_b32_e32 v118, 0x2060, v190
	v_ashrrev_i32_e32 v119, 31, v118
	global_load_dword v164, v188, s[14:15] offset:256
	s_waitcnt vmcnt(25)
; DI bfr f2bf(float a) { return (bfr)(pack2(a, 0.f) & 0xffffu); }
; DI int crow(int reg, int h) { return (reg & 3) + 8 * (reg >> 2) + 4 * h; }
; template <bool FIRST, bool HAS_H>
; DI void phase_gemm_resid(const Params& p, const bfr* A, const bfr* Wt, const float* gnext, float* ss, char* smem) {
;     ...
;               xo[jj][q] = xsrc[(rbase + i * 32 + crow(qh * 8 + q, 0)) * 1024 + cbase + (jh * 2 + jj) * 32];
; #pragma unroll
;           for (int q = 0; q < 8; ++q) {
;             const int o = (rbase + i * 32 + crow(qh * 8 + q, 0)) * 1024 + cbase;
; #pragma unroll
;             for (int jj = 0; jj < 2; ++jj) {
;               const int j = jh * 2 + jj;
;               const float xn = xo[jj][q] + acc[i][j][qh * 8 + q];
;               X[o + j * 32] = xn;
;               if (HAS_H) Hn[o + j * 32] = f2bf(xn * gnext[cbase + j * 32]);
;               rs[q] += xn * xn;
;             }
;           }
	v_add_f32_e32 v141, v68, v141
	v_lshl_add_u64 v[128:129], v[118:119], 2, s[16:17]
	v_ashrrev_i32_e32 v85, 31, v84
	v_or_b32_e32 v68, 0x2460, v190
	global_store_dword v[128:129], v141, off
	v_lshl_add_u64 v[128:129], v[84:85], 2, s[16:17]
	v_fmac_f32_e32 v137, v165, v165
	global_load_dword v165, v188, s[14:15] offset:384
	v_add_f32_e32 v134, v86, v134
	global_store_dword v[128:129], v166, off
	s_waitcnt vmcnt(25)
	v_add_f32_e32 v136, v69, v136
	v_ashrrev_i32_e32 v69, 31, v68
	v_lshl_add_u64 v[128:129], v[68:69], 2, s[16:17]
	global_load_dword v167, v188, s[14:15] offset:256
	v_or_b32_e32 v86, 0x2c40, v190
	global_store_dword v[128:129], v136, off
	v_or_b32_e32 v128, 0x2840, v190
	v_ashrrev_i32_e32 v129, 31, v128
	v_lshl_add_u64 v[130:131], v[128:129], 2, s[16:17]
	global_load_dword v168, v188, s[14:15] offset:384
	s_waitcnt vmcnt(26)
	v_add_f32_e32 v146, v70, v146
	global_store_dword v[130:131], v134, off
	v_or_b32_e32 v130, 0x2860, v190
	v_ashrrev_i32_e32 v131, 31, v130
	global_load_dword v170, v188, s[14:15] offset:256
	v_lshl_add_u64 v[132:133], v[130:131], 2, s[16:17]
	global_store_dword v[132:133], v146, off
	s_waitcnt vmcnt(28)
	v_add_f32_e32 v147, v87, v147
	v_ashrrev_i32_e32 v87, 31, v86
	global_load_dword v172, v188, s[14:15] offset:384
	v_lshl_add_u64 v[132:133], v[86:87], 2, s[16:17]
	v_or_b32_e32 v70, 0x2c60, v190
	global_store_dword v[132:133], v147, off
	s_waitcnt vmcnt(29)
	v_add_f32_e32 v148, v71, v148
	v_ashrrev_i32_e32 v71, 31, v70
	global_load_dword v173, v188, s[14:15] offset:256
	v_lshl_add_u64 v[132:133], v[70:71], 2, s[16:17]
	global_store_dword v[132:133], v148, off
	global_load_dword v132, v188, s[14:15] offset:384
	v_lshl_add_u64 v[98:99], v[98:99], 1, s[10:11]
	global_store_short v[98:99], v143, off
	v_mul_f32_e32 v98, v171, v145
	v_cvt_pk_bf16_f32 v133, v98, s0
	v_lshl_add_u64 v[98:99], v[100:101], 1, s[10:11]
	global_store_short v[98:99], v133, off
	s_waitcnt vmcnt(32)
	v_mul_f32_e32 v99, v149, v150
	v_cvt_pk_bf16_f32 v99, v99, s0
	global_store_short v[112:113], v99, off offset:128
	s_waitcnt vmcnt(31)
	v_mul_f32_e32 v99, v135, v151
	v_cvt_pk_bf16_f32 v99, v99, s0
	global_store_short v[112:113], v99, off offset:192
	s_waitcnt vmcnt(30)
	v_mul_f32_e32 v99, v153, v154
	v_cvt_pk_bf16_f32 v99, v99, s0
	global_store_short v[112:113], v99, off offset:2176
	s_waitcnt vmcnt(29)
	v_mul_f32_e32 v99, v138, v155
	v_cvt_pk_bf16_f32 v99, v99, s0
	global_store_short v[112:113], v99, off offset:2240
	s_waitcnt vmcnt(28)
	v_mul_f32_e32 v99, v157, v158
	v_cvt_pk_bf16_f32 v99, v99, s0
	v_lshl_add_u64 v[64:65], v[64:65], 1, s[10:11]
	global_store_short v[64:65], v99, off
	v_mul_f32_e32 v98, v171, v171
	s_waitcnt vmcnt(27)
	v_mul_f32_e32 v64, v144, v159
	v_cvt_pk_bf16_f32 v99, v64, s0
	v_lshl_add_u64 v[64:65], v[80:81], 1, s[10:11]
	global_store_short v[64:65], v99, off
	v_fmac_f32_e32 v156, v209, v209
	v_fmac_f32_e32 v152, v177, v177
	s_waitcnt vmcnt(26)
	v_mul_f32_e32 v64, v160, v161
	v_cvt_pk_bf16_f32 v80, v64, s0
	v_lshl_add_u64 v[64:65], v[82:83], 1, s[10:11]
	global_store_short v[64:65], v80, off
	v_fmac_f32_e32 v98, v169, v169
	v_fmac_f32_e32 v114, v149, v149
	s_waitcnt vmcnt(25)
	v_mul_f32_e32 v64, v140, v162
	v_cvt_pk_bf16_f32 v80, v64, s0
	v_lshl_add_u64 v[64:65], v[66:67], 1, s[10:11]
	global_store_short v[64:65], v80, off
	v_fmac_f32_e32 v156, v153, v153
	s_waitcnt vmcnt(24)
	v_mul_f32_e32 v64, v163, v164
	v_cvt_pk_bf16_f32 v66, v64, s0
	v_lshl_add_u64 v[64:65], v[116:117], 1, s[10:11]
	global_store_short v[64:65], v66, off
	v_fmac_f32_e32 v152, v157, v157
	v_fmac_f32_e32 v139, v160, v160
	v_fmac_f32_e32 v115, v163, v163
	v_fmac_f32_e32 v142, v166, v166
	s_waitcnt vmcnt(23)
	v_mul_f32_e32 v64, v141, v165
	v_cvt_pk_bf16_f32 v66, v64, s0
	v_lshl_add_u64 v[64:65], v[118:119], 1, s[10:11]
	global_store_short v[64:65], v66, off
	v_fmac_f32_e32 v137, v134, v134
	v_fmac_f32_e32 v98, v147, v147
	s_waitcnt vmcnt(22)
	v_mul_f32_e32 v64, v166, v167
	v_cvt_pk_bf16_f32 v66, v64, s0
	v_lshl_add_u64 v[64:65], v[84:85], 1, s[10:11]
	global_store_short v[64:65], v66, off
	v_fmac_f32_e32 v114, v135, v135
	v_fmac_f32_e32 v156, v138, v138
	s_waitcnt vmcnt(21)
	v_mul_f32_e32 v64, v136, v168
	v_cvt_pk_bf16_f32 v66, v64, s0
	v_lshl_add_u64 v[64:65], v[68:69], 1, s[10:11]
	global_store_short v[64:65], v66, off
	v_fmac_f32_e32 v152, v144, v144
	s_waitcnt vmcnt(20)
	v_mul_f32_e32 v64, v134, v170
	v_cvt_pk_bf16_f32 v66, v64, s0
	v_lshl_add_u64 v[64:65], v[128:129], 1, s[10:11]
	global_store_short v[64:65], v66, off
	v_fmac_f32_e32 v139, v140, v140
	s_waitcnt vmcnt(19)
; DI bfr f2bf(float a) { return (bfr)(pack2(a, 0.f) & 0xffffu); }
; DI int crow(int reg, int h) { return (reg & 3) + 8 * (reg >> 2) + 4 * h; }
; template <bool FIRST, bool HAS_H>
; DI void phase_gemm_resid(const Params& p, const bfr* A, const bfr* Wt, const float* gnext, float* ss, char* smem) {
;     ...
;               if (HAS_H) Hn[o + j * 32] = f2bf(xn * gnext[cbase + j * 32]);
;               rs[q] += xn * xn;
;             }
;           }
;         }
; #pragma unroll
;         for (int q = 0; q < 8; ++q) rs[q] = half32_sum_hi(rs[q]);
;         if (r == 31) {
; #pragma unroll
;           for (int q = 0; q < 8; ++q) unsafeAtomicAdd(ss + rbase + i * 32 + crow(qh * 8 + q, 0), rs[q]);
;         }
	v_mul_f32_e32 v64, v146, v172
	v_cvt_pk_bf16_f32 v66, v64, s0
	v_lshl_add_u64 v[64:65], v[130:131], 1, s[10:11]
	global_store_short v[64:65], v66, off
	v_fmac_f32_e32 v115, v141, v141
	v_fmac_f32_e32 v142, v136, v136
	s_waitcnt vmcnt(18)
	v_mul_f32_e32 v64, v147, v173
	v_cvt_pk_bf16_f32 v66, v64, s0
	v_lshl_add_u64 v[64:65], v[86:87], 1, s[10:11]
	global_store_short v[64:65], v66, off
	s_waitcnt vmcnt(17)
	v_mul_f32_e32 v64, v148, v132
	v_fmac_f32_e32 v137, v146, v146
	v_cvt_pk_bf16_f32 v66, v64, s0
	v_lshl_add_u64 v[64:65], v[70:71], 1, s[10:11]
	v_fmac_f32_e32 v98, v148, v148
	global_store_short v[64:65], v66, off
	v_add_f32_dpp v64, v114, v114 quad_perm:[1,0,3,2] row_mask:0xf bank_mask:0xf bound_ctrl:1
	v_add_f32_dpp v66, v156, v156 quad_perm:[1,0,3,2] row_mask:0xf bank_mask:0xf bound_ctrl:1
	v_add_f32_dpp v68, v152, v152 quad_perm:[1,0,3,2] row_mask:0xf bank_mask:0xf bound_ctrl:1
	v_add_f32_dpp v70, v139, v139 quad_perm:[1,0,3,2] row_mask:0xf bank_mask:0xf bound_ctrl:1
	v_add_f32_dpp v80, v115, v115 quad_perm:[1,0,3,2] row_mask:0xf bank_mask:0xf bound_ctrl:1
	v_add_f32_dpp v82, v142, v142 quad_perm:[1,0,3,2] row_mask:0xf bank_mask:0xf bound_ctrl:1
	v_add_f32_dpp v84, v137, v137 quad_perm:[1,0,3,2] row_mask:0xf bank_mask:0xf bound_ctrl:1
	v_add_f32_dpp v86, v98, v98 quad_perm:[1,0,3,2] row_mask:0xf bank_mask:0xf bound_ctrl:1
	v_add_f32_dpp v64, v64, v64 quad_perm:[2,3,0,1] row_mask:0xf bank_mask:0xf bound_ctrl:1
	v_add_f32_dpp v66, v66, v66 quad_perm:[2,3,0,1] row_mask:0xf bank_mask:0xf bound_ctrl:1
	v_add_f32_dpp v68, v68, v68 quad_perm:[2,3,0,1] row_mask:0xf bank_mask:0xf bound_ctrl:1
	v_add_f32_dpp v70, v70, v70 quad_perm:[2,3,0,1] row_mask:0xf bank_mask:0xf bound_ctrl:1
	v_add_f32_dpp v80, v80, v80 quad_perm:[2,3,0,1] row_mask:0xf bank_mask:0xf bound_ctrl:1
	v_add_f32_dpp v82, v82, v82 quad_perm:[2,3,0,1] row_mask:0xf bank_mask:0xf bound_ctrl:1
	v_add_f32_dpp v84, v84, v84 quad_perm:[2,3,0,1] row_mask:0xf bank_mask:0xf bound_ctrl:1
	v_add_f32_dpp v86, v86, v86 quad_perm:[2,3,0,1] row_mask:0xf bank_mask:0xf bound_ctrl:1
	v_add_f32_dpp v64, v64, v64 row_half_mirror row_mask:0xf bank_mask:0xf bound_ctrl:1
	v_add_f32_dpp v66, v66, v66 row_half_mirror row_mask:0xf bank_mask:0xf bound_ctrl:1
	v_add_f32_dpp v68, v68, v68 row_half_mirror row_mask:0xf bank_mask:0xf bound_ctrl:1
	v_add_f32_dpp v70, v70, v70 row_half_mirror row_mask:0xf bank_mask:0xf bound_ctrl:1
	v_add_f32_dpp v80, v80, v80 row_half_mirror row_mask:0xf bank_mask:0xf bound_ctrl:1
	v_add_f32_dpp v82, v82, v82 row_half_mirror row_mask:0xf bank_mask:0xf bound_ctrl:1
	v_add_f32_dpp v84, v84, v84 row_half_mirror row_mask:0xf bank_mask:0xf bound_ctrl:1
	v_add_f32_dpp v86, v86, v86 row_half_mirror row_mask:0xf bank_mask:0xf bound_ctrl:1
	v_add_f32_dpp v64, v64, v64 row_mirror row_mask:0xf bank_mask:0xf bound_ctrl:1
	v_mov_b32_e32 v65, 0
	v_add_f32_dpp v66, v66, v66 row_mirror row_mask:0xf bank_mask:0xf bound_ctrl:1
	v_mov_b32_e32 v67, 0
	v_add_f32_dpp v68, v68, v68 row_mirror row_mask:0xf bank_mask:0xf bound_ctrl:1
	v_mov_b32_e32 v69, 0
	v_add_f32_dpp v70, v70, v70 row_mirror row_mask:0xf bank_mask:0xf bound_ctrl:1
	v_mov_b32_e32 v71, 0
	v_add_f32_dpp v80, v80, v80 row_mirror row_mask:0xf bank_mask:0xf bound_ctrl:1
	v_mov_b32_e32 v81, 0
	v_add_f32_dpp v82, v82, v82 row_mirror row_mask:0xf bank_mask:0xf bound_ctrl:1
	v_mov_b32_e32 v83, 0
	v_add_f32_dpp v84, v84, v84 row_mirror row_mask:0xf bank_mask:0xf bound_ctrl:1
	v_mov_b32_e32 v85, 0
	v_add_f32_dpp v86, v86, v86 row_mirror row_mask:0xf bank_mask:0xf bound_ctrl:1
	v_mov_b32_e32 v87, 0
	v_mov_b32_dpp v65, v64 row_bcast:15 row_mask:0xa bank_mask:0xf
	v_mov_b32_dpp v67, v66 row_bcast:15 row_mask:0xa bank_mask:0xf
	v_mov_b32_dpp v69, v68 row_bcast:15 row_mask:0xa bank_mask:0xf
	v_mov_b32_dpp v71, v70 row_bcast:15 row_mask:0xa bank_mask:0xf
	v_mov_b32_dpp v81, v80 row_bcast:15 row_mask:0xa bank_mask:0xf
	v_mov_b32_dpp v83, v82 row_bcast:15 row_mask:0xa bank_mask:0xf
	v_mov_b32_dpp v85, v84 row_bcast:15 row_mask:0xa bank_mask:0xf
	v_mov_b32_dpp v87, v86 row_bcast:15 row_mask:0xa bank_mask:0xf
	s_and_saveexec_b64 s[4:5], vcc
	s_cbranch_execz .LBB0_856
	v_add_f32_e32 v64, v64, v65
	v_add_f32_e32 v86, v86, v87
	v_add_f32_e32 v84, v84, v85
	v_add_f32_e32 v82, v82, v83
	v_add_f32_e32 v80, v80, v81
	v_add_f32_e32 v70, v70, v71
	v_add_f32_e32 v68, v68, v69
	v_add_f32_e32 v66, v66, v67
	global_atomic_add_f32 v[96:97], v64, off
	global_atomic_add_f32 v[96:97], v66, off offset:4
	global_atomic_add_f32 v[96:97], v68, off offset:8
	global_atomic_add_f32 v[96:97], v70, off offset:12
	global_atomic_add_f32 v[96:97], v80, off offset:32
	global_atomic_add_f32 v[96:97], v82, off offset:36
	global_atomic_add_f32 v[96:97], v84, off offset:40
	global_atomic_add_f32 v[96:97], v86, off offset:44

; #define MFMA32(a, b, c) __builtin_amdgcn_mfma_f32_32x32x16_bf16((a), (b), (c), 0, 0, 0)
; #define GA_LOAD(pr_) do { _Pragma("unroll") for (int i = 0; i < 4; ++i) ra[i] = *(const u32x4*)(Ab + (i * 32) * lda + (pr_) * 64); } while (0)
; #define GB_LOAD(kt_) do { const bfr* bk_ = Bb + (kt_) * NB * 32; \
;     _Pragma("unroll") for (int i = 0; i < 4; ++i) rb[i] = *(const u32x4*)(bk_ + (i * 64) * 32); } while (0)
; #define G_STORE(kt_) do { bfr* as_ = S0 + ((kt_) & 1) * GSTAGE; bfr* bs_ = as_ + 128 * 40; \
;     if (apar == ((kt_) & 1)) { _Pragma("unroll") for (int i = 0; i < 4; ++i) *(u32x4*)(as_ + asoff + i * 32 * 40) = ra[i]; } \
;     _Pragma("unroll") for (int i = 0; i < 4; ++i) *(u32x4*)(bs_ + bsoff + i * 64 * 40) = rb[i]; } while (0)
; template <int lda>
; DI void gemm_mainloop(const bfr* __restrict__ A, const bfr* __restrict__ Bt, int NB, int K, int m0, int n0, char* smem, f32x16 (&acc)[2][4]) {
;     ...
;   for (int kt = 0; kt < nk; ++kt) {
;     if (kt + 1 < nk) G_STORE(kt + 1);
;     if (kt + 2 < nk) {
;       GB_LOAD(kt + 2);
;       if ((kt & 1) == 0) GA_LOAD((kt >> 1) + 1);
;     }
;     const bfr* As = S0 + (kt & 1) * GSTAGE;
;     const bfr* Bs = As + 128 * 40;
; #pragma unroll
;     for (int ks = 0; ks < 2; ++ks) {
;       bf16x8 af[2], bfg[4];
; #pragma unroll
;       for (int i = 0; i < 2; ++i) af[i] = *(const bf16x8*)(As + (wr * 64 + i * 32 + r) * 40 + ks * 16 + hl * 8);
; #pragma unroll
;       for (int j = 0; j < 4; ++j) bfg[j] = *(const bf16x8*)(Bs + (wc * 128 + j * 32 + r) * 40 + ks * 16 + hl * 8);
; #pragma unroll
;       for (int i = 0; i < 2; ++i)
; #pragma unroll
;         for (int j = 0; j < 4; ++j) acc[i][j] = MFMA32(af[i], bfg[j], acc[i][j]);
;     }
;     __syncthreads();
;   }
.Lp8_loop:
	s_waitcnt vmcnt(6)
	s_barrier
	s_mul_i32 s74, s71, 0x6000
	s_add_u32 s75, s74, 0x2000
	s_cmp_eq_u32 s71, 2
	s_cselect_b32 s75, 0x10000, s75
	v_add_u32_e32 v183, s74, v179
	v_add_u32_e32 v185, s75, v181
	v_add_u32_e32 v184, s74, v180
	v_add_u32_e32 v186, s75, v182
	ds_read_b128 v[128:131], v183
	ds_read_b128 v[144:147], v185
	ds_read_b128 v[148:151], v185 offset:2048
	ds_read_b128 v[152:155], v185 offset:4096
	ds_read_b128 v[156:159], v185 offset:6144
	ds_read_b128 v[132:135], v183 offset:2048
	ds_read_b128 v[136:139], v184
	ds_read_b128 v[160:163], v186
	ds_read_b128 v[164:167], v186 offset:2048
	ds_read_b128 v[168:171], v186 offset:4096
	ds_read_b128 v[172:175], v186 offset:6144
	ds_read_b128 v[140:143], v184 offset:2048
	s_add_u32 s71, s71, 1
	s_cmp_eq_u32 s71, 3
	s_cselect_b32 s71, 0, s71
	s_waitcnt lgkmcnt(10)
	v_mfma_f32_32x32x16_bf16 v[112:127], v[128:131], v[144:147], v[112:127]
	s_mul_i32 s74, s70, 0x6000
	s_add_u32 s75, s74, s68
	s_mov_b32 m0, s75
	s_add_u32 s76, s74, 0x2000
	s_cmp_eq_u32 s70, 2
	s_cselect_b32 s76, 0x10000, s76
	global_load_lds_dwordx4 v176, s[64:65]
	s_waitcnt lgkmcnt(9)
	v_mfma_f32_32x32x16_bf16 v[96:111], v[128:131], v[148:151], v[96:111]
	s_add_u32 m0, s75, 0x400
	s_add_u32 s76, s76, s69
	global_load_lds_dwordx4 v177, s[64:65]
	s_waitcnt lgkmcnt(8)
	v_mfma_f32_32x32x16_bf16 v[80:95], v[128:131], v[152:155], v[80:95]
	s_mov_b32 m0, s76
	s_add_u32 s64, s64, 64
	s_addc_u32 s65, s65, 0
	global_load_lds_dwordx4 v178, s[66:67]
	s_waitcnt lgkmcnt(7)
	v_mfma_f32_32x32x16_bf16 v[64:79], v[128:131], v[156:159], v[64:79]
	global_load_lds_dwordx4 v178, s[66:67] offset:1024
	s_waitcnt lgkmcnt(6)
	v_mfma_f32_32x32x16_bf16 v[48:63], v[132:135], v[144:147], v[48:63]
	global_load_lds_dwordx4 v178, s[66:67] offset:2048
	v_mfma_f32_32x32x16_bf16 v[32:47], v[132:135], v[148:151], v[32:47]
	global_load_lds_dwordx4 v178, s[66:67] offset:3072
	s_add_u32 s66, s66, 0x10000
	s_addc_u32 s67, s67, 0
	v_mfma_f32_32x32x16_bf16 v[16:31], v[132:135], v[152:155], v[16:31]
	s_add_u32 s70, s70, 1
	s_cmp_eq_u32 s70, 3
	s_cselect_b32 s70, 0, s70
	v_mfma_f32_32x32x16_bf16 v[0:15], v[132:135], v[156:159], v[0:15]
	s_waitcnt lgkmcnt(4)
	v_mfma_f32_32x32x16_bf16 v[112:127], v[136:139], v[160:163], v[112:127]
	s_waitcnt lgkmcnt(3)
	v_mfma_f32_32x32x16_bf16 v[96:111], v[136:139], v[164:167], v[96:111]
	s_waitcnt lgkmcnt(2)
	v_mfma_f32_32x32x16_bf16 v[80:95], v[136:139], v[168:171], v[80:95]
	s_waitcnt lgkmcnt(1)
	v_mfma_f32_32x32x16_bf16 v[64:79], v[136:139], v[172:175], v[64:79]
	s_waitcnt lgkmcnt(0)
	v_mfma_f32_32x32x16_bf16 v[48:63], v[140:143], v[160:163], v[48:63]
	v_mfma_f32_32x32x16_bf16 v[32:47], v[140:143], v[164:167], v[32:47]
	v_mfma_f32_32x32x16_bf16 v[16:31], v[140:143], v[168:171], v[16:31]
	v_mfma_f32_32x32x16_bf16 v[0:15], v[140:143], v[172:175], v[0:15]
	s_add_u32 s72, s72, 1
	s_cmp_lt_u32 s72, 30
	s_cbranch_scc1 .Lp8_loop
	s_waitcnt vmcnt(6)
	s_barrier
; #define MFMA32(a, b, c) __builtin_amdgcn_mfma_f32_32x32x16_bf16((a), (b), (c), 0, 0, 0)
; template <int lda>
; DI void gemm_mainloop(const bfr* __restrict__ A, const bfr* __restrict__ Bt, int NB, int K, int m0, int n0, char* smem, f32x16 (&acc)[2][4]) {
;     ...
;     for (int ks = 0; ks < 2; ++ks) {
;       bf16x8 af[2], bfg[4];
; #pragma unroll
;       for (int i = 0; i < 2; ++i) af[i] = *(const bf16x8*)(As + (wr * 64 + i * 32 + r) * 40 + ks * 16 + hl * 8);
; #pragma unroll
;       for (int j = 0; j < 4; ++j) bfg[j] = *(const bf16x8*)(Bs + (wc * 128 + j * 32 + r) * 40 + ks * 16 + hl * 8);
; #pragma unroll
;       for (int i = 0; i < 2; ++i)
; #pragma unroll
;         for (int j = 0; j < 4; ++j) acc[i][j] = MFMA32(af[i], bfg[j], acc[i][j]);
;     }
	s_mul_i32 s74, s71, 0x6000
	s_add_u32 s75, s74, 0x2000
	s_cmp_eq_u32 s71, 2
	s_cselect_b32 s75, 0x10000, s75
	v_add_u32_e32 v183, s74, v179
	v_add_u32_e32 v185, s75, v181
	v_add_u32_e32 v184, s74, v180
	v_add_u32_e32 v186, s75, v182
	ds_read_b128 v[128:131], v183
	ds_read_b128 v[144:147], v185
	ds_read_b128 v[148:151], v185 offset:2048
	ds_read_b128 v[152:155], v185 offset:4096
	ds_read_b128 v[156:159], v185 offset:6144
	ds_read_b128 v[132:135], v183 offset:2048
	ds_read_b128 v[136:139], v184
	ds_read_b128 v[160:163], v186
	ds_read_b128 v[164:167], v186 offset:2048
	ds_read_b128 v[168:171], v186 offset:4096
	ds_read_b128 v[172:175], v186 offset:6144
	ds_read_b128 v[140:143], v184 offset:2048
	s_add_u32 s71, s71, 1
	s_cmp_eq_u32 s71, 3
	s_cselect_b32 s71, 0, s71
	s_waitcnt lgkmcnt(10)
	v_mfma_f32_32x32x16_bf16 v[112:127], v[128:131], v[144:147], v[112:127]
	s_waitcnt lgkmcnt(9)
	v_mfma_f32_32x32x16_bf16 v[96:111], v[128:131], v[148:151], v[96:111]
	s_waitcnt lgkmcnt(8)
	v_mfma_f32_32x32x16_bf16 v[80:95], v[128:131], v[152:155], v[80:95]
	s_waitcnt lgkmcnt(7)
	v_mfma_f32_32x32x16_bf16 v[64:79], v[128:131], v[156:159], v[64:79]
	s_waitcnt lgkmcnt(6)
	v_mfma_f32_32x32x16_bf16 v[48:63], v[132:135], v[144:147], v[48:63]
	v_mfma_f32_32x32x16_bf16 v[32:47], v[132:135], v[148:151], v[32:47]
	v_mfma_f32_32x32x16_bf16 v[16:31], v[132:135], v[152:155], v[16:31]
	v_mfma_f32_32x32x16_bf16 v[0:15], v[132:135], v[156:159], v[0:15]
	s_waitcnt lgkmcnt(4)
	v_mfma_f32_32x32x16_bf16 v[112:127], v[136:139], v[160:163], v[112:127]
	s_waitcnt lgkmcnt(3)
	v_mfma_f32_32x32x16_bf16 v[96:111], v[136:139], v[164:167], v[96:111]
	s_waitcnt lgkmcnt(2)
	v_mfma_f32_32x32x16_bf16 v[80:95], v[136:139], v[168:171], v[80:95]
	s_waitcnt lgkmcnt(1)
	v_mfma_f32_32x32x16_bf16 v[64:79], v[136:139], v[172:175], v[64:79]
	s_waitcnt lgkmcnt(0)
	v_mfma_f32_32x32x16_bf16 v[48:63], v[140:143], v[160:163], v[48:63]
	v_mfma_f32_32x32x16_bf16 v[32:47], v[140:143], v[164:167], v[32:47]
	v_mfma_f32_32x32x16_bf16 v[16:31], v[140:143], v[168:171], v[16:31]
	v_mfma_f32_32x32x16_bf16 v[0:15], v[140:143], v[172:175], v[0:15]
	s_waitcnt vmcnt(0)
	s_barrier
	s_mul_i32 s74, s71, 0x6000
	s_add_u32 s75, s74, 0x2000
	s_cmp_eq_u32 s71, 2
	s_cselect_b32 s75, 0x10000, s75
	v_add_u32_e32 v183, s74, v179
	v_add_u32_e32 v185, s75, v181
	v_add_u32_e32 v184, s74, v180
	v_add_u32_e32 v186, s75, v182
	ds_read_b128 v[128:131], v183
	ds_read_b128 v[144:147], v185
	ds_read_b128 v[148:151], v185 offset:2048
	ds_read_b128 v[152:155], v185 offset:4096
	ds_read_b128 v[156:159], v185 offset:6144
	ds_read_b128 v[132:135], v183 offset:2048
	ds_read_b128 v[136:139], v184
	ds_read_b128 v[160:163], v186
	ds_read_b128 v[164:167], v186 offset:2048
	ds_read_b128 v[168:171], v186 offset:4096
	ds_read_b128 v[172:175], v186 offset:6144
	ds_read_b128 v[140:143], v184 offset:2048
	s_add_u32 s71, s71, 1
	s_cmp_eq_u32 s71, 3
	s_cselect_b32 s71, 0, s71
	s_waitcnt lgkmcnt(10)
	v_mfma_f32_32x32x16_bf16 v[112:127], v[128:131], v[144:147], v[112:127]
	s_waitcnt lgkmcnt(9)
	v_mfma_f32_32x32x16_bf16 v[96:111], v[128:131], v[148:151], v[96:111]
	s_waitcnt lgkmcnt(8)
	v_mfma_f32_32x32x16_bf16 v[80:95], v[128:131], v[152:155], v[80:95]
	s_waitcnt lgkmcnt(7)
	v_mfma_f32_32x32x16_bf16 v[64:79], v[128:131], v[156:159], v[64:79]
	s_waitcnt lgkmcnt(6)
	v_mfma_f32_32x32x16_bf16 v[48:63], v[132:135], v[144:147], v[48:63]
	v_mfma_f32_32x32x16_bf16 v[32:47], v[132:135], v[148:151], v[32:47]
	v_mfma_f32_32x32x16_bf16 v[16:31], v[132:135], v[152:155], v[16:31]
	v_mfma_f32_32x32x16_bf16 v[0:15], v[132:135], v[156:159], v[0:15]
	s_waitcnt lgkmcnt(4)
	v_mfma_f32_32x32x16_bf16 v[112:127], v[136:139], v[160:163], v[112:127]
	s_waitcnt lgkmcnt(3)
	v_mfma_f32_32x32x16_bf16 v[96:111], v[136:139], v[164:167], v[96:111]
	s_waitcnt lgkmcnt(2)
	v_mfma_f32_32x32x16_bf16 v[80:95], v[136:139], v[168:171], v[80:95]
	s_waitcnt lgkmcnt(1)
	v_mfma_f32_32x32x16_bf16 v[64:79], v[136:139], v[172:175], v[64:79]
	s_waitcnt lgkmcnt(0)
	v_mfma_f32_32x32x16_bf16 v[48:63], v[140:143], v[160:163], v[48:63]
	v_mfma_f32_32x32x16_bf16 v[32:47], v[140:143], v[164:167], v[32:47]
	v_mfma_f32_32x32x16_bf16 v[16:31], v[140:143], v[168:171], v[16:31]
	v_mfma_f32_32x32x16_bf16 v[0:15], v[140:143], v[172:175], v[0:15]
	s_nop 7
	v_readlane_b32 s64, v187, 0
	v_readlane_b32 s65, v187, 1
	v_readlane_b32 s66, v187, 2
	v_readlane_b32 s67, v187, 3
	v_readlane_b32 s68, v187, 4
	v_readlane_b32 s69, v187, 5
	v_readlane_b32 s70, v187, 6
	v_readlane_b32 s71, v187, 7
	v_readlane_b32 s72, v187, 8
	v_readlane_b32 s73, v187, 9
	v_readlane_b32 s74, v187, 10
	v_readlane_b32 s75, v187, 11
	v_readlane_b32 s76, v187, 12
	v_readlane_b32 s77, v187, 13
	v_readlane_b32 s78, v187, 14
	v_readlane_b32 s79, v187, 15
	s_nop 7
	s_branch .LBB0_922

; #define MFMA32(a, b, c) __builtin_amdgcn_mfma_f32_32x32x16_bf16((a), (b), (c), 0, 0, 0)
; #define GA_LOAD(pr_) do { _Pragma("unroll") for (int i = 0; i < 4; ++i) ra[i] = *(const u32x4*)(Ab + (i * 32) * lda + (pr_) * 64); } while (0)
; #define GB_LOAD(kt_) do { const bfr* bk_ = Bb + (kt_) * NB * 32; \
;     _Pragma("unroll") for (int i = 0; i < 4; ++i) rb[i] = *(const u32x4*)(bk_ + (i * 64) * 32); } while (0)
; #define G_STORE(kt_) do { bfr* as_ = S0 + ((kt_) & 1) * GSTAGE; bfr* bs_ = as_ + 128 * 40; \
;     if (apar == ((kt_) & 1)) { _Pragma("unroll") for (int i = 0; i < 4; ++i) *(u32x4*)(as_ + asoff + i * 32 * 40) = ra[i]; } \
;     _Pragma("unroll") for (int i = 0; i < 4; ++i) *(u32x4*)(bs_ + bsoff + i * 64 * 40) = rb[i]; } while (0)
; template <int lda>
; DI void gemm_mainloop(const bfr* __restrict__ A, const bfr* __restrict__ Bt, int NB, int K, int m0, int n0, char* smem, f32x16 (&acc)[2][4]) {
;     ...
;   for (int kt = 0; kt < nk; ++kt) {
;     if (kt + 1 < nk) G_STORE(kt + 1);
;     if (kt + 2 < nk) {
;       GB_LOAD(kt + 2);
;       if ((kt & 1) == 0) GA_LOAD((kt >> 1) + 1);
;     }
;     const bfr* As = S0 + (kt & 1) * GSTAGE;
;     const bfr* Bs = As + 128 * 40;
; #pragma unroll
;     for (int ks = 0; ks < 2; ++ks) {
;       bf16x8 af[2], bfg[4];
; #pragma unroll
;       for (int i = 0; i < 2; ++i) af[i] = *(const bf16x8*)(As + (wr * 64 + i * 32 + r) * 40 + ks * 16 + hl * 8);
; #pragma unroll
;       for (int j = 0; j < 4; ++j) bfg[j] = *(const bf16x8*)(Bs + (wc * 128 + j * 32 + r) * 40 + ks * 16 + hl * 8);
; #pragma unroll
;       for (int i = 0; i < 2; ++i)
; #pragma unroll
;         for (int j = 0; j < 4; ++j) acc[i][j] = MFMA32(af[i], bfg[j], acc[i][j]);
;     }
;     __syncthreads();
;   }
.Lp10_loop:
	s_waitcnt vmcnt(6)
	s_barrier
	s_mul_i32 s74, s71, 0x6000
	s_add_u32 s75, s74, 0x2000
	s_cmp_eq_u32 s71, 2
	s_cselect_b32 s75, 0x10000, s75
	v_add_u32_e32 v183, s74, v179
	v_add_u32_e32 v185, s75, v181
	v_add_u32_e32 v184, s74, v180
	v_add_u32_e32 v186, s75, v182
	ds_read_b128 v[128:131], v183
	ds_read_b128 v[144:147], v185
	ds_read_b128 v[148:151], v185 offset:2048
	ds_read_b128 v[152:155], v185 offset:4096
	ds_read_b128 v[156:159], v185 offset:6144
	ds_read_b128 v[132:135], v183 offset:2048
	ds_read_b128 v[136:139], v184
	ds_read_b128 v[160:163], v186
	ds_read_b128 v[164:167], v186 offset:2048
	ds_read_b128 v[168:171], v186 offset:4096
	ds_read_b128 v[172:175], v186 offset:6144
	ds_read_b128 v[140:143], v184 offset:2048
	s_add_u32 s71, s71, 1
	s_cmp_eq_u32 s71, 3
	s_cselect_b32 s71, 0, s71
	s_waitcnt lgkmcnt(10)
	v_mfma_f32_32x32x16_bf16 v[112:127], v[128:131], v[144:147], v[112:127]
	s_mul_i32 s74, s70, 0x6000
	s_add_u32 s75, s74, s68
	s_mov_b32 m0, s75
	s_add_u32 s76, s74, 0x2000
	s_cmp_eq_u32 s70, 2
	s_cselect_b32 s76, 0x10000, s76
	global_load_lds_dwordx4 v176, s[64:65]
	s_waitcnt lgkmcnt(9)
	v_mfma_f32_32x32x16_bf16 v[96:111], v[128:131], v[148:151], v[96:111]
	s_add_u32 m0, s75, 0x400
	s_add_u32 s76, s76, s69
	global_load_lds_dwordx4 v177, s[64:65]
	s_waitcnt lgkmcnt(8)
	v_mfma_f32_32x32x16_bf16 v[80:95], v[128:131], v[152:155], v[80:95]
	s_mov_b32 m0, s76
	s_add_u32 s64, s64, 64
	s_addc_u32 s65, s65, 0
	global_load_lds_dwordx4 v178, s[66:67]
	s_waitcnt lgkmcnt(7)
	v_mfma_f32_32x32x16_bf16 v[64:79], v[128:131], v[156:159], v[64:79]
	global_load_lds_dwordx4 v178, s[66:67] offset:1024
	s_waitcnt lgkmcnt(6)
	v_mfma_f32_32x32x16_bf16 v[48:63], v[132:135], v[144:147], v[48:63]
	global_load_lds_dwordx4 v178, s[66:67] offset:2048
	v_mfma_f32_32x32x16_bf16 v[32:47], v[132:135], v[148:151], v[32:47]
	global_load_lds_dwordx4 v178, s[66:67] offset:3072
	s_add_u32 s66, s66, 0x10000
	s_addc_u32 s67, s67, 0
	v_mfma_f32_32x32x16_bf16 v[16:31], v[132:135], v[152:155], v[16:31]
	s_add_u32 s70, s70, 1
	s_cmp_eq_u32 s70, 3
	s_cselect_b32 s70, 0, s70
	v_mfma_f32_32x32x16_bf16 v[0:15], v[132:135], v[156:159], v[0:15]
	s_waitcnt lgkmcnt(4)
	v_mfma_f32_32x32x16_bf16 v[112:127], v[136:139], v[160:163], v[112:127]
	s_waitcnt lgkmcnt(3)
	v_mfma_f32_32x32x16_bf16 v[96:111], v[136:139], v[164:167], v[96:111]
	s_waitcnt lgkmcnt(2)
	v_mfma_f32_32x32x16_bf16 v[80:95], v[136:139], v[168:171], v[80:95]
	s_waitcnt lgkmcnt(1)
	v_mfma_f32_32x32x16_bf16 v[64:79], v[136:139], v[172:175], v[64:79]
	s_waitcnt lgkmcnt(0)
	v_mfma_f32_32x32x16_bf16 v[48:63], v[140:143], v[160:163], v[48:63]
	v_mfma_f32_32x32x16_bf16 v[32:47], v[140:143], v[164:167], v[32:47]
	v_mfma_f32_32x32x16_bf16 v[16:31], v[140:143], v[168:171], v[16:31]
	v_mfma_f32_32x32x16_bf16 v[0:15], v[140:143], v[172:175], v[0:15]
	s_add_u32 s72, s72, 1
	s_cmp_lt_u32 s72, 30
	s_cbranch_scc1 .Lp10_loop
	s_waitcnt vmcnt(6)
	s_barrier
	s_mul_i32 s74, s71, 0x6000
	s_add_u32 s75, s74, 0x2000
	s_cmp_eq_u32 s71, 2
	s_cselect_b32 s75, 0x10000, s75
	v_add_u32_e32 v183, s74, v179
	v_add_u32_e32 v185, s75, v181
	v_add_u32_e32 v184, s74, v180
	v_add_u32_e32 v186, s75, v182
	ds_read_b128 v[128:131], v183
	ds_read_b128 v[144:147], v185
	ds_read_b128 v[148:151], v185 offset:2048
	ds_read_b128 v[152:155], v185 offset:4096
	ds_read_b128 v[156:159], v185 offset:6144
	ds_read_b128 v[132:135], v183 offset:2048
	ds_read_b128 v[136:139], v184
	ds_read_b128 v[160:163], v186
	ds_read_b128 v[164:167], v186 offset:2048
	ds_read_b128 v[168:171], v186 offset:4096
	ds_read_b128 v[172:175], v186 offset:6144
	ds_read_b128 v[140:143], v184 offset:2048
	s_add_u32 s71, s71, 1
	s_cmp_eq_u32 s71, 3
	s_cselect_b32 s71, 0, s71
	s_waitcnt lgkmcnt(10)
	v_mfma_f32_32x32x16_bf16 v[112:127], v[128:131], v[144:147], v[112:127]
	s_waitcnt lgkmcnt(9)
	v_mfma_f32_32x32x16_bf16 v[96:111], v[128:131], v[148:151], v[96:111]
	s_waitcnt lgkmcnt(8)
	v_mfma_f32_32x32x16_bf16 v[80:95], v[128:131], v[152:155], v[80:95]
	s_waitcnt lgkmcnt(7)
	v_mfma_f32_32x32x16_bf16 v[64:79], v[128:131], v[156:159], v[64:79]
	s_waitcnt lgkmcnt(6)
	v_mfma_f32_32x32x16_bf16 v[48:63], v[132:135], v[144:147], v[48:63]
	v_mfma_f32_32x32x16_bf16 v[32:47], v[132:135], v[148:151], v[32:47]
	v_mfma_f32_32x32x16_bf16 v[16:31], v[132:135], v[152:155], v[16:31]
	v_mfma_f32_32x32x16_bf16 v[0:15], v[132:135], v[156:159], v[0:15]
	s_waitcnt lgkmcnt(4)
	v_mfma_f32_32x32x16_bf16 v[112:127], v[136:139], v[160:163], v[112:127]
	s_waitcnt lgkmcnt(3)
	v_mfma_f32_32x32x16_bf16 v[96:111], v[136:139], v[164:167], v[96:111]
	s_waitcnt lgkmcnt(2)
	v_mfma_f32_32x32x16_bf16 v[80:95], v[136:139], v[168:171], v[80:95]
	s_waitcnt lgkmcnt(1)
	v_mfma_f32_32x32x16_bf16 v[64:79], v[136:139], v[172:175], v[64:79]
	s_waitcnt lgkmcnt(0)
	v_mfma_f32_32x32x16_bf16 v[48:63], v[140:143], v[160:163], v[48:63]
	v_mfma_f32_32x32x16_bf16 v[32:47], v[140:143], v[164:167], v[32:47]
	v_mfma_f32_32x32x16_bf16 v[16:31], v[140:143], v[168:171], v[16:31]
	v_mfma_f32_32x32x16_bf16 v[0:15], v[140:143], v[172:175], v[0:15]
	s_waitcnt vmcnt(0)
	s_barrier
; #define MFMA32(a, b, c) __builtin_amdgcn_mfma_f32_32x32x16_bf16((a), (b), (c), 0, 0, 0)
; DI int crow(int reg, int h) { return (reg & 3) + 8 * (reg >> 2) + 4 * h; }
; template <int lda>
; DI void gemm_mainloop(const bfr* __restrict__ A, const bfr* __restrict__ Bt, int NB, int K, int m0, int n0, char* smem, f32x16 (&acc)[2][4]) {
;     ...
;     const bfr* As = S0 + (kt & 1) * GSTAGE;
;     const bfr* Bs = As + 128 * 40;
; #pragma unroll
;     for (int ks = 0; ks < 2; ++ks) {
;       bf16x8 af[2], bfg[4];
; #pragma unroll
;       for (int i = 0; i < 2; ++i) af[i] = *(const bf16x8*)(As + (wr * 64 + i * 32 + r) * 40 + ks * 16 + hl * 8);
; #pragma unroll
;       for (int j = 0; j < 4; ++j) bfg[j] = *(const bf16x8*)(Bs + (wc * 128 + j * 32 + r) * 40 + ks * 16 + hl * 8);
; #pragma unroll
;       for (int i = 0; i < 2; ++i)
; #pragma unroll
;         for (int j = 0; j < 4; ++j) acc[i][j] = MFMA32(af[i], bfg[j], acc[i][j]);
;     }
; template <bool FIRST, bool HAS_H>
; DI void phase_gemm_resid(const Params& p, const bfr* A, const bfr* Wt, const float* gnext, float* ss, char* smem) {
;     ...
;     int tid2 = threadIdx.x;
;     asm volatile("" : "+v"(tid2));
;     const int lane = tid2 & 63, wid = tid2 >> 6, wr = wid >> 1, wc = wid & 1, r = lane & 31, hl = lane >> 5;
;     const float* xsrc = FIRST ? p.x_prompt : X;
;     const int rbase = m0 + wr * 64 + 4 * hl, cbase = n0 + wc * 128 + r;
; #pragma unroll
;     for (int i = 0; i < 2; ++i) {
; #pragma unroll
;       for (int qh = 0; qh < 2; ++qh) {
;         float rs[8];
; #pragma unroll
;         for (int q = 0; q < 8; ++q) rs[q] = 0.f;
; #pragma unroll
;         for (int jh = 0; jh < 2; ++jh) {
;           float xo[2][8];
; #pragma unroll
;           for (int jj = 0; jj < 2; ++jj)
; #pragma unroll
;             for (int q = 0; q < 8; ++q)
;               xo[jj][q] = xsrc[(rbase + i * 32 + crow(qh * 8 + q, 0)) * 1024 + cbase + (jh * 2 + jj) * 32];
	s_mul_i32 s74, s71, 0x6000
	s_add_u32 s75, s74, 0x2000
	s_cmp_eq_u32 s71, 2
	s_cselect_b32 s75, 0x10000, s75
	v_add_u32_e32 v183, s74, v179
	v_add_u32_e32 v185, s75, v181
	v_add_u32_e32 v184, s74, v180
	v_add_u32_e32 v186, s75, v182
	ds_read_b128 v[128:131], v183
	ds_read_b128 v[144:147], v185
	ds_read_b128 v[148:151], v185 offset:2048
	ds_read_b128 v[152:155], v185 offset:4096
	ds_read_b128 v[156:159], v185 offset:6144
	ds_read_b128 v[132:135], v183 offset:2048
	ds_read_b128 v[136:139], v184
	ds_read_b128 v[160:163], v186
	ds_read_b128 v[164:167], v186 offset:2048
	ds_read_b128 v[168:171], v186 offset:4096
	ds_read_b128 v[172:175], v186 offset:6144
	ds_read_b128 v[140:143], v184 offset:2048
	s_add_u32 s71, s71, 1
	s_cmp_eq_u32 s71, 3
	s_cselect_b32 s71, 0, s71
	s_waitcnt lgkmcnt(10)
	v_mfma_f32_32x32x16_bf16 v[112:127], v[128:131], v[144:147], v[112:127]
	s_waitcnt lgkmcnt(9)
	v_mfma_f32_32x32x16_bf16 v[96:111], v[128:131], v[148:151], v[96:111]
	s_waitcnt lgkmcnt(8)
	v_mfma_f32_32x32x16_bf16 v[80:95], v[128:131], v[152:155], v[80:95]
	s_waitcnt lgkmcnt(7)
	v_mfma_f32_32x32x16_bf16 v[64:79], v[128:131], v[156:159], v[64:79]
	s_waitcnt lgkmcnt(6)
	v_mfma_f32_32x32x16_bf16 v[48:63], v[132:135], v[144:147], v[48:63]
	v_mfma_f32_32x32x16_bf16 v[32:47], v[132:135], v[148:151], v[32:47]
	v_mfma_f32_32x32x16_bf16 v[16:31], v[132:135], v[152:155], v[16:31]
	v_mfma_f32_32x32x16_bf16 v[0:15], v[132:135], v[156:159], v[0:15]
	s_waitcnt lgkmcnt(4)
	v_mfma_f32_32x32x16_bf16 v[112:127], v[136:139], v[160:163], v[112:127]
	s_waitcnt lgkmcnt(3)
	v_mfma_f32_32x32x16_bf16 v[96:111], v[136:139], v[164:167], v[96:111]
	s_waitcnt lgkmcnt(2)
	v_mfma_f32_32x32x16_bf16 v[80:95], v[136:139], v[168:171], v[80:95]
	s_waitcnt lgkmcnt(1)
	v_mfma_f32_32x32x16_bf16 v[64:79], v[136:139], v[172:175], v[64:79]
	s_waitcnt lgkmcnt(0)
	v_mfma_f32_32x32x16_bf16 v[48:63], v[140:143], v[160:163], v[48:63]
	v_mfma_f32_32x32x16_bf16 v[32:47], v[140:143], v[164:167], v[32:47]
	v_mfma_f32_32x32x16_bf16 v[16:31], v[140:143], v[168:171], v[16:31]
	v_mfma_f32_32x32x16_bf16 v[0:15], v[140:143], v[172:175], v[0:15]
	s_nop 7
	v_readlane_b32 s64, v187, 0
	v_readlane_b32 s65, v187, 1
	v_readlane_b32 s66, v187, 2
	v_readlane_b32 s67, v187, 3
	v_readlane_b32 s68, v187, 4
	v_readlane_b32 s69, v187, 5
	v_readlane_b32 s70, v187, 6
	v_readlane_b32 s71, v187, 7
	v_readlane_b32 s72, v187, 8
	v_readlane_b32 s73, v187, 9
	v_readlane_b32 s74, v187, 10
	v_readlane_b32 s75, v187, 11
	v_readlane_b32 s76, v187, 12
	v_readlane_b32 s77, v187, 13
	v_readlane_b32 s78, v187, 14
	v_readlane_b32 s79, v187, 15
	s_nop 7
	s_waitcnt vmcnt(1)
	s_nop 0
	s_nop 0
	s_nop 0
	s_waitcnt vmcnt(0)
	s_nop 0
	v_add_u32_e32 v132, v169, v171
	s_nop 0
	v_add_u32_e32 v133, v169, v170
	s_nop 0
	s_nop 0
	s_nop 0
	s_nop 0
	s_nop 0
	s_nop 0
	s_nop 0
	s_nop 0
	s_nop 0
	s_nop 0
	s_nop 0
	v_mov_b32_e32 v192, v196
	s_waitcnt lgkmcnt(0)
	s_nop 0
	s_nop 0
	s_nop 0
	s_nop 0
	s_nop 0
	s_nop 0
	s_nop 0
	s_nop 0
	s_nop 0
	s_nop 0
	s_nop 0
	s_nop 0
	s_nop 0
	s_nop 0
	s_nop 0
	s_nop 0
	s_nop 0
	s_waitcnt lgkmcnt(0)
	s_nop 0
	s_nop 0
	v_ashrrev_i32_e32 v194, 1, v192
	v_and_b32_e32 v194, 0xffffffc0, v194
	v_add_u32_e32 v194, s36, v194
	v_lshrrev_b32_e32 v195, 3, v192
	v_and_b32_e32 v229, 31, v192
	v_and_or_b32 v228, v195, 4, v194
	v_lshlrev_b32_e32 v192, 1, v192
	s_nop 0
	v_and_b32_e32 v192, 0x80, v192
	v_lshlrev_b32_e32 v204, 10, v228
	v_or3_b32 v202, s33, v192, v229
	v_or_b32_e32 v194, v204, v202
	v_ashrrev_i32_e32 v195, 31, v194
	v_or_b32_e32 v203, 32, v202
	v_or_b32_e32 v230, 0x2c00, v204
	s_nop 0
	v_or_b32_e32 v218, 0x400, v204
	v_or_b32_e32 v216, v218, v202
	v_ashrrev_i32_e32 v217, 31, v216
	v_lshl_add_u64 v[216:217], v[216:217], 2, s[10:11]
	global_load_dword v219, v[216:217], off
	v_or_b32_e32 v216, v218, v203
	v_ashrrev_i32_e32 v217, 31, v216
	s_nop 0
	v_ashrrev_i32_e32 v201, 31, v204
	v_mov_b32_e32 v200, v194
	v_lshl_add_u64 v[198:199], v[194:195], 2, s[10:11]
	v_lshl_add_u64 v[200:201], v[200:201], 2, s[10:11]
	global_load_dword v192, v[198:199], off
	global_load_dword v205, v[200:201], off offset:128
	v_lshl_add_u64 v[216:217], v[216:217], 2, s[10:11]
	s_nop 0
	v_or_b32_e32 v221, 0x800, v204
	global_load_dword v220, v[216:217], off
	v_or_b32_e32 v216, v221, v202
	v_ashrrev_i32_e32 v217, 31, v216
	v_lshl_add_u64 v[216:217], v[216:217], 2, s[10:11]
	global_load_dword v222, v[216:217], off
	v_or_b32_e32 v216, v221, v203
	v_ashrrev_i32_e32 v217, 31, v216
	v_lshl_add_u64 v[216:217], v[216:217], 2, s[10:11]
	global_load_dword v223, v[216:217], off
	s_nop 0
	v_or_b32_e32 v224, 0xc00, v204
	v_or_b32_e32 v225, 0x2000, v204
	v_or_b32_e32 v226, 0x2400, v204
	v_or_b32_e32 v227, 0x2800, v204
	v_or_b32_e32 v216, v224, v202
	v_ashrrev_i32_e32 v217, 31, v216
	v_lshl_add_u64 v[216:217], v[216:217], 2, s[10:11]
	s_nop 0
	v_cmp_eq_u32_e32 vcc, 31, v229
	v_ashrrev_i32_e32 v229, 31, v228
	s_nop 0
	s_nop 0
	s_nop 0
	s_nop 0
	s_nop 0
	s_waitcnt vmcnt(3)
; DI bfr f2bf(float a) { return (bfr)(pack2(a, 0.f) & 0xffffu); }
; DI int crow(int reg, int h) { return (reg & 3) + 8 * (reg >> 2) + 4 * h; }
; template <bool FIRST, bool HAS_H>
; DI void phase_gemm_resid(const Params& p, const bfr* A, const bfr* Wt, const float* gnext, float* ss, char* smem) {
;     ...
; #pragma unroll
;     for (int i = 0; i < 2; ++i) {
; #pragma unroll
;       for (int qh = 0; qh < 2; ++qh) {
;         float rs[8];
; #pragma unroll
;         for (int q = 0; q < 8; ++q) rs[q] = 0.f;
; #pragma unroll
;         for (int jh = 0; jh < 2; ++jh) {
;           float xo[2][8];
; #pragma unroll
;           for (int jj = 0; jj < 2; ++jj)
; #pragma unroll
;             for (int q = 0; q < 8; ++q)
;               xo[jj][q] = xsrc[(rbase + i * 32 + crow(qh * 8 + q, 0)) * 1024 + cbase + (jh * 2 + jj) * 32];
; #pragma unroll
;           for (int q = 0; q < 8; ++q) {
;             const int o = (rbase + i * 32 + crow(qh * 8 + q, 0)) * 1024 + cbase;
; #pragma unroll
;             for (int jj = 0; jj < 2; ++jj) {
;               const int j = jh * 2 + jj;
;               const float xn = xo[jj][q] + acc[i][j][qh * 8 + q];
;               X[o + j * 32] = xn;
;               if (HAS_H) Hn[o + j * 32] = f2bf(xn * gnext[cbase + j * 32]);
;               rs[q] += xn * xn;
;             }
;           }
;         }
	s_nop 9
	v_add_f32_e32 v205, v96, v205
	s_nop 0
	v_or_b32_e32 v206, v225, v202
	v_or_b32_e32 v208, v226, v202
	v_ashrrev_i32_e32 v207, 31, v206
	v_ashrrev_i32_e32 v209, 31, v208
	v_lshl_add_u64 v[206:207], v[206:207], 2, s[10:11]
	v_lshl_add_u64 v[208:209], v[208:209], 2, s[10:11]
	v_or_b32_e32 v96, 0x420, v194
	s_nop 0
	v_or_b32_e32 v210, v227, v202
	v_ashrrev_i32_e32 v211, 31, v210
	v_or_b32_e32 v212, v230, v202
	v_lshl_add_u64 v[210:211], v[210:211], 2, s[10:11]
	v_ashrrev_i32_e32 v213, 31, v212
	v_lshl_add_u64 v[212:213], v[212:213], 2, s[10:11]
	global_load_dword v231, v[216:217], off
	global_load_dword v232, v[206:207], off
	global_load_dword v233, v[208:209], off
	global_load_dword v234, v[210:211], off
	global_load_dword v235, v[212:213], off
	v_or_b32_e32 v206, v224, v203
	v_or_b32_e32 v208, v225, v203
	v_or_b32_e32 v210, v226, v203
	v_ashrrev_i32_e32 v207, 31, v206
	v_ashrrev_i32_e32 v209, 31, v208
	v_ashrrev_i32_e32 v211, 31, v210
	v_or_b32_e32 v212, v227, v203
	v_or_b32_e32 v216, v230, v203
	v_lshl_add_u64 v[206:207], v[206:207], 2, s[10:11]
	v_lshl_add_u64 v[208:209], v[208:209], 2, s[10:11]
	v_lshl_add_u64 v[210:211], v[210:211], 2, s[10:11]
	v_ashrrev_i32_e32 v213, 31, v212
	v_ashrrev_i32_e32 v217, 31, v216
	v_lshl_add_u64 v[212:213], v[212:213], 2, s[10:11]
	v_lshl_add_u64 v[216:217], v[216:217], 2, s[10:11]
	global_load_dword v206, v[206:207], off
	s_nop 0
	global_load_dword v207, v[208:209], off
	s_nop 0
	global_load_dword v208, v[210:211], off
	global_load_dword v209, v[212:213], off
	s_nop 0
	global_load_dword v210, v[216:217], off
	v_add_f32_e32 v211, v112, v192
	v_or_b32_e32 v112, 0x400, v194
	global_store_dword v[198:199], v211, off
	v_lshlrev_b32_e32 v192, 2, v202
	s_nop 0
	v_add_f32_e32 v189, v113, v219
	v_ashrrev_i32_e32 v113, 31, v112
	global_load_dword v212, v192, s[12:13]
	v_lshl_add_u64 v[112:113], v[112:113], 2, s[10:11]
	global_store_dword v[198:199], v205, off offset:128
	global_load_dword v188, v192, s[12:13] offset:128
	s_waitcnt vmcnt(14)
	v_add_f32_e32 v98, v98, v223
	s_nop 0
	v_add_f32_e32 v185, v97, v220
	v_ashrrev_i32_e32 v97, 31, v96
	global_store_dword v[112:113], v189, off
	v_lshl_add_u64 v[96:97], v[96:97], 2, s[10:11]
	global_load_dword v184, v192, s[12:13]
	s_waitcnt vmcnt(15)
	v_add_f32_e32 v115, v115, v231
	s_nop 0
	v_or_b32_e32 v172, 0x800, v194
	v_ashrrev_i32_e32 v173, 31, v172
	global_store_dword v[96:97], v185, off
	v_add_f32_e32 v176, v114, v222
	v_lshl_add_u64 v[96:97], v[172:173], 2, s[10:11]
	v_or_b32_e32 v174, 0x820, v194
	global_load_dword v186, v192, s[12:13] offset:128
	v_ashrrev_i32_e32 v175, 31, v174
	global_store_dword v[96:97], v176, off
	global_load_dword v177, v192, s[12:13]
	v_lshl_add_u64 v[96:97], v[174:175], 2, s[10:11]
	global_store_dword v[96:97], v98, off
	global_load_dword v178, v192, s[12:13] offset:128
	s_nop 0
	v_lshl_add_u64 v[162:163], v[172:173], 1, s[6:7]
	v_lshl_add_u64 v[96:97], v[228:229], 2, s[14:15]
	s_waitcnt vmcnt(10)
	v_mul_f32_e32 v112, v211, v212
	s_nop 0
	v_cvt_pk_bf16_f32 v114, v112, s0
	v_lshl_add_u64 v[112:113], v[194:195], 1, s[6:7]
	global_store_short v[112:113], v114, off
	s_waitcnt vmcnt(9)
	v_mul_f32_e32 v114, v205, v188
	v_cvt_pk_bf16_f32 v114, v114, s0
	global_store_short v[112:113], v114, off offset:64
	v_mul_f32_e32 v114, v205, v205
	s_nop 0
	s_waitcnt vmcnt(8)
	v_mul_f32_e32 v160, v189, v184
	v_cvt_pk_bf16_f32 v160, v160, s0
	global_store_short v[112:113], v160, off offset:2048
	v_fmac_f32_e32 v114, v211, v211
	s_waitcnt vmcnt(7)
	v_mul_f32_e32 v160, v185, v186
	s_nop 0
	v_or_b32_e32 v152, 0xc00, v194
	v_ashrrev_i32_e32 v153, 31, v152
	v_lshl_add_u64 v[154:155], v[152:153], 2, s[10:11]
	global_store_dword v[154:155], v115, off
	s_waitcnt vmcnt(6)
	v_mul_f32_e32 v161, v176, v177
	v_cvt_pk_bf16_f32 v161, v161, s0
	global_store_short v[162:163], v161, off
	s_nop 0
	s_waitcnt vmcnt(5)
	v_mul_f32_e32 v161, v98, v178
	v_or_b32_e32 v154, 0xc20, v194
	v_cvt_pk_bf16_f32 v161, v161, s0
	v_lshl_add_u64 v[162:163], v[174:175], 1, s[6:7]
	v_ashrrev_i32_e32 v155, 31, v154
	global_store_short v[162:163], v161, off
	v_mul_f32_e32 v161, v98, v98
	s_nop 0
	global_load_dword v158, v192, s[12:13]
	v_add_f32_e32 v159, v99, v206
	v_lshl_add_u64 v[98:99], v[154:155], 2, s[10:11]
	global_store_dword v[98:99], v159, off
	global_load_dword v162, v192, s[12:13] offset:128
	v_or_b32_e32 v156, 0x2000, v194
	v_ashrrev_i32_e32 v157, 31, v156
	s_nop 0
	v_add_f32_e32 v163, v116, v232
	v_lshl_add_u64 v[98:99], v[156:157], 2, s[10:11]
	global_store_dword v[98:99], v163, off
	v_or_b32_e32 v116, 0x2400, v194
	v_add_f32_e32 v165, v117, v233
	v_ashrrev_i32_e32 v117, 31, v116
	v_add_f32_e32 v167, v102, v209
	s_nop 0
	v_or_b32_e32 v148, 0x2020, v194
	v_ashrrev_i32_e32 v149, 31, v148
	global_load_dword v150, v192, s[12:13]
	v_add_f32_e32 v151, v100, v207
	v_lshl_add_u64 v[98:99], v[148:149], 2, s[10:11]
	global_store_dword v[98:99], v151, off
	global_load_dword v164, v192, s[12:13] offset:128
	s_nop 0
	v_lshl_add_u64 v[98:99], v[116:117], 2, s[10:11]
	v_or_b32_e32 v140, 0x2420, v194
	global_store_dword v[98:99], v165, off
	v_ashrrev_i32_e32 v141, 31, v140
	v_lshl_add_u64 v[98:99], v[140:141], 2, s[10:11]
	v_add_f32_e32 v169, v119, v235
	v_add_f32_e32 v171, v103, v210
	s_nop 0
	global_load_dword v144, v192, s[12:13]
	v_add_f32_e32 v145, v101, v208
	global_store_dword v[98:99], v145, off
	global_load_dword v146, v192, s[12:13] offset:128
	v_add_f32_e32 v147, v118, v234
	v_cvt_pk_bf16_f32 v160, v160, s0
	global_store_short v[112:113], v160, off offset:2112
	s_nop 0
	v_or_b32_e32 v136, 0x2800, v194
	v_ashrrev_i32_e32 v137, 31, v136
	v_lshl_add_u64 v[98:99], v[136:137], 2, s[10:11]
; DI bfr f2bf(float a) { return (bfr)(pack2(a, 0.f) & 0xffffu); }
; DI int crow(int reg, int h) { return (reg & 3) + 8 * (reg >> 2) + 4 * h; }
; template <bool FIRST, bool HAS_H>
; DI void phase_gemm_resid(const Params& p, const bfr* A, const bfr* Wt, const float* gnext, float* ss, char* smem) {
;     ...
; #pragma unroll
;     for (int i = 0; i < 2; ++i) {
; #pragma unroll
;       for (int qh = 0; qh < 2; ++qh) {
;         float rs[8];
; #pragma unroll
;         for (int q = 0; q < 8; ++q) rs[q] = 0.f;
; #pragma unroll
;         for (int jh = 0; jh < 2; ++jh) {
;           float xo[2][8];
; #pragma unroll
;           for (int jj = 0; jj < 2; ++jj)
; #pragma unroll
;             for (int q = 0; q < 8; ++q)
;               xo[jj][q] = xsrc[(rbase + i * 32 + crow(qh * 8 + q, 0)) * 1024 + cbase + (jh * 2 + jj) * 32];
; #pragma unroll
;           for (int q = 0; q < 8; ++q) {
;             const int o = (rbase + i * 32 + crow(qh * 8 + q, 0)) * 1024 + cbase;
; #pragma unroll
;             for (int jj = 0; jj < 2; ++jj) {
;               const int j = jh * 2 + jj;
;               const float xn = xo[jj][q] + acc[i][j][qh * 8 + q];
;               X[o + j * 32] = xn;
;               if (HAS_H) Hn[o + j * 32] = f2bf(xn * gnext[cbase + j * 32]);
;               rs[q] += xn * xn;
;             }
;           }
;         }
	global_store_dword v[98:99], v147, off
	global_load_dword v166, v192, s[12:13]
	v_lshl_add_u64 v[116:117], v[116:117], 1, s[6:7]
	v_mul_f32_e32 v160, v185, v185
	s_nop 0
	v_or_b32_e32 v128, 0x2820, v194
	v_ashrrev_i32_e32 v129, 31, v128
	v_lshl_add_u64 v[98:99], v[128:129], 2, s[10:11]
	global_store_dword v[98:99], v167, off
	global_load_dword v168, v192, s[12:13] offset:128
	v_or_b32_e32 v98, 0x2c00, v194
	v_ashrrev_i32_e32 v99, 31, v98
	v_lshl_add_u64 v[100:101], v[98:99], 2, s[10:11]
	global_store_dword v[100:101], v169, off
	global_load_dword v170, v192, s[12:13]
	v_or_b32_e32 v100, 0x2c20, v194
	v_ashrrev_i32_e32 v101, 31, v100
	v_lshl_add_u64 v[102:103], v[100:101], 2, s[10:11]
	global_store_dword v[102:103], v171, off
	v_or_b32_e32 v102, 64, v202
	v_or_b32_e32 v118, v218, v102
	v_or_b32_e32 v130, v221, v102
	v_or_b32_e32 v132, v224, v102
	v_or_b32_e32 v134, v225, v102
	v_ashrrev_i32_e32 v119, 31, v118
	v_ashrrev_i32_e32 v131, 31, v130
	v_ashrrev_i32_e32 v133, 31, v132
	v_ashrrev_i32_e32 v135, 31, v134
	v_or_b32_e32 v138, v226, v102
	v_or_b32_e32 v142, v227, v102
	v_lshl_add_u64 v[118:119], v[118:119], 2, s[10:11]
	v_lshl_add_u64 v[130:131], v[130:131], 2, s[10:11]
	v_lshl_add_u64 v[132:133], v[132:133], 2, s[10:11]
	v_lshl_add_u64 v[134:135], v[134:135], 2, s[10:11]
	v_ashrrev_i32_e32 v139, 31, v138
	v_ashrrev_i32_e32 v143, 31, v142
	v_lshl_add_u64 v[138:139], v[138:139], 2, s[10:11]
	s_waitcnt vmcnt(18)
	v_mul_f32_e32 v103, v115, v158
	v_lshl_add_u64 v[142:143], v[142:143], 2, s[10:11]
	global_load_dword v172, v[200:201], off offset:256
	global_load_dword v173, v[118:119], off
	s_nop 0
	global_load_dword v130, v[130:131], off
	s_nop 0
	global_load_dword v131, v[132:133], off
	s_nop 0
	global_load_dword v132, v[134:135], off
	global_load_dword v133, v[138:139], off
	s_nop 0
	global_load_dword v134, v[142:143], off
	global_load_dword v135, v[200:201], off offset:384
	v_cvt_pk_bf16_f32 v103, v103, s0
	v_lshl_add_u64 v[118:119], v[152:153], 1, s[6:7]
	global_store_short v[118:119], v103, off
	v_or_b32_e32 v103, 0x60, v202
	v_or_b32_e32 v118, v218, v103
	v_ashrrev_i32_e32 v119, 31, v118
	v_lshl_add_u64 v[118:119], v[118:119], 2, s[10:11]
	global_load_dword v138, v[118:119], off
	s_waitcnt vmcnt(26)
	v_mul_f32_e32 v118, v159, v162
	v_cvt_pk_bf16_f32 v139, v118, s0
	v_lshl_add_u64 v[118:119], v[154:155], 1, s[6:7]
	global_store_short v[118:119], v139, off
	v_or_b32_e32 v118, v221, v103
	v_mul_f32_e32 v139, v159, v159
	v_ashrrev_i32_e32 v119, 31, v118
	v_fmac_f32_e32 v139, v115, v115
	s_waitcnt vmcnt(25)
	v_mul_f32_e32 v115, v163, v150
	v_lshl_add_u64 v[118:119], v[118:119], 2, s[10:11]
	v_cvt_pk_bf16_f32 v115, v115, s0
	global_load_dword v142, v[118:119], off
	v_lshl_add_u64 v[118:119], v[156:157], 1, s[6:7]
	global_store_short v[118:119], v115, off
	s_waitcnt vmcnt(25)
	v_mul_f32_e32 v115, v151, v164
	v_cvt_pk_bf16_f32 v115, v115, s0
	v_lshl_add_u64 v[118:119], v[148:149], 1, s[6:7]
	global_store_short v[118:119], v115, off
	v_or_b32_e32 v118, v224, v103
	v_ashrrev_i32_e32 v119, 31, v118
	v_lshl_add_u64 v[118:119], v[118:119], 2, s[10:11]
	global_load_dword v143, v[118:119], off
	s_waitcnt vmcnt(25)
	v_mul_f32_e32 v118, v165, v144
	v_cvt_pk_bf16_f32 v118, v118, s0
	global_store_short v[116:117], v118, off
	s_waitcnt vmcnt(24)
	v_mul_f32_e32 v116, v145, v146
	v_cvt_pk_bf16_f32 v118, v116, s0
	v_lshl_add_u64 v[116:117], v[140:141], 1, s[6:7]
	global_store_short v[116:117], v118, off
	v_or_b32_e32 v116, v225, v103
	v_ashrrev_i32_e32 v117, 31, v116
	v_lshl_add_u64 v[116:117], v[116:117], 2, s[10:11]
	global_load_dword v140, v[116:117], off
	s_waitcnt vmcnt(23)
	v_mul_f32_e32 v116, v147, v166
	v_cvt_pk_bf16_f32 v118, v116, s0
	v_lshl_add_u64 v[116:117], v[136:137], 1, s[6:7]
	global_store_short v[116:117], v118, off
	v_mul_f32_e32 v137, v167, v167
	v_mul_f32_e32 v141, v145, v145
	v_fmac_f32_e32 v137, v147, v147
	global_load_dword v145, v192, s[12:13] offset:128
	s_waitcnt vmcnt(23)
	v_mul_f32_e32 v116, v167, v168
	v_cvt_pk_bf16_f32 v118, v116, s0
	v_or_b32_e32 v116, v226, v103
	v_ashrrev_i32_e32 v117, 31, v116
	v_lshl_add_u64 v[116:117], v[116:117], 2, s[10:11]
	global_load_dword v136, v[116:117], off
	v_lshl_add_u64 v[116:117], v[128:129], 1, s[6:7]
	global_store_short v[116:117], v118, off
	v_or_b32_e32 v118, v227, v103
	s_waitcnt vmcnt(23)
	v_mul_f32_e32 v116, v169, v170
	v_ashrrev_i32_e32 v119, 31, v118
	v_cvt_pk_bf16_f32 v144, v116, s0
	v_or_b32_e32 v116, v230, v102
	v_lshl_add_u64 v[118:119], v[118:119], 2, s[10:11]
	global_load_dword v146, v[118:119], off
	v_ashrrev_i32_e32 v117, 31, v116
	v_or_b32_e32 v118, v230, v103
	v_lshl_add_u64 v[116:117], v[116:117], 2, s[10:11]
	v_ashrrev_i32_e32 v119, 31, v118
	v_lshl_add_u64 v[118:119], v[118:119], 2, s[10:11]
	global_load_dword v147, v[116:117], off
	global_load_dword v148, v[118:119], off
	v_mul_f32_e32 v115, v151, v151
	v_fmac_f32_e32 v115, v163, v163
	s_waitcnt vmcnt(24)
	v_add_f32_e32 v149, v80, v172
	global_store_dword v[198:199], v149, off offset:256
	v_or_b32_e32 v80, 0x440, v194
	global_load_dword v150, v192, s[12:13] offset:256
	s_waitcnt vmcnt(25)
	v_add_f32_e32 v152, v81, v173
	v_ashrrev_i32_e32 v81, 31, v80
	v_lshl_add_u64 v[80:81], v[80:81], 2, s[10:11]
	s_waitcnt vmcnt(19)
	v_add_f32_e32 v135, v64, v135
	v_or_b32_e32 v64, 0x460, v194
	global_store_dword v[198:199], v135, off offset:384
	global_load_dword v151, v192, s[12:13] offset:384
	v_add_f32_e32 v155, v82, v130
	global_store_dword v[80:81], v152, off
	global_load_dword v153, v192, s[12:13] offset:256
	v_or_b32_e32 v82, 0xc40, v194
	s_waitcnt vmcnt(21)
; DI bfr f2bf(float a) { return (bfr)(pack2(a, 0.f) & 0xffffu); }
; DI int crow(int reg, int h) { return (reg & 3) + 8 * (reg >> 2) + 4 * h; }
; template <bool FIRST, bool HAS_H>
; DI void phase_gemm_resid(const Params& p, const bfr* A, const bfr* Wt, const float* gnext, float* ss, char* smem) {
;     ...
;         for (int jh = 0; jh < 2; ++jh) {
;           float xo[2][8];
; #pragma unroll
;           for (int jj = 0; jj < 2; ++jj)
; #pragma unroll
;             for (int q = 0; q < 8; ++q)
;               xo[jj][q] = xsrc[(rbase + i * 32 + crow(qh * 8 + q, 0)) * 1024 + cbase + (jh * 2 + jj) * 32];
; #pragma unroll
;           for (int q = 0; q < 8; ++q) {
;             const int o = (rbase + i * 32 + crow(qh * 8 + q, 0)) * 1024 + cbase;
; #pragma unroll
;             for (int jj = 0; jj < 2; ++jj) {
;               const int j = jh * 2 + jj;
;               const float xn = xo[jj][q] + acc[i][j][qh * 8 + q];
;               X[o + j * 32] = xn;
;               if (HAS_H) Hn[o + j * 32] = f2bf(xn * gnext[cbase + j * 32]);
;               rs[q] += xn * xn;
;             }
;           }
;         }
	v_add_f32_e32 v138, v65, v138
	v_ashrrev_i32_e32 v65, 31, v64
	v_lshl_add_u64 v[64:65], v[64:65], 2, s[10:11]
	global_store_dword v[64:65], v138, off
	v_or_b32_e32 v64, 0x840, v194
	v_ashrrev_i32_e32 v65, 31, v64
	v_lshl_add_u64 v[80:81], v[64:65], 2, s[10:11]
	global_load_dword v154, v192, s[12:13] offset:384
	v_add_f32_e32 v158, v83, v131
	global_store_dword v[80:81], v155, off
	v_or_b32_e32 v80, 0x860, v194
	v_ashrrev_i32_e32 v81, 31, v80
	global_load_dword v156, v192, s[12:13] offset:256
	s_waitcnt vmcnt(23)
	v_add_f32_e32 v142, v66, v142
	v_lshl_add_u64 v[116:117], v[80:81], 2, s[10:11]
	v_ashrrev_i32_e32 v83, 31, v82
	v_or_b32_e32 v66, 0xc60, v194
	global_store_dword v[116:117], v142, off
	v_lshl_add_u64 v[116:117], v[82:83], 2, s[10:11]
	global_load_dword v157, v192, s[12:13] offset:384
	v_add_f32_e32 v163, v84, v132
	global_store_dword v[116:117], v158, off
	s_waitcnt vmcnt(23)
	v_add_f32_e32 v143, v67, v143
	v_ashrrev_i32_e32 v67, 31, v66
	v_lshl_add_u64 v[116:117], v[66:67], 2, s[10:11]
	global_load_dword v159, v192, s[12:13] offset:256
	v_or_b32_e32 v84, 0x2440, v194
	global_store_dword v[116:117], v143, off
	v_or_b32_e32 v116, 0x2040, v194
	v_ashrrev_i32_e32 v117, 31, v116
	v_lshl_add_u64 v[118:119], v[116:117], 2, s[10:11]
	global_load_dword v162, v192, s[12:13] offset:384
	v_add_f32_e32 v166, v85, v133
	global_store_dword v[118:119], v163, off
	v_or_b32_e32 v118, 0x2060, v194
	v_ashrrev_i32_e32 v119, 31, v118
	global_load_dword v164, v192, s[12:13] offset:256
	s_waitcnt vmcnt(25)
	v_add_f32_e32 v140, v68, v140
	v_lshl_add_u64 v[128:129], v[118:119], 2, s[10:11]
	v_ashrrev_i32_e32 v85, 31, v84
	v_or_b32_e32 v68, 0x2460, v194
	global_store_dword v[128:129], v140, off
	v_lshl_add_u64 v[128:129], v[84:85], 2, s[10:11]
	v_fmac_f32_e32 v141, v165, v165
	global_load_dword v165, v192, s[12:13] offset:384
	v_add_f32_e32 v134, v86, v134
	global_store_dword v[128:129], v166, off
	s_waitcnt vmcnt(25)
	v_add_f32_e32 v136, v69, v136
	v_ashrrev_i32_e32 v69, 31, v68
	v_lshl_add_u64 v[128:129], v[68:69], 2, s[10:11]
	global_load_dword v167, v192, s[12:13] offset:256
	v_or_b32_e32 v86, 0x2c40, v194
	global_store_dword v[128:129], v136, off
	v_or_b32_e32 v128, 0x2840, v194
	v_ashrrev_i32_e32 v129, 31, v128
	v_lshl_add_u64 v[130:131], v[128:129], 2, s[10:11]
	global_load_dword v168, v192, s[12:13] offset:384
	s_waitcnt vmcnt(26)
	v_add_f32_e32 v146, v70, v146
	global_store_dword v[130:131], v134, off
	v_or_b32_e32 v130, 0x2860, v194
	v_ashrrev_i32_e32 v131, 31, v130
	global_load_dword v170, v192, s[12:13] offset:256
	v_lshl_add_u64 v[132:133], v[130:131], 2, s[10:11]
	global_store_dword v[132:133], v146, off
	s_waitcnt vmcnt(28)
	v_add_f32_e32 v147, v87, v147
	v_ashrrev_i32_e32 v87, 31, v86
	global_load_dword v172, v192, s[12:13] offset:384
	v_lshl_add_u64 v[132:133], v[86:87], 2, s[10:11]
	v_or_b32_e32 v70, 0x2c60, v194
	global_store_dword v[132:133], v147, off
	s_waitcnt vmcnt(29)
	v_add_f32_e32 v148, v71, v148
	v_ashrrev_i32_e32 v71, 31, v70
	global_load_dword v173, v192, s[12:13] offset:256
	v_lshl_add_u64 v[132:133], v[70:71], 2, s[10:11]
	global_store_dword v[132:133], v148, off
	global_load_dword v132, v192, s[12:13] offset:384
	v_lshl_add_u64 v[98:99], v[98:99], 1, s[6:7]
	global_store_short v[98:99], v144, off
	v_mul_f32_e32 v98, v171, v145
	v_cvt_pk_bf16_f32 v133, v98, s0
	v_lshl_add_u64 v[98:99], v[100:101], 1, s[6:7]
	global_store_short v[98:99], v133, off
	s_waitcnt vmcnt(32)
	v_mul_f32_e32 v99, v149, v150
	v_cvt_pk_bf16_f32 v99, v99, s0
	global_store_short v[112:113], v99, off offset:128
	s_waitcnt vmcnt(31)
	v_mul_f32_e32 v99, v135, v151
	v_cvt_pk_bf16_f32 v99, v99, s0
	global_store_short v[112:113], v99, off offset:192
	s_waitcnt vmcnt(30)
	v_mul_f32_e32 v99, v152, v153
	v_cvt_pk_bf16_f32 v99, v99, s0
	global_store_short v[112:113], v99, off offset:2176
	s_waitcnt vmcnt(29)
	v_mul_f32_e32 v99, v138, v154
	v_cvt_pk_bf16_f32 v99, v99, s0
	global_store_short v[112:113], v99, off offset:2240
	s_waitcnt vmcnt(28)
	v_mul_f32_e32 v99, v155, v156
	v_cvt_pk_bf16_f32 v99, v99, s0
	v_lshl_add_u64 v[64:65], v[64:65], 1, s[6:7]
	global_store_short v[64:65], v99, off
	v_mul_f32_e32 v98, v171, v171
	s_waitcnt vmcnt(27)
	v_mul_f32_e32 v64, v142, v157
	v_cvt_pk_bf16_f32 v99, v64, s0
	v_lshl_add_u64 v[64:65], v[80:81], 1, s[6:7]
	global_store_short v[64:65], v99, off
	v_fmac_f32_e32 v160, v189, v189
	v_fmac_f32_e32 v161, v176, v176
	s_waitcnt vmcnt(26)
	v_mul_f32_e32 v64, v158, v159
	v_cvt_pk_bf16_f32 v80, v64, s0
	v_lshl_add_u64 v[64:65], v[82:83], 1, s[6:7]
	global_store_short v[64:65], v80, off
	v_fmac_f32_e32 v98, v169, v169
	v_fmac_f32_e32 v114, v149, v149
	s_waitcnt vmcnt(25)
	v_mul_f32_e32 v64, v143, v162
	v_cvt_pk_bf16_f32 v80, v64, s0
	v_lshl_add_u64 v[64:65], v[66:67], 1, s[6:7]
	global_store_short v[64:65], v80, off
	v_fmac_f32_e32 v160, v152, v152
	s_waitcnt vmcnt(24)
	v_mul_f32_e32 v64, v163, v164
	v_cvt_pk_bf16_f32 v66, v64, s0
	v_lshl_add_u64 v[64:65], v[116:117], 1, s[6:7]
	global_store_short v[64:65], v66, off
	v_fmac_f32_e32 v161, v155, v155
	v_fmac_f32_e32 v139, v158, v158
	v_fmac_f32_e32 v115, v163, v163
	v_fmac_f32_e32 v141, v166, v166
	s_waitcnt vmcnt(23)
	v_mul_f32_e32 v64, v140, v165
	v_cvt_pk_bf16_f32 v66, v64, s0
	v_lshl_add_u64 v[64:65], v[118:119], 1, s[6:7]
	global_store_short v[64:65], v66, off
	v_fmac_f32_e32 v137, v134, v134
	v_fmac_f32_e32 v98, v147, v147
	s_waitcnt vmcnt(22)
; DI bfr f2bf(float a) { return (bfr)(pack2(a, 0.f) & 0xffffu); }
; #define DPPF(v, ctrl, rmask) __builtin_bit_cast(float, __builtin_amdgcn_update_dpp(0, __builtin_bit_cast(int, (v)), (ctrl), (rmask), 0xf, false))
; DI int crow(int reg, int h) { return (reg & 3) + 8 * (reg >> 2) + 4 * h; }
; DI float row16_sum(float v) {
;   v += DPPF(v, 0xB1, 0xf);
;   v += DPPF(v, 0x4E, 0xf);
;   v += DPPF(v, 0x141, 0xf);
;   v += DPPF(v, 0x140, 0xf);
;   return v;
; }
; DI float half32_sum_hi(float v) {
;   v = row16_sum(v);
;   v += DPPF(v, 0x142, 0xa);
;   return v;
; template <bool FIRST, bool HAS_H>
; DI void phase_gemm_resid(const Params& p, const bfr* A, const bfr* Wt, const float* gnext, float* ss, char* smem) {
;     ...
;           for (int q = 0; q < 8; ++q) {
;             const int o = (rbase + i * 32 + crow(qh * 8 + q, 0)) * 1024 + cbase;
; #pragma unroll
;             for (int jj = 0; jj < 2; ++jj) {
;               const int j = jh * 2 + jj;
;               const float xn = xo[jj][q] + acc[i][j][qh * 8 + q];
;               X[o + j * 32] = xn;
;               if (HAS_H) Hn[o + j * 32] = f2bf(xn * gnext[cbase + j * 32]);
;               rs[q] += xn * xn;
;             }
;           }
;         }
; #pragma unroll
;         for (int q = 0; q < 8; ++q) rs[q] = half32_sum_hi(rs[q]);
;         if (r == 31) {
; #pragma unroll
;           for (int q = 0; q < 8; ++q) unsafeAtomicAdd(ss + rbase + i * 32 + crow(qh * 8 + q, 0), rs[q]);
;         }
	v_mul_f32_e32 v64, v166, v167
	v_cvt_pk_bf16_f32 v66, v64, s0
	v_lshl_add_u64 v[64:65], v[84:85], 1, s[6:7]
	global_store_short v[64:65], v66, off
	v_fmac_f32_e32 v114, v135, v135
	v_fmac_f32_e32 v160, v138, v138
	s_waitcnt vmcnt(21)
	v_mul_f32_e32 v64, v136, v168
	v_cvt_pk_bf16_f32 v66, v64, s0
	v_lshl_add_u64 v[64:65], v[68:69], 1, s[6:7]
	global_store_short v[64:65], v66, off
	v_fmac_f32_e32 v161, v142, v142
	s_waitcnt vmcnt(20)
	v_mul_f32_e32 v64, v134, v170
	v_cvt_pk_bf16_f32 v66, v64, s0
	v_lshl_add_u64 v[64:65], v[128:129], 1, s[6:7]
	global_store_short v[64:65], v66, off
	v_fmac_f32_e32 v139, v143, v143
	s_waitcnt vmcnt(19)
	v_mul_f32_e32 v64, v146, v172
	v_cvt_pk_bf16_f32 v66, v64, s0
	v_lshl_add_u64 v[64:65], v[130:131], 1, s[6:7]
	global_store_short v[64:65], v66, off
	v_fmac_f32_e32 v115, v140, v140
	v_fmac_f32_e32 v141, v136, v136
	s_waitcnt vmcnt(18)
	v_mul_f32_e32 v64, v147, v173
	v_cvt_pk_bf16_f32 v66, v64, s0
	v_lshl_add_u64 v[64:65], v[86:87], 1, s[6:7]
	global_store_short v[64:65], v66, off
	s_waitcnt vmcnt(17)
	v_mul_f32_e32 v64, v148, v132
	v_fmac_f32_e32 v137, v146, v146
	v_cvt_pk_bf16_f32 v66, v64, s0
	v_lshl_add_u64 v[64:65], v[70:71], 1, s[6:7]
	v_fmac_f32_e32 v98, v148, v148
	global_store_short v[64:65], v66, off
	v_add_f32_dpp v64, v114, v114 quad_perm:[1,0,3,2] row_mask:0xf bank_mask:0xf bound_ctrl:1
	v_add_f32_dpp v66, v160, v160 quad_perm:[1,0,3,2] row_mask:0xf bank_mask:0xf bound_ctrl:1
	v_add_f32_dpp v68, v161, v161 quad_perm:[1,0,3,2] row_mask:0xf bank_mask:0xf bound_ctrl:1
	v_add_f32_dpp v70, v139, v139 quad_perm:[1,0,3,2] row_mask:0xf bank_mask:0xf bound_ctrl:1
	v_add_f32_dpp v80, v115, v115 quad_perm:[1,0,3,2] row_mask:0xf bank_mask:0xf bound_ctrl:1
	v_add_f32_dpp v82, v141, v141 quad_perm:[1,0,3,2] row_mask:0xf bank_mask:0xf bound_ctrl:1
	v_add_f32_dpp v84, v137, v137 quad_perm:[1,0,3,2] row_mask:0xf bank_mask:0xf bound_ctrl:1
	v_add_f32_dpp v86, v98, v98 quad_perm:[1,0,3,2] row_mask:0xf bank_mask:0xf bound_ctrl:1
	v_add_f32_dpp v64, v64, v64 quad_perm:[2,3,0,1] row_mask:0xf bank_mask:0xf bound_ctrl:1
	v_add_f32_dpp v66, v66, v66 quad_perm:[2,3,0,1] row_mask:0xf bank_mask:0xf bound_ctrl:1
	v_add_f32_dpp v68, v68, v68 quad_perm:[2,3,0,1] row_mask:0xf bank_mask:0xf bound_ctrl:1
	v_add_f32_dpp v70, v70, v70 quad_perm:[2,3,0,1] row_mask:0xf bank_mask:0xf bound_ctrl:1
	v_add_f32_dpp v80, v80, v80 quad_perm:[2,3,0,1] row_mask:0xf bank_mask:0xf bound_ctrl:1
	v_add_f32_dpp v82, v82, v82 quad_perm:[2,3,0,1] row_mask:0xf bank_mask:0xf bound_ctrl:1
	v_add_f32_dpp v84, v84, v84 quad_perm:[2,3,0,1] row_mask:0xf bank_mask:0xf bound_ctrl:1
	v_add_f32_dpp v86, v86, v86 quad_perm:[2,3,0,1] row_mask:0xf bank_mask:0xf bound_ctrl:1
	v_add_f32_dpp v64, v64, v64 row_half_mirror row_mask:0xf bank_mask:0xf bound_ctrl:1
	v_add_f32_dpp v66, v66, v66 row_half_mirror row_mask:0xf bank_mask:0xf bound_ctrl:1
	v_add_f32_dpp v68, v68, v68 row_half_mirror row_mask:0xf bank_mask:0xf bound_ctrl:1
	v_add_f32_dpp v70, v70, v70 row_half_mirror row_mask:0xf bank_mask:0xf bound_ctrl:1
	v_add_f32_dpp v80, v80, v80 row_half_mirror row_mask:0xf bank_mask:0xf bound_ctrl:1
	v_add_f32_dpp v82, v82, v82 row_half_mirror row_mask:0xf bank_mask:0xf bound_ctrl:1
	v_add_f32_dpp v84, v84, v84 row_half_mirror row_mask:0xf bank_mask:0xf bound_ctrl:1
	v_add_f32_dpp v86, v86, v86 row_half_mirror row_mask:0xf bank_mask:0xf bound_ctrl:1
	v_add_f32_dpp v64, v64, v64 row_mirror row_mask:0xf bank_mask:0xf bound_ctrl:1
	v_mov_b32_e32 v65, 0
	v_add_f32_dpp v66, v66, v66 row_mirror row_mask:0xf bank_mask:0xf bound_ctrl:1
	v_mov_b32_e32 v67, 0
	v_add_f32_dpp v68, v68, v68 row_mirror row_mask:0xf bank_mask:0xf bound_ctrl:1
	v_mov_b32_e32 v69, 0
	v_add_f32_dpp v70, v70, v70 row_mirror row_mask:0xf bank_mask:0xf bound_ctrl:1
	v_mov_b32_e32 v71, 0
	v_add_f32_dpp v80, v80, v80 row_mirror row_mask:0xf bank_mask:0xf bound_ctrl:1
	v_mov_b32_e32 v81, 0
	v_add_f32_dpp v82, v82, v82 row_mirror row_mask:0xf bank_mask:0xf bound_ctrl:1
	v_mov_b32_e32 v83, 0
	v_add_f32_dpp v84, v84, v84 row_mirror row_mask:0xf bank_mask:0xf bound_ctrl:1
	v_mov_b32_e32 v85, 0
	v_add_f32_dpp v86, v86, v86 row_mirror row_mask:0xf bank_mask:0xf bound_ctrl:1
	v_mov_b32_e32 v87, 0
	v_mov_b32_dpp v65, v64 row_bcast:15 row_mask:0xa bank_mask:0xf
	v_mov_b32_dpp v67, v66 row_bcast:15 row_mask:0xa bank_mask:0xf
	v_mov_b32_dpp v69, v68 row_bcast:15 row_mask:0xa bank_mask:0xf
	v_mov_b32_dpp v71, v70 row_bcast:15 row_mask:0xa bank_mask:0xf
	v_mov_b32_dpp v81, v80 row_bcast:15 row_mask:0xa bank_mask:0xf
	v_mov_b32_dpp v83, v82 row_bcast:15 row_mask:0xa bank_mask:0xf
	v_mov_b32_dpp v85, v84 row_bcast:15 row_mask:0xa bank_mask:0xf
	v_mov_b32_dpp v87, v86 row_bcast:15 row_mask:0xa bank_mask:0xf
	s_and_saveexec_b64 s[4:5], vcc
	s_cbranch_execz .LBB0_1112
	v_add_f32_e32 v64, v64, v65
	v_add_f32_e32 v86, v86, v87
	v_add_f32_e32 v84, v84, v85
	v_add_f32_e32 v82, v82, v83
	v_add_f32_e32 v80, v80, v81
	v_add_f32_e32 v70, v70, v71
	v_add_f32_e32 v68, v68, v69
	v_add_f32_e32 v66, v66, v67
	global_atomic_add_f32 v[96:97], v64, off
	global_atomic_add_f32 v[96:97], v66, off offset:4
	global_atomic_add_f32 v[96:97], v68, off offset:8
	global_atomic_add_f32 v[96:97], v70, off offset:12
	global_atomic_add_f32 v[96:97], v80, off offset:32
	global_atomic_add_f32 v[96:97], v82, off offset:36
	global_atomic_add_f32 v[96:97], v84, off offset:40
	global_atomic_add_f32 v[96:97], v86, off offset:44

; #define MFMA32(a, b, c) __builtin_amdgcn_mfma_f32_32x32x16_bf16((a), (b), (c), 0, 0, 0)
; #define GA_LOAD(pr_) do { _Pragma("unroll") for (int i = 0; i < 4; ++i) ra[i] = *(const u32x4*)(Ab + (i * 32) * lda + (pr_) * 64); } while (0)
; #define GB_LOAD(kt_) do { const bfr* bk_ = Bb + (kt_) * NB * 32; \
;     _Pragma("unroll") for (int i = 0; i < 4; ++i) rb[i] = *(const u32x4*)(bk_ + (i * 64) * 32); } while (0)
; #define G_STORE(kt_) do { bfr* as_ = S0 + ((kt_) & 1) * GSTAGE; bfr* bs_ = as_ + 128 * 40; \
;     if (apar == ((kt_) & 1)) { _Pragma("unroll") for (int i = 0; i < 4; ++i) *(u32x4*)(as_ + asoff + i * 32 * 40) = ra[i]; } \
;     _Pragma("unroll") for (int i = 0; i < 4; ++i) *(u32x4*)(bs_ + bsoff + i * 64 * 40) = rb[i]; } while (0)
; template <int lda>
; DI void gemm_mainloop(const bfr* __restrict__ A, const bfr* __restrict__ Bt, int NB, int K, int m0, int n0, char* smem, f32x16 (&acc)[2][4]) {
;     ...
;   GA_LOAD(0);
;   GB_LOAD(0);
;   G_STORE(0);
;   GB_LOAD(1);
;   __syncthreads();
;   for (int kt = 0; kt < nk; ++kt) {
;     if (kt + 1 < nk) G_STORE(kt + 1);
;     if (kt + 2 < nk) {
;       GB_LOAD(kt + 2);
;       if ((kt & 1) == 0) GA_LOAD((kt >> 1) + 1);
;     }
;     const bfr* As = S0 + (kt & 1) * GSTAGE;
;     const bfr* Bs = As + 128 * 40;
; #pragma unroll
;     for (int ks = 0; ks < 2; ++ks) {
;       bf16x8 af[2], bfg[4];
; #pragma unroll
;       for (int i = 0; i < 2; ++i) af[i] = *(const bf16x8*)(As + (wr * 64 + i * 32 + r) * 40 + ks * 16 + hl * 8);
; #pragma unroll
;       for (int j = 0; j < 4; ++j) bfg[j] = *(const bf16x8*)(Bs + (wc * 128 + j * 32 + r) * 40 + ks * 16 + hl * 8);
; #pragma unroll
;       for (int i = 0; i < 2; ++i)
; #pragma unroll
;         for (int j = 0; j < 4; ++j) acc[i][j] = MFMA32(af[i], bfg[j], acc[i][j]);
;     }
;     __syncthreads();
.Lp12_loop:
	s_waitcnt vmcnt(6)
	s_barrier
	s_mul_i32 s74, s71, 0x6000
	s_add_u32 s75, s74, 0x2000
	s_cmp_eq_u32 s71, 2
	s_cselect_b32 s75, 0x10000, s75
	v_add_u32_e32 v183, s74, v179
	v_add_u32_e32 v185, s75, v181
	v_add_u32_e32 v184, s74, v180
	v_add_u32_e32 v186, s75, v182
	ds_read_b128 v[128:131], v183
	ds_read_b128 v[144:147], v185
	ds_read_b128 v[148:151], v185 offset:2048
	ds_read_b128 v[152:155], v185 offset:4096
	ds_read_b128 v[156:159], v185 offset:6144
	ds_read_b128 v[132:135], v183 offset:2048
	ds_read_b128 v[136:139], v184
	ds_read_b128 v[160:163], v186
	ds_read_b128 v[164:167], v186 offset:2048
	ds_read_b128 v[168:171], v186 offset:4096
	ds_read_b128 v[172:175], v186 offset:6144
	ds_read_b128 v[140:143], v184 offset:2048
	s_add_u32 s71, s71, 1
	s_cmp_eq_u32 s71, 3
	s_cselect_b32 s71, 0, s71
	s_waitcnt lgkmcnt(10)
	v_mfma_f32_32x32x16_bf16 v[112:127], v[128:131], v[144:147], v[112:127]
	s_mul_i32 s74, s70, 0x6000
	s_add_u32 s75, s74, s68
	s_mov_b32 m0, s75
	s_add_u32 s76, s74, 0x2000
	s_cmp_eq_u32 s70, 2
	s_cselect_b32 s76, 0x10000, s76
	global_load_lds_dwordx4 v176, s[64:65]
	s_waitcnt lgkmcnt(9)
	v_mfma_f32_32x32x16_bf16 v[96:111], v[128:131], v[148:151], v[96:111]
	s_add_u32 m0, s75, 0x400
	s_add_u32 s76, s76, s69
	global_load_lds_dwordx4 v177, s[64:65]
	s_waitcnt lgkmcnt(8)
	v_mfma_f32_32x32x16_bf16 v[80:95], v[128:131], v[152:155], v[80:95]
	s_mov_b32 m0, s76
	s_add_u32 s64, s64, 64
	s_addc_u32 s65, s65, 0
	global_load_lds_dwordx4 v178, s[66:67]
	s_waitcnt lgkmcnt(7)
	v_mfma_f32_32x32x16_bf16 v[64:79], v[128:131], v[156:159], v[64:79]
	global_load_lds_dwordx4 v178, s[66:67] offset:1024
	s_waitcnt lgkmcnt(6)
	v_mfma_f32_32x32x16_bf16 v[48:63], v[132:135], v[144:147], v[48:63]
	global_load_lds_dwordx4 v178, s[66:67] offset:2048
	v_mfma_f32_32x32x16_bf16 v[32:47], v[132:135], v[148:151], v[32:47]
	global_load_lds_dwordx4 v178, s[66:67] offset:3072
	s_add_u32 s66, s66, 0x20000
	s_addc_u32 s67, s67, 0
	v_mfma_f32_32x32x16_bf16 v[16:31], v[132:135], v[152:155], v[16:31]
	s_add_u32 s70, s70, 1
	s_cmp_eq_u32 s70, 3
	s_cselect_b32 s70, 0, s70
	v_mfma_f32_32x32x16_bf16 v[0:15], v[132:135], v[156:159], v[0:15]
	s_waitcnt lgkmcnt(4)
	v_mfma_f32_32x32x16_bf16 v[112:127], v[136:139], v[160:163], v[112:127]
	s_waitcnt lgkmcnt(3)
	v_mfma_f32_32x32x16_bf16 v[96:111], v[136:139], v[164:167], v[96:111]
	s_waitcnt lgkmcnt(2)
	v_mfma_f32_32x32x16_bf16 v[80:95], v[136:139], v[168:171], v[80:95]
	s_waitcnt lgkmcnt(1)
	v_mfma_f32_32x32x16_bf16 v[64:79], v[136:139], v[172:175], v[64:79]
	s_waitcnt lgkmcnt(0)
	v_mfma_f32_32x32x16_bf16 v[48:63], v[140:143], v[160:163], v[48:63]
	v_mfma_f32_32x32x16_bf16 v[32:47], v[140:143], v[164:167], v[32:47]
	v_mfma_f32_32x32x16_bf16 v[16:31], v[140:143], v[168:171], v[16:31]
	v_mfma_f32_32x32x16_bf16 v[0:15], v[140:143], v[172:175], v[0:15]
	s_add_u32 s72, s72, 1
	s_cmp_lt_u32 s72, 30
	s_cbranch_scc1 .Lp12_loop
	s_waitcnt vmcnt(6)
	s_barrier
; #define MFMA32(a, b, c) __builtin_amdgcn_mfma_f32_32x32x16_bf16((a), (b), (c), 0, 0, 0)
; #define GA_LOAD(pr_) do { _Pragma("unroll") for (int i = 0; i < 4; ++i) ra[i] = *(const u32x4*)(Ab + (i * 32) * lda + (pr_) * 64); } while (0)
; #define GB_LOAD(kt_) do { const bfr* bk_ = Bb + (kt_) * NB * 32; \
;     _Pragma("unroll") for (int i = 0; i < 4; ++i) rb[i] = *(const u32x4*)(bk_ + (i * 64) * 32); } while (0)
; #define G_STORE(kt_) do { bfr* as_ = S0 + ((kt_) & 1) * GSTAGE; bfr* bs_ = as_ + 128 * 40; \
;     if (apar == ((kt_) & 1)) { _Pragma("unroll") for (int i = 0; i < 4; ++i) *(u32x4*)(as_ + asoff + i * 32 * 40) = ra[i]; } \
;     _Pragma("unroll") for (int i = 0; i < 4; ++i) *(u32x4*)(bs_ + bsoff + i * 64 * 40) = rb[i]; } while (0)
; template <int lda>
; DI void gemm_mainloop(const bfr* __restrict__ A, const bfr* __restrict__ Bt, int NB, int K, int m0, int n0, char* smem, f32x16 (&acc)[2][4]) {
;     ...
;   for (int kt = 0; kt < nk; ++kt) {
;     if (kt + 1 < nk) G_STORE(kt + 1);
;     if (kt + 2 < nk) {
;       GB_LOAD(kt + 2);
;       if ((kt & 1) == 0) GA_LOAD((kt >> 1) + 1);
;     }
;     const bfr* As = S0 + (kt & 1) * GSTAGE;
;     const bfr* Bs = As + 128 * 40;
; #pragma unroll
;     for (int ks = 0; ks < 2; ++ks) {
;       bf16x8 af[2], bfg[4];
; #pragma unroll
;       for (int i = 0; i < 2; ++i) af[i] = *(const bf16x8*)(As + (wr * 64 + i * 32 + r) * 40 + ks * 16 + hl * 8);
; #pragma unroll
;       for (int j = 0; j < 4; ++j) bfg[j] = *(const bf16x8*)(Bs + (wc * 128 + j * 32 + r) * 40 + ks * 16 + hl * 8);
; #pragma unroll
;       for (int i = 0; i < 2; ++i)
; #pragma unroll
;         for (int j = 0; j < 4; ++j) acc[i][j] = MFMA32(af[i], bfg[j], acc[i][j]);
;     }
;     __syncthreads();
	s_mul_i32 s74, s71, 0x6000
	s_add_u32 s75, s74, 0x2000
	s_cmp_eq_u32 s71, 2
	s_cselect_b32 s75, 0x10000, s75
	v_add_u32_e32 v183, s74, v179
	v_add_u32_e32 v185, s75, v181
	v_add_u32_e32 v184, s74, v180
	v_add_u32_e32 v186, s75, v182
	ds_read_b128 v[128:131], v183
	ds_read_b128 v[144:147], v185
	ds_read_b128 v[148:151], v185 offset:2048
	ds_read_b128 v[152:155], v185 offset:4096
	ds_read_b128 v[156:159], v185 offset:6144
	ds_read_b128 v[132:135], v183 offset:2048
	ds_read_b128 v[136:139], v184
	ds_read_b128 v[160:163], v186
	ds_read_b128 v[164:167], v186 offset:2048
	ds_read_b128 v[168:171], v186 offset:4096
	ds_read_b128 v[172:175], v186 offset:6144
	ds_read_b128 v[140:143], v184 offset:2048
	s_add_u32 s71, s71, 1
	s_cmp_eq_u32 s71, 3
	s_cselect_b32 s71, 0, s71
	s_waitcnt lgkmcnt(10)
	v_mfma_f32_32x32x16_bf16 v[112:127], v[128:131], v[144:147], v[112:127]
	s_waitcnt lgkmcnt(9)
	v_mfma_f32_32x32x16_bf16 v[96:111], v[128:131], v[148:151], v[96:111]
	s_waitcnt lgkmcnt(8)
	v_mfma_f32_32x32x16_bf16 v[80:95], v[128:131], v[152:155], v[80:95]
	s_waitcnt lgkmcnt(7)
	v_mfma_f32_32x32x16_bf16 v[64:79], v[128:131], v[156:159], v[64:79]
	s_waitcnt lgkmcnt(6)
	v_mfma_f32_32x32x16_bf16 v[48:63], v[132:135], v[144:147], v[48:63]
	v_mfma_f32_32x32x16_bf16 v[32:47], v[132:135], v[148:151], v[32:47]
	v_mfma_f32_32x32x16_bf16 v[16:31], v[132:135], v[152:155], v[16:31]
	v_mfma_f32_32x32x16_bf16 v[0:15], v[132:135], v[156:159], v[0:15]
	s_waitcnt lgkmcnt(4)
	v_mfma_f32_32x32x16_bf16 v[112:127], v[136:139], v[160:163], v[112:127]
	s_waitcnt lgkmcnt(3)
	v_mfma_f32_32x32x16_bf16 v[96:111], v[136:139], v[164:167], v[96:111]
	s_waitcnt lgkmcnt(2)
	v_mfma_f32_32x32x16_bf16 v[80:95], v[136:139], v[168:171], v[80:95]
	s_waitcnt lgkmcnt(1)
	v_mfma_f32_32x32x16_bf16 v[64:79], v[136:139], v[172:175], v[64:79]
	s_waitcnt lgkmcnt(0)
	v_mfma_f32_32x32x16_bf16 v[48:63], v[140:143], v[160:163], v[48:63]
	v_mfma_f32_32x32x16_bf16 v[32:47], v[140:143], v[164:167], v[32:47]
	v_mfma_f32_32x32x16_bf16 v[16:31], v[140:143], v[168:171], v[16:31]
	v_mfma_f32_32x32x16_bf16 v[0:15], v[140:143], v[172:175], v[0:15]
	s_waitcnt vmcnt(0)
	s_barrier
	s_mul_i32 s74, s71, 0x6000
	s_add_u32 s75, s74, 0x2000
	s_cmp_eq_u32 s71, 2
	s_cselect_b32 s75, 0x10000, s75
	v_add_u32_e32 v183, s74, v179
	v_add_u32_e32 v185, s75, v181
	v_add_u32_e32 v184, s74, v180
	v_add_u32_e32 v186, s75, v182
	ds_read_b128 v[128:131], v183
	ds_read_b128 v[144:147], v185
	ds_read_b128 v[148:151], v185 offset:2048
	ds_read_b128 v[152:155], v185 offset:4096
	ds_read_b128 v[156:159], v185 offset:6144
	ds_read_b128 v[132:135], v183 offset:2048
	ds_read_b128 v[136:139], v184
	ds_read_b128 v[160:163], v186
	ds_read_b128 v[164:167], v186 offset:2048
	ds_read_b128 v[168:171], v186 offset:4096
	ds_read_b128 v[172:175], v186 offset:6144
	ds_read_b128 v[140:143], v184 offset:2048
	s_add_u32 s71, s71, 1
	s_cmp_eq_u32 s71, 3
	s_cselect_b32 s71, 0, s71
	s_waitcnt lgkmcnt(10)
	v_mfma_f32_32x32x16_bf16 v[112:127], v[128:131], v[144:147], v[112:127]
	s_waitcnt lgkmcnt(9)
	v_mfma_f32_32x32x16_bf16 v[96:111], v[128:131], v[148:151], v[96:111]
	s_waitcnt lgkmcnt(8)
	v_mfma_f32_32x32x16_bf16 v[80:95], v[128:131], v[152:155], v[80:95]
	s_waitcnt lgkmcnt(7)
	v_mfma_f32_32x32x16_bf16 v[64:79], v[128:131], v[156:159], v[64:79]
	s_waitcnt lgkmcnt(6)
	v_mfma_f32_32x32x16_bf16 v[48:63], v[132:135], v[144:147], v[48:63]
	v_mfma_f32_32x32x16_bf16 v[32:47], v[132:135], v[148:151], v[32:47]
	v_mfma_f32_32x32x16_bf16 v[16:31], v[132:135], v[152:155], v[16:31]
	v_mfma_f32_32x32x16_bf16 v[0:15], v[132:135], v[156:159], v[0:15]
	s_waitcnt lgkmcnt(4)
	v_mfma_f32_32x32x16_bf16 v[112:127], v[136:139], v[160:163], v[112:127]
	s_waitcnt lgkmcnt(3)
	v_mfma_f32_32x32x16_bf16 v[96:111], v[136:139], v[164:167], v[96:111]
	s_waitcnt lgkmcnt(2)
	v_mfma_f32_32x32x16_bf16 v[80:95], v[136:139], v[168:171], v[80:95]
	s_waitcnt lgkmcnt(1)
	v_mfma_f32_32x32x16_bf16 v[64:79], v[136:139], v[172:175], v[64:79]
	s_waitcnt lgkmcnt(0)
	v_mfma_f32_32x32x16_bf16 v[48:63], v[140:143], v[160:163], v[48:63]
	v_mfma_f32_32x32x16_bf16 v[32:47], v[140:143], v[164:167], v[32:47]
	v_mfma_f32_32x32x16_bf16 v[16:31], v[140:143], v[168:171], v[16:31]
	v_mfma_f32_32x32x16_bf16 v[0:15], v[140:143], v[172:175], v[0:15]
	s_nop 7
	v_readlane_b32 s64, v187, 0
	v_readlane_b32 s65, v187, 1
	v_readlane_b32 s66, v187, 2
	v_readlane_b32 s67, v187, 3
	v_readlane_b32 s68, v187, 4
	v_readlane_b32 s69, v187, 5
	v_readlane_b32 s70, v187, 6
	v_readlane_b32 s71, v187, 7
	v_readlane_b32 s72, v187, 8
	v_readlane_b32 s73, v187, 9
	v_readlane_b32 s74, v187, 10
	v_readlane_b32 s75, v187, 11
	v_readlane_b32 s76, v187, 12
	v_readlane_b32 s77, v187, 13
	v_readlane_b32 s78, v187, 14
	v_readlane_b32 s79, v187, 15
	s_nop 7
	s_branch .LBB0_1178

; #define MFMA32(a, b, c) __builtin_amdgcn_mfma_f32_32x32x16_bf16((a), (b), (c), 0, 0, 0)
; #define GA_LOAD(pr_) do { _Pragma("unroll") for (int i = 0; i < 4; ++i) ra[i] = *(const u32x4*)(Ab + (i * 32) * lda + (pr_) * 64); } while (0)
; #define GB_LOAD(kt_) do { const bfr* bk_ = Bb + (kt_) * NB * 32; \
;     _Pragma("unroll") for (int i = 0; i < 4; ++i) rb[i] = *(const u32x4*)(bk_ + (i * 64) * 32); } while (0)
; #define G_STORE(kt_) do { bfr* as_ = S0 + ((kt_) & 1) * GSTAGE; bfr* bs_ = as_ + 128 * 40; \
;     if (apar == ((kt_) & 1)) { _Pragma("unroll") for (int i = 0; i < 4; ++i) *(u32x4*)(as_ + asoff + i * 32 * 40) = ra[i]; } \
;     _Pragma("unroll") for (int i = 0; i < 4; ++i) *(u32x4*)(bs_ + bsoff + i * 64 * 40) = rb[i]; } while (0)
; template <int lda>
; DI void gemm_mainloop(const bfr* __restrict__ A, const bfr* __restrict__ Bt, int NB, int K, int m0, int n0, char* smem, f32x16 (&acc)[2][4]) {
;     ...
;   GA_LOAD(0);
;   GB_LOAD(0);
;   G_STORE(0);
;   GB_LOAD(1);
;   __syncthreads();
;   for (int kt = 0; kt < nk; ++kt) {
;     if (kt + 1 < nk) G_STORE(kt + 1);
;     if (kt + 2 < nk) {
;       GB_LOAD(kt + 2);
;       if ((kt & 1) == 0) GA_LOAD((kt >> 1) + 1);
;     }
;     const bfr* As = S0 + (kt & 1) * GSTAGE;
;     const bfr* Bs = As + 128 * 40;
; #pragma unroll
;     for (int ks = 0; ks < 2; ++ks) {
;       bf16x8 af[2], bfg[4];
; #pragma unroll
;       for (int i = 0; i < 2; ++i) af[i] = *(const bf16x8*)(As + (wr * 64 + i * 32 + r) * 40 + ks * 16 + hl * 8);
; #pragma unroll
;       for (int j = 0; j < 4; ++j) bfg[j] = *(const bf16x8*)(Bs + (wc * 128 + j * 32 + r) * 40 + ks * 16 + hl * 8);
; #pragma unroll
;       for (int i = 0; i < 2; ++i)
; #pragma unroll
;         for (int j = 0; j < 4; ++j) acc[i][j] = MFMA32(af[i], bfg[j], acc[i][j]);
;     }
;     __syncthreads();
.Lp15_loop:
	s_waitcnt vmcnt(6)
	s_barrier
	s_mul_i32 s74, s71, 0x6000
	s_add_u32 s75, s74, 0x2000
	s_cmp_eq_u32 s71, 2
	s_cselect_b32 s75, 0x10000, s75
	v_add_u32_e32 v183, s74, v179
	v_add_u32_e32 v185, s75, v181
	v_add_u32_e32 v184, s74, v180
	v_add_u32_e32 v186, s75, v182
	ds_read_b128 v[128:131], v183
	ds_read_b128 v[144:147], v185
	ds_read_b128 v[148:151], v185 offset:2048
	ds_read_b128 v[152:155], v185 offset:4096
	ds_read_b128 v[156:159], v185 offset:6144
	ds_read_b128 v[132:135], v183 offset:2048
	ds_read_b128 v[136:139], v184
	ds_read_b128 v[160:163], v186
	ds_read_b128 v[164:167], v186 offset:2048
	ds_read_b128 v[168:171], v186 offset:4096
	ds_read_b128 v[172:175], v186 offset:6144
	ds_read_b128 v[140:143], v184 offset:2048
	s_add_u32 s71, s71, 1
	s_cmp_eq_u32 s71, 3
	s_cselect_b32 s71, 0, s71
	s_waitcnt lgkmcnt(10)
	v_mfma_f32_32x32x16_bf16 v[112:127], v[128:131], v[144:147], v[112:127]
	s_mul_i32 s74, s70, 0x6000
	s_add_u32 s75, s74, s68
	s_mov_b32 m0, s75
	s_add_u32 s76, s74, 0x2000
	s_cmp_eq_u32 s70, 2
	s_cselect_b32 s76, 0x10000, s76
	global_load_lds_dwordx4 v176, s[64:65]
	s_waitcnt lgkmcnt(9)
	v_mfma_f32_32x32x16_bf16 v[96:111], v[128:131], v[148:151], v[96:111]
	s_add_u32 m0, s75, 0x400
	s_add_u32 s76, s76, s69
	global_load_lds_dwordx4 v177, s[64:65]
	s_waitcnt lgkmcnt(8)
	v_mfma_f32_32x32x16_bf16 v[80:95], v[128:131], v[152:155], v[80:95]
	s_mov_b32 m0, s76
	s_add_u32 s64, s64, 64
	s_addc_u32 s65, s65, 0
	global_load_lds_dwordx4 v178, s[66:67]
	s_waitcnt lgkmcnt(7)
	v_mfma_f32_32x32x16_bf16 v[64:79], v[128:131], v[156:159], v[64:79]
	global_load_lds_dwordx4 v178, s[66:67] offset:1024
	s_waitcnt lgkmcnt(6)
	v_mfma_f32_32x32x16_bf16 v[48:63], v[132:135], v[144:147], v[48:63]
	global_load_lds_dwordx4 v178, s[66:67] offset:2048
	v_mfma_f32_32x32x16_bf16 v[32:47], v[132:135], v[148:151], v[32:47]
	global_load_lds_dwordx4 v178, s[66:67] offset:3072
	s_add_u32 s66, s66, 0x10000
	s_addc_u32 s67, s67, 0
	v_mfma_f32_32x32x16_bf16 v[16:31], v[132:135], v[152:155], v[16:31]
	s_add_u32 s70, s70, 1
	s_cmp_eq_u32 s70, 3
	s_cselect_b32 s70, 0, s70
	v_mfma_f32_32x32x16_bf16 v[0:15], v[132:135], v[156:159], v[0:15]
	s_waitcnt lgkmcnt(4)
	v_mfma_f32_32x32x16_bf16 v[112:127], v[136:139], v[160:163], v[112:127]
	s_waitcnt lgkmcnt(3)
	v_mfma_f32_32x32x16_bf16 v[96:111], v[136:139], v[164:167], v[96:111]
	s_waitcnt lgkmcnt(2)
	v_mfma_f32_32x32x16_bf16 v[80:95], v[136:139], v[168:171], v[80:95]
	s_waitcnt lgkmcnt(1)
	v_mfma_f32_32x32x16_bf16 v[64:79], v[136:139], v[172:175], v[64:79]
	s_waitcnt lgkmcnt(0)
	v_mfma_f32_32x32x16_bf16 v[48:63], v[140:143], v[160:163], v[48:63]
	v_mfma_f32_32x32x16_bf16 v[32:47], v[140:143], v[164:167], v[32:47]
	v_mfma_f32_32x32x16_bf16 v[16:31], v[140:143], v[168:171], v[16:31]
	v_mfma_f32_32x32x16_bf16 v[0:15], v[140:143], v[172:175], v[0:15]
	s_add_u32 s72, s72, 1
	s_cmp_lt_u32 s72, 30
	s_cbranch_scc1 .Lp15_loop
	s_waitcnt vmcnt(6)
	s_barrier
	s_mul_i32 s74, s71, 0x6000
	s_add_u32 s75, s74, 0x2000
	s_cmp_eq_u32 s71, 2
	s_cselect_b32 s75, 0x10000, s75
	v_add_u32_e32 v183, s74, v179
	v_add_u32_e32 v185, s75, v181
	v_add_u32_e32 v184, s74, v180
	v_add_u32_e32 v186, s75, v182
	ds_read_b128 v[128:131], v183
	ds_read_b128 v[144:147], v185
	ds_read_b128 v[148:151], v185 offset:2048
	ds_read_b128 v[152:155], v185 offset:4096
	ds_read_b128 v[156:159], v185 offset:6144
	ds_read_b128 v[132:135], v183 offset:2048
	ds_read_b128 v[136:139], v184
	ds_read_b128 v[160:163], v186
	ds_read_b128 v[164:167], v186 offset:2048
	ds_read_b128 v[168:171], v186 offset:4096
	ds_read_b128 v[172:175], v186 offset:6144
	ds_read_b128 v[140:143], v184 offset:2048
	s_add_u32 s71, s71, 1
	s_cmp_eq_u32 s71, 3
	s_cselect_b32 s71, 0, s71
	s_waitcnt lgkmcnt(10)
	v_mfma_f32_32x32x16_bf16 v[112:127], v[128:131], v[144:147], v[112:127]
	s_waitcnt lgkmcnt(9)
	v_mfma_f32_32x32x16_bf16 v[96:111], v[128:131], v[148:151], v[96:111]
	s_waitcnt lgkmcnt(8)
	v_mfma_f32_32x32x16_bf16 v[80:95], v[128:131], v[152:155], v[80:95]
	s_waitcnt lgkmcnt(7)
	v_mfma_f32_32x32x16_bf16 v[64:79], v[128:131], v[156:159], v[64:79]
	s_waitcnt lgkmcnt(6)
	v_mfma_f32_32x32x16_bf16 v[48:63], v[132:135], v[144:147], v[48:63]
	v_mfma_f32_32x32x16_bf16 v[32:47], v[132:135], v[148:151], v[32:47]
	v_mfma_f32_32x32x16_bf16 v[16:31], v[132:135], v[152:155], v[16:31]
	v_mfma_f32_32x32x16_bf16 v[0:15], v[132:135], v[156:159], v[0:15]
	s_waitcnt lgkmcnt(4)
	v_mfma_f32_32x32x16_bf16 v[112:127], v[136:139], v[160:163], v[112:127]
	s_waitcnt lgkmcnt(3)
	v_mfma_f32_32x32x16_bf16 v[96:111], v[136:139], v[164:167], v[96:111]
	s_waitcnt lgkmcnt(2)
	v_mfma_f32_32x32x16_bf16 v[80:95], v[136:139], v[168:171], v[80:95]
	s_waitcnt lgkmcnt(1)
	v_mfma_f32_32x32x16_bf16 v[64:79], v[136:139], v[172:175], v[64:79]
	s_waitcnt lgkmcnt(0)
	v_mfma_f32_32x32x16_bf16 v[48:63], v[140:143], v[160:163], v[48:63]
	v_mfma_f32_32x32x16_bf16 v[32:47], v[140:143], v[164:167], v[32:47]
	v_mfma_f32_32x32x16_bf16 v[16:31], v[140:143], v[168:171], v[16:31]
	v_mfma_f32_32x32x16_bf16 v[0:15], v[140:143], v[172:175], v[0:15]
	s_waitcnt vmcnt(0)
	s_barrier
; #define MFMA32(a, b, c) __builtin_amdgcn_mfma_f32_32x32x16_bf16((a), (b), (c), 0, 0, 0)
; DI int crow(int reg, int h) { return (reg & 3) + 8 * (reg >> 2) + 4 * h; }
; template <int lda>
; DI void gemm_mainloop(const bfr* __restrict__ A, const bfr* __restrict__ Bt, int NB, int K, int m0, int n0, char* smem, f32x16 (&acc)[2][4]) {
;     ...
;     const bfr* As = S0 + (kt & 1) * GSTAGE;
;     const bfr* Bs = As + 128 * 40;
; #pragma unroll
;     for (int ks = 0; ks < 2; ++ks) {
;       bf16x8 af[2], bfg[4];
; #pragma unroll
;       for (int i = 0; i < 2; ++i) af[i] = *(const bf16x8*)(As + (wr * 64 + i * 32 + r) * 40 + ks * 16 + hl * 8);
; #pragma unroll
;       for (int j = 0; j < 4; ++j) bfg[j] = *(const bf16x8*)(Bs + (wc * 128 + j * 32 + r) * 40 + ks * 16 + hl * 8);
; #pragma unroll
;       for (int i = 0; i < 2; ++i)
; #pragma unroll
;         for (int j = 0; j < 4; ++j) acc[i][j] = MFMA32(af[i], bfg[j], acc[i][j]);
;     }
; template <bool FIRST, bool HAS_H>
; DI void phase_gemm_resid(const Params& p, const bfr* A, const bfr* Wt, const float* gnext, float* ss, char* smem) {
;     ...
;     int tid2 = threadIdx.x;
;     asm volatile("" : "+v"(tid2));
;     const int lane = tid2 & 63, wid = tid2 >> 6, wr = wid >> 1, wc = wid & 1, r = lane & 31, hl = lane >> 5;
;     const float* xsrc = FIRST ? p.x_prompt : X;
;     const int rbase = m0 + wr * 64 + 4 * hl, cbase = n0 + wc * 128 + r;
; #pragma unroll
;     for (int i = 0; i < 2; ++i) {
; #pragma unroll
;       for (int qh = 0; qh < 2; ++qh) {
;         float rs[8];
; #pragma unroll
;         for (int q = 0; q < 8; ++q) rs[q] = 0.f;
; #pragma unroll
;         for (int jh = 0; jh < 2; ++jh) {
;           float xo[2][8];
; #pragma unroll
;           for (int jj = 0; jj < 2; ++jj)
; #pragma unroll
;             for (int q = 0; q < 8; ++q)
;               xo[jj][q] = xsrc[(rbase + i * 32 + crow(qh * 8 + q, 0)) * 1024 + cbase + (jh * 2 + jj) * 32];
	s_mul_i32 s74, s71, 0x6000
	s_add_u32 s75, s74, 0x2000
	s_cmp_eq_u32 s71, 2
	s_cselect_b32 s75, 0x10000, s75
	v_add_u32_e32 v183, s74, v179
	v_add_u32_e32 v185, s75, v181
	v_add_u32_e32 v184, s74, v180
	v_add_u32_e32 v186, s75, v182
	ds_read_b128 v[128:131], v183
	ds_read_b128 v[144:147], v185
	ds_read_b128 v[148:151], v185 offset:2048
	ds_read_b128 v[152:155], v185 offset:4096
	ds_read_b128 v[156:159], v185 offset:6144
	ds_read_b128 v[132:135], v183 offset:2048
	ds_read_b128 v[136:139], v184
	ds_read_b128 v[160:163], v186
	ds_read_b128 v[164:167], v186 offset:2048
	ds_read_b128 v[168:171], v186 offset:4096
	ds_read_b128 v[172:175], v186 offset:6144
	ds_read_b128 v[140:143], v184 offset:2048
	s_add_u32 s71, s71, 1
	s_cmp_eq_u32 s71, 3
	s_cselect_b32 s71, 0, s71
	s_waitcnt lgkmcnt(10)
	v_mfma_f32_32x32x16_bf16 v[112:127], v[128:131], v[144:147], v[112:127]
	s_waitcnt lgkmcnt(9)
	v_mfma_f32_32x32x16_bf16 v[96:111], v[128:131], v[148:151], v[96:111]
	s_waitcnt lgkmcnt(8)
	v_mfma_f32_32x32x16_bf16 v[80:95], v[128:131], v[152:155], v[80:95]
	s_waitcnt lgkmcnt(7)
	v_mfma_f32_32x32x16_bf16 v[64:79], v[128:131], v[156:159], v[64:79]
	s_waitcnt lgkmcnt(6)
	v_mfma_f32_32x32x16_bf16 v[48:63], v[132:135], v[144:147], v[48:63]
	v_mfma_f32_32x32x16_bf16 v[32:47], v[132:135], v[148:151], v[32:47]
	v_mfma_f32_32x32x16_bf16 v[16:31], v[132:135], v[152:155], v[16:31]
	v_mfma_f32_32x32x16_bf16 v[0:15], v[132:135], v[156:159], v[0:15]
	s_waitcnt lgkmcnt(4)
	v_mfma_f32_32x32x16_bf16 v[112:127], v[136:139], v[160:163], v[112:127]
	s_waitcnt lgkmcnt(3)
	v_mfma_f32_32x32x16_bf16 v[96:111], v[136:139], v[164:167], v[96:111]
	s_waitcnt lgkmcnt(2)
	v_mfma_f32_32x32x16_bf16 v[80:95], v[136:139], v[168:171], v[80:95]
	s_waitcnt lgkmcnt(1)
	v_mfma_f32_32x32x16_bf16 v[64:79], v[136:139], v[172:175], v[64:79]
	s_waitcnt lgkmcnt(0)
	v_mfma_f32_32x32x16_bf16 v[48:63], v[140:143], v[160:163], v[48:63]
	v_mfma_f32_32x32x16_bf16 v[32:47], v[140:143], v[164:167], v[32:47]
	v_mfma_f32_32x32x16_bf16 v[16:31], v[140:143], v[168:171], v[16:31]
	v_mfma_f32_32x32x16_bf16 v[0:15], v[140:143], v[172:175], v[0:15]
	s_nop 7
	v_readlane_b32 s64, v187, 0
	v_readlane_b32 s65, v187, 1
	v_readlane_b32 s66, v187, 2
	v_readlane_b32 s67, v187, 3
	v_readlane_b32 s68, v187, 4
	v_readlane_b32 s69, v187, 5
	v_readlane_b32 s70, v187, 6
	v_readlane_b32 s71, v187, 7
	v_readlane_b32 s72, v187, 8
	v_readlane_b32 s73, v187, 9
	v_readlane_b32 s74, v187, 10
	v_readlane_b32 s75, v187, 11
	v_readlane_b32 s76, v187, 12
	v_readlane_b32 s77, v187, 13
	v_readlane_b32 s78, v187, 14
	v_readlane_b32 s79, v187, 15
	s_nop 7
	s_waitcnt vmcnt(1)
	s_nop 0
	s_nop 0
	s_nop 0
	s_waitcnt vmcnt(0)
	s_nop 0
	v_add_u32_e32 v132, v169, v171
	s_nop 0
	v_add_u32_e32 v133, v169, v170
	s_nop 0
	s_nop 0
	s_nop 0
	s_nop 0
	s_nop 0
	s_nop 0
	s_nop 0
	s_nop 0
	s_nop 0
	s_nop 0
	s_nop 0
	v_mov_b32_e32 v192, v196
	s_waitcnt lgkmcnt(0)
	s_nop 0
	s_nop 0
	s_nop 0
	s_nop 0
	s_nop 0
	s_nop 0
	s_nop 0
	s_nop 0
	s_nop 0
	s_nop 0
	s_nop 0
	s_nop 0
	s_nop 0
	s_nop 0
	s_nop 0
	s_nop 0
	s_nop 0
	s_waitcnt lgkmcnt(0)
	s_nop 0
	s_nop 0
	v_ashrrev_i32_e32 v194, 1, v192
	v_and_b32_e32 v194, 0xffffffc0, v194
	v_add_u32_e32 v194, s36, v194
	v_lshrrev_b32_e32 v195, 3, v192
	v_and_b32_e32 v232, 31, v192
	s_nop 0
	v_and_or_b32 v216, v195, 4, v194
	v_lshlrev_b32_e32 v192, 1, v192
	v_and_b32_e32 v192, 0x80, v192
	v_lshlrev_b32_e32 v205, 10, v216
	v_or3_b32 v199, s33, v192, v232
	v_or_b32_e32 v194, v205, v199
	v_ashrrev_i32_e32 v195, 31, v194
	s_nop 0
	v_or_b32_e32 v220, 0x400, v205
	v_or_b32_e32 v218, v220, v199
	v_ashrrev_i32_e32 v219, 31, v218
	v_lshl_add_u64 v[218:219], v[218:219], 2, s[10:11]
	v_or_b32_e32 v204, 32, v199
	global_load_dword v221, v[218:219], off
	v_or_b32_e32 v218, v220, v204
	s_nop 0
	v_ashrrev_i32_e32 v203, 31, v205
	v_mov_b32_e32 v202, v194
	v_lshl_add_u64 v[200:201], v[194:195], 2, s[10:11]
	v_lshl_add_u64 v[202:203], v[202:203], 2, s[10:11]
	global_load_dword v192, v[200:201], off
	global_load_dword v217, v[202:203], off offset:128
	v_ashrrev_i32_e32 v219, 31, v218
	v_lshl_add_u64 v[218:219], v[218:219], 2, s[10:11]
	v_or_b32_e32 v223, 0x800, v205
	global_load_dword v222, v[218:219], off
	v_or_b32_e32 v218, v223, v199
	v_ashrrev_i32_e32 v219, 31, v218
	v_lshl_add_u64 v[218:219], v[218:219], 2, s[10:11]
	s_nop 0
	global_load_dword v224, v[218:219], off
	v_or_b32_e32 v218, v223, v204
	v_ashrrev_i32_e32 v219, 31, v218
	v_lshl_add_u64 v[218:219], v[218:219], 2, s[10:11]
	global_load_dword v225, v[218:219], off
	v_or_b32_e32 v226, 0xc00, v205
	v_or_b32_e32 v227, 0x2000, v205
	s_nop 0
	v_or_b32_e32 v228, 0x2400, v205
	v_or_b32_e32 v229, 0x2800, v205
	v_or_b32_e32 v218, v226, v199
	v_or_b32_e32 v230, 0x2c00, v205
	v_ashrrev_i32_e32 v219, 31, v218
	v_lshl_add_u64 v[218:219], v[218:219], 2, s[10:11]
	v_cmp_eq_u32_e32 vcc, 31, v232
	s_nop 0
	s_nop 0
	s_nop 0
	s_nop 0
	s_nop 0
	s_nop 0
	s_waitcnt vmcnt(0)
; DI bfr f2bf(float a) { return (bfr)(pack2(a, 0.f) & 0xffffu); }
; DI int crow(int reg, int h) { return (reg & 3) + 8 * (reg >> 2) + 4 * h; }
; template <bool FIRST, bool HAS_H>
; DI void phase_gemm_resid(const Params& p, const bfr* A, const bfr* Wt, const float* gnext, float* ss, char* smem) {
;     ...
; #pragma unroll
;     for (int i = 0; i < 2; ++i) {
; #pragma unroll
;       for (int qh = 0; qh < 2; ++qh) {
;         float rs[8];
; #pragma unroll
;         for (int q = 0; q < 8; ++q) rs[q] = 0.f;
; #pragma unroll
;         for (int jh = 0; jh < 2; ++jh) {
;           float xo[2][8];
; #pragma unroll
;           for (int jj = 0; jj < 2; ++jj)
; #pragma unroll
;             for (int q = 0; q < 8; ++q)
;               xo[jj][q] = xsrc[(rbase + i * 32 + crow(qh * 8 + q, 0)) * 1024 + cbase + (jh * 2 + jj) * 32];
; #pragma unroll
;           for (int q = 0; q < 8; ++q) {
;             const int o = (rbase + i * 32 + crow(qh * 8 + q, 0)) * 1024 + cbase;
; #pragma unroll
;             for (int jj = 0; jj < 2; ++jj) {
;               const int j = jh * 2 + jj;
;               const float xn = xo[jj][q] + acc[i][j][qh * 8 + q];
;               X[o + j * 32] = xn;
;               if (HAS_H) Hn[o + j * 32] = f2bf(xn * gnext[cbase + j * 32]);
;               rs[q] += xn * xn;
;             }
;           }
;         }
	s_nop 9
	v_add_f32_e32 v98, v98, v225
	s_nop 0
	v_or_b32_e32 v206, v227, v199
	v_or_b32_e32 v208, v228, v199
	v_ashrrev_i32_e32 v207, 31, v206
	v_ashrrev_i32_e32 v209, 31, v208
	v_lshl_add_u64 v[206:207], v[206:207], 2, s[10:11]
	v_lshl_add_u64 v[208:209], v[208:209], 2, s[10:11]
	s_nop 0
	v_or_b32_e32 v210, v229, v199
	v_ashrrev_i32_e32 v211, 31, v210
	v_or_b32_e32 v212, v230, v199
	v_lshl_add_u64 v[210:211], v[210:211], 2, s[10:11]
	v_ashrrev_i32_e32 v213, 31, v212
	v_lshl_add_u64 v[212:213], v[212:213], 2, s[10:11]
	global_load_dword v231, v[218:219], off
	global_load_dword v233, v[206:207], off
	global_load_dword v234, v[208:209], off
	global_load_dword v235, v[210:211], off
	global_load_dword v236, v[212:213], off
	v_or_b32_e32 v206, v226, v204
	v_or_b32_e32 v208, v227, v204
	v_or_b32_e32 v210, v228, v204
	v_ashrrev_i32_e32 v207, 31, v206
	v_ashrrev_i32_e32 v209, 31, v208
	v_ashrrev_i32_e32 v211, 31, v210
	v_or_b32_e32 v212, v229, v204
	v_or_b32_e32 v218, v230, v204
	v_lshl_add_u64 v[206:207], v[206:207], 2, s[10:11]
	v_lshl_add_u64 v[208:209], v[208:209], 2, s[10:11]
	v_lshl_add_u64 v[210:211], v[210:211], 2, s[10:11]
	v_ashrrev_i32_e32 v213, 31, v212
	v_ashrrev_i32_e32 v219, 31, v218
	v_lshl_add_u64 v[212:213], v[212:213], 2, s[10:11]
	v_lshl_add_u64 v[218:219], v[218:219], 2, s[10:11]
	global_load_dword v206, v[206:207], off
	s_nop 0
	global_load_dword v207, v[208:209], off
	s_nop 0
	global_load_dword v208, v[210:211], off
	global_load_dword v209, v[212:213], off
	s_nop 0
	global_load_dword v210, v[218:219], off
	v_add_f32_e32 v211, v112, v192
	v_or_b32_e32 v112, 0x400, v194
	global_store_dword v[200:201], v211, off
	v_lshlrev_b32_e32 v192, 2, v199
	v_add_f32_e32 v213, v96, v217
	s_nop 0
	v_add_f32_e32 v189, v113, v221
	v_ashrrev_i32_e32 v113, 31, v112
	v_or_b32_e32 v96, 0x420, v194
	global_load_dword v212, v192, s[12:13]
	v_lshl_add_u64 v[112:113], v[112:113], 2, s[10:11]
	global_store_dword v[200:201], v213, off offset:128
	global_load_dword v188, v192, s[12:13] offset:128
	s_nop 0
	v_add_f32_e32 v185, v97, v222
	v_ashrrev_i32_e32 v97, 31, v96
	global_store_dword v[112:113], v189, off
	v_lshl_add_u64 v[96:97], v[96:97], 2, s[10:11]
	global_load_dword v184, v192, s[12:13]
	v_ashrrev_i32_e32 v217, 31, v216
	global_store_dword v[96:97], v185, off
	s_nop 0
	v_or_b32_e32 v172, 0x800, v194
	v_ashrrev_i32_e32 v173, 31, v172
	v_add_f32_e32 v176, v114, v224
	v_lshl_add_u64 v[96:97], v[172:173], 2, s[10:11]
	v_or_b32_e32 v174, 0x820, v194
	global_load_dword v186, v192, s[12:13] offset:128
	v_ashrrev_i32_e32 v175, 31, v174
	global_store_dword v[96:97], v176, off
	global_load_dword v177, v192, s[12:13]
	v_lshl_add_u64 v[96:97], v[174:175], 2, s[10:11]
	global_store_dword v[96:97], v98, off
	global_load_dword v178, v192, s[12:13] offset:128
	s_nop 0
	v_lshl_add_u64 v[162:163], v[172:173], 1, s[6:7]
	v_lshl_add_u64 v[96:97], v[216:217], 2, s[14:15]
	s_waitcnt vmcnt(21)
	v_add_f32_e32 v115, v115, v231
	s_nop 0
	s_waitcnt vmcnt(10)
	v_mul_f32_e32 v112, v211, v212
	s_nop 0
	v_cvt_pk_bf16_f32 v114, v112, s0
	v_lshl_add_u64 v[112:113], v[194:195], 1, s[6:7]
	global_store_short v[112:113], v114, off
	s_waitcnt vmcnt(9)
	v_mul_f32_e32 v114, v213, v188
	v_cvt_pk_bf16_f32 v114, v114, s0
	global_store_short v[112:113], v114, off offset:64
	v_mul_f32_e32 v114, v213, v213
	s_nop 0
	v_or_b32_e32 v152, 0xc00, v194
	v_ashrrev_i32_e32 v153, 31, v152
	v_lshl_add_u64 v[154:155], v[152:153], 2, s[10:11]
	global_store_dword v[154:155], v115, off
	v_or_b32_e32 v154, 0xc20, v194
	v_ashrrev_i32_e32 v155, 31, v154
	s_waitcnt vmcnt(9)
	v_mul_f32_e32 v160, v189, v184
	s_nop 0
	v_add_f32_e32 v169, v119, v236
	v_add_f32_e32 v171, v103, v210
	v_cvt_pk_bf16_f32 v160, v160, s0
	s_waitcnt vmcnt(5)
	v_mul_f32_e32 v161, v176, v177
	v_cvt_pk_bf16_f32 v161, v161, s0
	global_store_short v[162:163], v161, off
	s_waitcnt vmcnt(4)
	v_mul_f32_e32 v161, v98, v178
	s_nop 0
	global_load_dword v158, v192, s[12:13]
	v_cvt_pk_bf16_f32 v161, v161, s0
	v_lshl_add_u64 v[162:163], v[174:175], 1, s[6:7]
	global_store_short v[162:163], v161, off
	v_mul_f32_e32 v161, v98, v98
	v_add_f32_e32 v159, v99, v206
	v_lshl_add_u64 v[98:99], v[154:155], 2, s[10:11]
	global_store_dword v[98:99], v159, off
	global_load_dword v162, v192, s[12:13] offset:128
	v_or_b32_e32 v156, 0x2000, v194
	v_ashrrev_i32_e32 v157, 31, v156
	s_nop 0
	v_add_f32_e32 v163, v116, v233
	v_lshl_add_u64 v[98:99], v[156:157], 2, s[10:11]
	global_store_dword v[98:99], v163, off
	v_or_b32_e32 v116, 0x2400, v194
	v_add_f32_e32 v165, v117, v234
	v_ashrrev_i32_e32 v117, 31, v116
	v_add_f32_e32 v167, v102, v209
	s_nop 0
	v_or_b32_e32 v148, 0x2020, v194
	v_ashrrev_i32_e32 v149, 31, v148
	global_load_dword v150, v192, s[12:13]
	v_add_f32_e32 v151, v100, v207
	v_lshl_add_u64 v[98:99], v[148:149], 2, s[10:11]
	global_store_dword v[98:99], v151, off
	global_load_dword v164, v192, s[12:13] offset:128
	s_nop 0
	v_lshl_add_u64 v[98:99], v[116:117], 2, s[10:11]
	v_or_b32_e32 v140, 0x2420, v194
	global_store_dword v[98:99], v165, off
	v_ashrrev_i32_e32 v141, 31, v140
	v_lshl_add_u64 v[98:99], v[140:141], 2, s[10:11]
	global_store_short v[112:113], v160, off offset:2048
	v_mul_f32_e32 v160, v185, v186
	s_nop 0
	global_load_dword v144, v192, s[12:13]
	v_add_f32_e32 v145, v101, v208
	global_store_dword v[98:99], v145, off
	global_load_dword v146, v192, s[12:13] offset:128
	v_add_f32_e32 v147, v118, v235
	v_cvt_pk_bf16_f32 v160, v160, s0
	global_store_short v[112:113], v160, off offset:2112
	s_nop 0
	v_or_b32_e32 v136, 0x2800, v194
	v_ashrrev_i32_e32 v137, 31, v136
	v_lshl_add_u64 v[98:99], v[136:137], 2, s[10:11]
	global_store_dword v[98:99], v147, off
	global_load_dword v166, v192, s[12:13]
	v_lshl_add_u64 v[116:117], v[116:117], 1, s[6:7]
	v_mul_f32_e32 v160, v185, v185
	s_nop 0
	v_or_b32_e32 v128, 0x2820, v194
	v_ashrrev_i32_e32 v129, 31, v128
	v_lshl_add_u64 v[98:99], v[128:129], 2, s[10:11]
	global_store_dword v[98:99], v167, off
	global_load_dword v168, v192, s[12:13] offset:128
	v_or_b32_e32 v98, 0x2c00, v194
	v_ashrrev_i32_e32 v99, 31, v98
	v_lshl_add_u64 v[100:101], v[98:99], 2, s[10:11]
	global_store_dword v[100:101], v169, off
	global_load_dword v170, v192, s[12:13]
	v_or_b32_e32 v100, 0x2c20, v194
	v_ashrrev_i32_e32 v101, 31, v100
	v_lshl_add_u64 v[102:103], v[100:101], 2, s[10:11]
	global_store_dword v[102:103], v171, off
	v_or_b32_e32 v102, 64, v199
	v_or_b32_e32 v118, v220, v102
	v_or_b32_e32 v130, v223, v102
	v_or_b32_e32 v132, v226, v102
	v_or_b32_e32 v134, v227, v102
	v_ashrrev_i32_e32 v119, 31, v118
	v_ashrrev_i32_e32 v131, 31, v130
	v_ashrrev_i32_e32 v133, 31, v132
	v_ashrrev_i32_e32 v135, 31, v134
	v_or_b32_e32 v138, v228, v102
	v_or_b32_e32 v142, v229, v102
	v_lshl_add_u64 v[118:119], v[118:119], 2, s[10:11]
	v_lshl_add_u64 v[130:131], v[130:131], 2, s[10:11]
	v_lshl_add_u64 v[132:133], v[132:133], 2, s[10:11]
	v_lshl_add_u64 v[134:135], v[134:135], 2, s[10:11]
	v_ashrrev_i32_e32 v139, 31, v138
	v_ashrrev_i32_e32 v143, 31, v142
	s_waitcnt vmcnt(20)
; DI bfr f2bf(float a) { return (bfr)(pack2(a, 0.f) & 0xffffu); }
; DI int crow(int reg, int h) { return (reg & 3) + 8 * (reg >> 2) + 4 * h; }
; template <bool FIRST, bool HAS_H>
; DI void phase_gemm_resid(const Params& p, const bfr* A, const bfr* Wt, const float* gnext, float* ss, char* smem) {
;     ...
; #pragma unroll
;     for (int i = 0; i < 2; ++i) {
; #pragma unroll
;       for (int qh = 0; qh < 2; ++qh) {
;         float rs[8];
; #pragma unroll
;         for (int q = 0; q < 8; ++q) rs[q] = 0.f;
; #pragma unroll
;         for (int jh = 0; jh < 2; ++jh) {
;           float xo[2][8];
; #pragma unroll
;           for (int jj = 0; jj < 2; ++jj)
; #pragma unroll
;             for (int q = 0; q < 8; ++q)
;               xo[jj][q] = xsrc[(rbase + i * 32 + crow(qh * 8 + q, 0)) * 1024 + cbase + (jh * 2 + jj) * 32];
; #pragma unroll
;           for (int q = 0; q < 8; ++q) {
;             const int o = (rbase + i * 32 + crow(qh * 8 + q, 0)) * 1024 + cbase;
; #pragma unroll
;             for (int jj = 0; jj < 2; ++jj) {
;               const int j = jh * 2 + jj;
;               const float xn = xo[jj][q] + acc[i][j][qh * 8 + q];
;               X[o + j * 32] = xn;
;               if (HAS_H) Hn[o + j * 32] = f2bf(xn * gnext[cbase + j * 32]);
;               rs[q] += xn * xn;
;             }
;           }
;         }
	v_mul_f32_e32 v103, v115, v158
	v_lshl_add_u64 v[138:139], v[138:139], 2, s[10:11]
	v_lshl_add_u64 v[142:143], v[142:143], 2, s[10:11]
	global_load_dword v172, v[202:203], off offset:256
	global_load_dword v173, v[118:119], off
	s_nop 0
	global_load_dword v130, v[130:131], off
	s_nop 0
	global_load_dword v131, v[132:133], off
	s_nop 0
	global_load_dword v132, v[134:135], off
	global_load_dword v133, v[138:139], off
	s_nop 0
	global_load_dword v134, v[142:143], off
	global_load_dword v135, v[202:203], off offset:384
	v_cvt_pk_bf16_f32 v103, v103, s0
	v_lshl_add_u64 v[118:119], v[152:153], 1, s[6:7]
	global_store_short v[118:119], v103, off
	v_or_b32_e32 v103, 0x60, v199
	v_or_b32_e32 v118, v220, v103
	v_ashrrev_i32_e32 v119, 31, v118
	v_lshl_add_u64 v[118:119], v[118:119], 2, s[10:11]
	global_load_dword v138, v[118:119], off
	s_waitcnt vmcnt(27)
	v_mul_f32_e32 v118, v159, v162
	v_cvt_pk_bf16_f32 v139, v118, s0
	v_lshl_add_u64 v[118:119], v[154:155], 1, s[6:7]
	global_store_short v[118:119], v139, off
	v_or_b32_e32 v118, v223, v103
	v_mul_f32_e32 v139, v159, v159
	v_ashrrev_i32_e32 v119, 31, v118
	v_fmac_f32_e32 v139, v115, v115
	s_waitcnt vmcnt(26)
	v_mul_f32_e32 v115, v163, v150
	v_lshl_add_u64 v[118:119], v[118:119], 2, s[10:11]
	v_cvt_pk_bf16_f32 v115, v115, s0
	global_load_dword v142, v[118:119], off
	v_lshl_add_u64 v[118:119], v[156:157], 1, s[6:7]
	global_store_short v[118:119], v115, off
	s_waitcnt vmcnt(26)
	v_mul_f32_e32 v115, v151, v164
	v_cvt_pk_bf16_f32 v115, v115, s0
	v_lshl_add_u64 v[118:119], v[148:149], 1, s[6:7]
	global_store_short v[118:119], v115, off
	v_or_b32_e32 v118, v226, v103
	v_ashrrev_i32_e32 v119, 31, v118
	v_lshl_add_u64 v[118:119], v[118:119], 2, s[10:11]
	global_load_dword v143, v[118:119], off
	s_waitcnt vmcnt(25)
	v_mul_f32_e32 v118, v165, v144
	v_cvt_pk_bf16_f32 v118, v118, s0
	global_store_short v[116:117], v118, off
	s_waitcnt vmcnt(24)
	v_mul_f32_e32 v116, v145, v146
	v_cvt_pk_bf16_f32 v118, v116, s0
	v_lshl_add_u64 v[116:117], v[140:141], 1, s[6:7]
	global_store_short v[116:117], v118, off
	v_or_b32_e32 v116, v227, v103
	v_ashrrev_i32_e32 v117, 31, v116
	v_lshl_add_u64 v[116:117], v[116:117], 2, s[10:11]
	global_load_dword v140, v[116:117], off
	s_waitcnt vmcnt(23)
	v_mul_f32_e32 v116, v147, v166
	v_cvt_pk_bf16_f32 v118, v116, s0
	v_lshl_add_u64 v[116:117], v[136:137], 1, s[6:7]
	global_store_short v[116:117], v118, off
	v_mul_f32_e32 v137, v167, v167
	v_mul_f32_e32 v141, v145, v145
	v_fmac_f32_e32 v137, v147, v147
	global_load_dword v145, v192, s[12:13] offset:128
	s_waitcnt vmcnt(23)
	v_mul_f32_e32 v116, v167, v168
	v_cvt_pk_bf16_f32 v118, v116, s0
	v_or_b32_e32 v116, v228, v103
	v_ashrrev_i32_e32 v117, 31, v116
	v_lshl_add_u64 v[116:117], v[116:117], 2, s[10:11]
	global_load_dword v136, v[116:117], off
	v_lshl_add_u64 v[116:117], v[128:129], 1, s[6:7]
	global_store_short v[116:117], v118, off
	v_or_b32_e32 v118, v229, v103
	s_waitcnt vmcnt(23)
	v_mul_f32_e32 v116, v169, v170
	v_ashrrev_i32_e32 v119, 31, v118
	v_cvt_pk_bf16_f32 v144, v116, s0
	v_or_b32_e32 v116, v230, v102
	v_lshl_add_u64 v[118:119], v[118:119], 2, s[10:11]
	global_load_dword v146, v[118:119], off
	v_ashrrev_i32_e32 v117, 31, v116
	v_or_b32_e32 v118, v230, v103
	v_lshl_add_u64 v[116:117], v[116:117], 2, s[10:11]
	v_ashrrev_i32_e32 v119, 31, v118
	v_lshl_add_u64 v[118:119], v[118:119], 2, s[10:11]
	global_load_dword v147, v[116:117], off
	global_load_dword v148, v[118:119], off
	v_mul_f32_e32 v115, v151, v151
	v_fmac_f32_e32 v115, v163, v163
	s_waitcnt vmcnt(24)
	v_add_f32_e32 v149, v80, v172
	global_store_dword v[200:201], v149, off offset:256
	v_or_b32_e32 v80, 0x440, v194
	global_load_dword v150, v192, s[12:13] offset:256
	s_waitcnt vmcnt(25)
	v_add_f32_e32 v152, v81, v173
	v_ashrrev_i32_e32 v81, 31, v80
	v_lshl_add_u64 v[80:81], v[80:81], 2, s[10:11]
	s_waitcnt vmcnt(19)
	v_add_f32_e32 v135, v64, v135
	v_or_b32_e32 v64, 0x460, v194
	global_store_dword v[200:201], v135, off offset:384
	global_load_dword v151, v192, s[12:13] offset:384
	v_add_f32_e32 v155, v82, v130
	global_store_dword v[80:81], v152, off
	global_load_dword v153, v192, s[12:13] offset:256
	v_or_b32_e32 v82, 0xc40, v194
	s_waitcnt vmcnt(21)
	v_add_f32_e32 v138, v65, v138
	v_ashrrev_i32_e32 v65, 31, v64
	v_lshl_add_u64 v[64:65], v[64:65], 2, s[10:11]
	global_store_dword v[64:65], v138, off
	v_or_b32_e32 v64, 0x840, v194
	v_ashrrev_i32_e32 v65, 31, v64
	v_lshl_add_u64 v[80:81], v[64:65], 2, s[10:11]
	global_load_dword v154, v192, s[12:13] offset:384
	v_add_f32_e32 v158, v83, v131
	global_store_dword v[80:81], v155, off
	v_or_b32_e32 v80, 0x860, v194
	v_ashrrev_i32_e32 v81, 31, v80
	global_load_dword v156, v192, s[12:13] offset:256
	s_waitcnt vmcnt(23)
	v_add_f32_e32 v142, v66, v142
	v_lshl_add_u64 v[116:117], v[80:81], 2, s[10:11]
	v_ashrrev_i32_e32 v83, 31, v82
	v_or_b32_e32 v66, 0xc60, v194
	global_store_dword v[116:117], v142, off
	v_lshl_add_u64 v[116:117], v[82:83], 2, s[10:11]
	global_load_dword v157, v192, s[12:13] offset:384
	v_add_f32_e32 v163, v84, v132
	global_store_dword v[116:117], v158, off
	s_waitcnt vmcnt(23)
	v_add_f32_e32 v143, v67, v143
	v_ashrrev_i32_e32 v67, 31, v66
	v_lshl_add_u64 v[116:117], v[66:67], 2, s[10:11]
	global_load_dword v159, v192, s[12:13] offset:256
	v_or_b32_e32 v84, 0x2440, v194
	global_store_dword v[116:117], v143, off
	v_or_b32_e32 v116, 0x2040, v194
	v_ashrrev_i32_e32 v117, 31, v116
	v_lshl_add_u64 v[118:119], v[116:117], 2, s[10:11]
	global_load_dword v162, v192, s[12:13] offset:384
	v_add_f32_e32 v166, v85, v133
	global_store_dword v[118:119], v163, off
	v_or_b32_e32 v118, 0x2060, v194
	v_ashrrev_i32_e32 v119, 31, v118
	global_load_dword v164, v192, s[12:13] offset:256
	s_waitcnt vmcnt(25)
; DI bfr f2bf(float a) { return (bfr)(pack2(a, 0.f) & 0xffffu); }
; DI int crow(int reg, int h) { return (reg & 3) + 8 * (reg >> 2) + 4 * h; }
; template <bool FIRST, bool HAS_H>
; DI void phase_gemm_resid(const Params& p, const bfr* A, const bfr* Wt, const float* gnext, float* ss, char* smem) {
;     ...
;         for (int jh = 0; jh < 2; ++jh) {
;           float xo[2][8];
; #pragma unroll
;           for (int jj = 0; jj < 2; ++jj)
; #pragma unroll
;             for (int q = 0; q < 8; ++q)
;               xo[jj][q] = xsrc[(rbase + i * 32 + crow(qh * 8 + q, 0)) * 1024 + cbase + (jh * 2 + jj) * 32];
; #pragma unroll
;           for (int q = 0; q < 8; ++q) {
;             const int o = (rbase + i * 32 + crow(qh * 8 + q, 0)) * 1024 + cbase;
; #pragma unroll
;             for (int jj = 0; jj < 2; ++jj) {
;               const int j = jh * 2 + jj;
;               const float xn = xo[jj][q] + acc[i][j][qh * 8 + q];
;               X[o + j * 32] = xn;
;               if (HAS_H) Hn[o + j * 32] = f2bf(xn * gnext[cbase + j * 32]);
;               rs[q] += xn * xn;
;             }
;           }
;         }
	v_add_f32_e32 v140, v68, v140
	v_lshl_add_u64 v[128:129], v[118:119], 2, s[10:11]
	v_ashrrev_i32_e32 v85, 31, v84
	v_or_b32_e32 v68, 0x2460, v194
	global_store_dword v[128:129], v140, off
	v_lshl_add_u64 v[128:129], v[84:85], 2, s[10:11]
	v_fmac_f32_e32 v141, v165, v165
	global_load_dword v165, v192, s[12:13] offset:384
	v_add_f32_e32 v134, v86, v134
	global_store_dword v[128:129], v166, off
	s_waitcnt vmcnt(25)
	v_add_f32_e32 v136, v69, v136
	v_ashrrev_i32_e32 v69, 31, v68
	v_lshl_add_u64 v[128:129], v[68:69], 2, s[10:11]
	global_load_dword v167, v192, s[12:13] offset:256
	v_or_b32_e32 v86, 0x2c40, v194
	global_store_dword v[128:129], v136, off
	v_or_b32_e32 v128, 0x2840, v194
	v_ashrrev_i32_e32 v129, 31, v128
	v_lshl_add_u64 v[130:131], v[128:129], 2, s[10:11]
	global_load_dword v168, v192, s[12:13] offset:384
	s_waitcnt vmcnt(26)
	v_add_f32_e32 v146, v70, v146
	global_store_dword v[130:131], v134, off
	v_or_b32_e32 v130, 0x2860, v194
	v_ashrrev_i32_e32 v131, 31, v130
	global_load_dword v170, v192, s[12:13] offset:256
	v_lshl_add_u64 v[132:133], v[130:131], 2, s[10:11]
	global_store_dword v[132:133], v146, off
	s_waitcnt vmcnt(28)
	v_add_f32_e32 v147, v87, v147
	v_ashrrev_i32_e32 v87, 31, v86
	global_load_dword v172, v192, s[12:13] offset:384
	v_lshl_add_u64 v[132:133], v[86:87], 2, s[10:11]
	v_or_b32_e32 v70, 0x2c60, v194
	global_store_dword v[132:133], v147, off
	s_waitcnt vmcnt(29)
	v_add_f32_e32 v148, v71, v148
	v_ashrrev_i32_e32 v71, 31, v70
	global_load_dword v173, v192, s[12:13] offset:256
	v_lshl_add_u64 v[132:133], v[70:71], 2, s[10:11]
	global_store_dword v[132:133], v148, off
	global_load_dword v132, v192, s[12:13] offset:384
	v_lshl_add_u64 v[98:99], v[98:99], 1, s[6:7]
	global_store_short v[98:99], v144, off
	v_mul_f32_e32 v98, v171, v145
	v_cvt_pk_bf16_f32 v133, v98, s0
	v_lshl_add_u64 v[98:99], v[100:101], 1, s[6:7]
	global_store_short v[98:99], v133, off
	s_waitcnt vmcnt(32)
	v_mul_f32_e32 v99, v149, v150
	v_cvt_pk_bf16_f32 v99, v99, s0
	global_store_short v[112:113], v99, off offset:128
	s_waitcnt vmcnt(31)
	v_mul_f32_e32 v99, v135, v151
	v_cvt_pk_bf16_f32 v99, v99, s0
	global_store_short v[112:113], v99, off offset:192
	s_waitcnt vmcnt(30)
	v_mul_f32_e32 v99, v152, v153
	v_cvt_pk_bf16_f32 v99, v99, s0
	global_store_short v[112:113], v99, off offset:2176
	s_waitcnt vmcnt(29)
	v_mul_f32_e32 v99, v138, v154
	v_cvt_pk_bf16_f32 v99, v99, s0
	global_store_short v[112:113], v99, off offset:2240
	s_waitcnt vmcnt(28)
	v_mul_f32_e32 v99, v155, v156
	v_cvt_pk_bf16_f32 v99, v99, s0
	v_lshl_add_u64 v[64:65], v[64:65], 1, s[6:7]
	global_store_short v[64:65], v99, off
	v_mul_f32_e32 v98, v171, v171
	s_waitcnt vmcnt(27)
	v_mul_f32_e32 v64, v142, v157
	v_cvt_pk_bf16_f32 v99, v64, s0
	v_lshl_add_u64 v[64:65], v[80:81], 1, s[6:7]
	global_store_short v[64:65], v99, off
	v_fmac_f32_e32 v114, v211, v211
	v_fmac_f32_e32 v160, v189, v189
	s_waitcnt vmcnt(26)
	v_mul_f32_e32 v64, v158, v159
	v_cvt_pk_bf16_f32 v80, v64, s0
	v_lshl_add_u64 v[64:65], v[82:83], 1, s[6:7]
	global_store_short v[64:65], v80, off
	v_fmac_f32_e32 v161, v176, v176
	v_fmac_f32_e32 v98, v169, v169
	s_waitcnt vmcnt(25)
	v_mul_f32_e32 v64, v143, v162
	v_cvt_pk_bf16_f32 v80, v64, s0
	v_lshl_add_u64 v[64:65], v[66:67], 1, s[6:7]
	global_store_short v[64:65], v80, off
	v_fmac_f32_e32 v114, v149, v149
	s_waitcnt vmcnt(24)
	v_mul_f32_e32 v64, v163, v164
	v_cvt_pk_bf16_f32 v66, v64, s0
	v_lshl_add_u64 v[64:65], v[116:117], 1, s[6:7]
	global_store_short v[64:65], v66, off
	v_fmac_f32_e32 v160, v152, v152
	v_fmac_f32_e32 v161, v155, v155
	v_fmac_f32_e32 v139, v158, v158
	v_fmac_f32_e32 v115, v163, v163
	s_waitcnt vmcnt(23)
	v_mul_f32_e32 v64, v140, v165
	v_cvt_pk_bf16_f32 v66, v64, s0
	v_lshl_add_u64 v[64:65], v[118:119], 1, s[6:7]
	global_store_short v[64:65], v66, off
	v_fmac_f32_e32 v141, v166, v166
	v_fmac_f32_e32 v137, v134, v134
	s_waitcnt vmcnt(22)
	v_mul_f32_e32 v64, v166, v167
	v_cvt_pk_bf16_f32 v66, v64, s0
	v_lshl_add_u64 v[64:65], v[84:85], 1, s[6:7]
	global_store_short v[64:65], v66, off
	v_fmac_f32_e32 v98, v147, v147
	v_fmac_f32_e32 v114, v135, v135
	s_waitcnt vmcnt(21)
	v_mul_f32_e32 v64, v136, v168
	v_cvt_pk_bf16_f32 v66, v64, s0
	v_lshl_add_u64 v[64:65], v[68:69], 1, s[6:7]
	global_store_short v[64:65], v66, off
	v_fmac_f32_e32 v160, v138, v138
	s_waitcnt vmcnt(20)
	v_mul_f32_e32 v64, v134, v170
	v_cvt_pk_bf16_f32 v66, v64, s0
	v_lshl_add_u64 v[64:65], v[128:129], 1, s[6:7]
	global_store_short v[64:65], v66, off
	v_fmac_f32_e32 v161, v142, v142
	s_waitcnt vmcnt(19)
	v_mul_f32_e32 v64, v146, v172
	v_cvt_pk_bf16_f32 v66, v64, s0
	v_lshl_add_u64 v[64:65], v[130:131], 1, s[6:7]
	global_store_short v[64:65], v66, off
	v_fmac_f32_e32 v139, v143, v143
	v_fmac_f32_e32 v115, v140, v140
	s_waitcnt vmcnt(18)
; DI bfr f2bf(float a) { return (bfr)(pack2(a, 0.f) & 0xffffu); }
; #define DPPF(v, ctrl, rmask) __builtin_bit_cast(float, __builtin_amdgcn_update_dpp(0, __builtin_bit_cast(int, (v)), (ctrl), (rmask), 0xf, false))
; DI int crow(int reg, int h) { return (reg & 3) + 8 * (reg >> 2) + 4 * h; }
; DI float row16_sum(float v) {
;   v += DPPF(v, 0xB1, 0xf);
;   v += DPPF(v, 0x4E, 0xf);
;   v += DPPF(v, 0x141, 0xf);
;   v += DPPF(v, 0x140, 0xf);
;   return v;
; }
; DI float half32_sum_hi(float v) {
;   v = row16_sum(v);
;   v += DPPF(v, 0x142, 0xa);
;   return v;
; template <bool FIRST, bool HAS_H>
; DI void phase_gemm_resid(const Params& p, const bfr* A, const bfr* Wt, const float* gnext, float* ss, char* smem) {
;     ...
;           for (int q = 0; q < 8; ++q) {
;             const int o = (rbase + i * 32 + crow(qh * 8 + q, 0)) * 1024 + cbase;
; #pragma unroll
;             for (int jj = 0; jj < 2; ++jj) {
;               const int j = jh * 2 + jj;
;               const float xn = xo[jj][q] + acc[i][j][qh * 8 + q];
;               X[o + j * 32] = xn;
;               if (HAS_H) Hn[o + j * 32] = f2bf(xn * gnext[cbase + j * 32]);
;               rs[q] += xn * xn;
;             }
;           }
;         }
; #pragma unroll
;         for (int q = 0; q < 8; ++q) rs[q] = half32_sum_hi(rs[q]);
;         if (r == 31) {
; #pragma unroll
;           for (int q = 0; q < 8; ++q) unsafeAtomicAdd(ss + rbase + i * 32 + crow(qh * 8 + q, 0), rs[q]);
;         }
	v_mul_f32_e32 v64, v147, v173
	v_cvt_pk_bf16_f32 v66, v64, s0
	v_lshl_add_u64 v[64:65], v[86:87], 1, s[6:7]
	global_store_short v[64:65], v66, off
	s_waitcnt vmcnt(17)
	v_mul_f32_e32 v64, v148, v132
	v_fmac_f32_e32 v141, v136, v136
	v_fmac_f32_e32 v137, v146, v146
	v_cvt_pk_bf16_f32 v66, v64, s0
	v_lshl_add_u64 v[64:65], v[70:71], 1, s[6:7]
	v_fmac_f32_e32 v98, v148, v148
	global_store_short v[64:65], v66, off
	v_add_f32_dpp v64, v114, v114 quad_perm:[1,0,3,2] row_mask:0xf bank_mask:0xf bound_ctrl:1
	v_add_f32_dpp v66, v160, v160 quad_perm:[1,0,3,2] row_mask:0xf bank_mask:0xf bound_ctrl:1
	v_add_f32_dpp v68, v161, v161 quad_perm:[1,0,3,2] row_mask:0xf bank_mask:0xf bound_ctrl:1
	v_add_f32_dpp v70, v139, v139 quad_perm:[1,0,3,2] row_mask:0xf bank_mask:0xf bound_ctrl:1
	v_add_f32_dpp v80, v115, v115 quad_perm:[1,0,3,2] row_mask:0xf bank_mask:0xf bound_ctrl:1
	v_add_f32_dpp v82, v141, v141 quad_perm:[1,0,3,2] row_mask:0xf bank_mask:0xf bound_ctrl:1
	v_add_f32_dpp v84, v137, v137 quad_perm:[1,0,3,2] row_mask:0xf bank_mask:0xf bound_ctrl:1
	v_add_f32_dpp v86, v98, v98 quad_perm:[1,0,3,2] row_mask:0xf bank_mask:0xf bound_ctrl:1
	v_add_f32_dpp v64, v64, v64 quad_perm:[2,3,0,1] row_mask:0xf bank_mask:0xf bound_ctrl:1
	v_add_f32_dpp v66, v66, v66 quad_perm:[2,3,0,1] row_mask:0xf bank_mask:0xf bound_ctrl:1
	v_add_f32_dpp v68, v68, v68 quad_perm:[2,3,0,1] row_mask:0xf bank_mask:0xf bound_ctrl:1
	v_add_f32_dpp v70, v70, v70 quad_perm:[2,3,0,1] row_mask:0xf bank_mask:0xf bound_ctrl:1
	v_add_f32_dpp v80, v80, v80 quad_perm:[2,3,0,1] row_mask:0xf bank_mask:0xf bound_ctrl:1
	v_add_f32_dpp v82, v82, v82 quad_perm:[2,3,0,1] row_mask:0xf bank_mask:0xf bound_ctrl:1
	v_add_f32_dpp v84, v84, v84 quad_perm:[2,3,0,1] row_mask:0xf bank_mask:0xf bound_ctrl:1
	v_add_f32_dpp v86, v86, v86 quad_perm:[2,3,0,1] row_mask:0xf bank_mask:0xf bound_ctrl:1
	v_add_f32_dpp v64, v64, v64 row_half_mirror row_mask:0xf bank_mask:0xf bound_ctrl:1
	v_add_f32_dpp v66, v66, v66 row_half_mirror row_mask:0xf bank_mask:0xf bound_ctrl:1
	v_add_f32_dpp v68, v68, v68 row_half_mirror row_mask:0xf bank_mask:0xf bound_ctrl:1
	v_add_f32_dpp v70, v70, v70 row_half_mirror row_mask:0xf bank_mask:0xf bound_ctrl:1
	v_add_f32_dpp v80, v80, v80 row_half_mirror row_mask:0xf bank_mask:0xf bound_ctrl:1
	v_add_f32_dpp v82, v82, v82 row_half_mirror row_mask:0xf bank_mask:0xf bound_ctrl:1
	v_add_f32_dpp v84, v84, v84 row_half_mirror row_mask:0xf bank_mask:0xf bound_ctrl:1
	v_add_f32_dpp v86, v86, v86 row_half_mirror row_mask:0xf bank_mask:0xf bound_ctrl:1
	v_add_f32_dpp v64, v64, v64 row_mirror row_mask:0xf bank_mask:0xf bound_ctrl:1
	v_mov_b32_e32 v65, 0
	v_add_f32_dpp v66, v66, v66 row_mirror row_mask:0xf bank_mask:0xf bound_ctrl:1
	v_mov_b32_e32 v67, 0
	v_add_f32_dpp v68, v68, v68 row_mirror row_mask:0xf bank_mask:0xf bound_ctrl:1
	v_mov_b32_e32 v69, 0
	v_add_f32_dpp v70, v70, v70 row_mirror row_mask:0xf bank_mask:0xf bound_ctrl:1
	v_mov_b32_e32 v71, 0
	v_add_f32_dpp v80, v80, v80 row_mirror row_mask:0xf bank_mask:0xf bound_ctrl:1
	v_mov_b32_e32 v81, 0
	v_add_f32_dpp v82, v82, v82 row_mirror row_mask:0xf bank_mask:0xf bound_ctrl:1
	v_mov_b32_e32 v83, 0
	v_add_f32_dpp v84, v84, v84 row_mirror row_mask:0xf bank_mask:0xf bound_ctrl:1
	v_mov_b32_e32 v85, 0
	v_add_f32_dpp v86, v86, v86 row_mirror row_mask:0xf bank_mask:0xf bound_ctrl:1
	v_mov_b32_e32 v87, 0
	v_mov_b32_dpp v65, v64 row_bcast:15 row_mask:0xa bank_mask:0xf
	v_mov_b32_dpp v67, v66 row_bcast:15 row_mask:0xa bank_mask:0xf
	v_mov_b32_dpp v69, v68 row_bcast:15 row_mask:0xa bank_mask:0xf
	v_mov_b32_dpp v71, v70 row_bcast:15 row_mask:0xa bank_mask:0xf
	v_mov_b32_dpp v81, v80 row_bcast:15 row_mask:0xa bank_mask:0xf
	v_mov_b32_dpp v83, v82 row_bcast:15 row_mask:0xa bank_mask:0xf
	v_mov_b32_dpp v85, v84 row_bcast:15 row_mask:0xa bank_mask:0xf
	v_mov_b32_dpp v87, v86 row_bcast:15 row_mask:0xa bank_mask:0xf
	s_and_saveexec_b64 s[4:5], vcc
	s_cbranch_execz .LBB0_1479
	v_add_f32_e32 v64, v64, v65
	v_add_f32_e32 v86, v86, v87
	v_add_f32_e32 v84, v84, v85
	v_add_f32_e32 v82, v82, v83
	v_add_f32_e32 v80, v80, v81
	v_add_f32_e32 v70, v70, v71
	v_add_f32_e32 v68, v68, v69
	v_add_f32_e32 v66, v66, v67
	global_atomic_add_f32 v[96:97], v64, off
	global_atomic_add_f32 v[96:97], v66, off offset:4
	global_atomic_add_f32 v[96:97], v68, off offset:8
	global_atomic_add_f32 v[96:97], v70, off offset:12
	global_atomic_add_f32 v[96:97], v80, off offset:32
	global_atomic_add_f32 v[96:97], v82, off offset:36
	global_atomic_add_f32 v[96:97], v84, off offset:40
	global_atomic_add_f32 v[96:97], v86, off offset:44

; #define MFMA32(a, b, c) __builtin_amdgcn_mfma_f32_32x32x16_bf16((a), (b), (c), 0, 0, 0)
; #define GA_LOAD(pr_) do { _Pragma("unroll") for (int i = 0; i < 4; ++i) ra[i] = *(const u32x4*)(Ab + (i * 32) * lda + (pr_) * 64); } while (0)
; #define GB_LOAD(kt_) do { const bfr* bk_ = Bb + (kt_) * NB * 32; \
;     _Pragma("unroll") for (int i = 0; i < 4; ++i) rb[i] = *(const u32x4*)(bk_ + (i * 64) * 32); } while (0)
; #define G_STORE(kt_) do { bfr* as_ = S0 + ((kt_) & 1) * GSTAGE; bfr* bs_ = as_ + 128 * 40; \
;     if (apar == ((kt_) & 1)) { _Pragma("unroll") for (int i = 0; i < 4; ++i) *(u32x4*)(as_ + asoff + i * 32 * 40) = ra[i]; } \
;     _Pragma("unroll") for (int i = 0; i < 4; ++i) *(u32x4*)(bs_ + bsoff + i * 64 * 40) = rb[i]; } while (0)
; template <int lda>
; DI void gemm_mainloop(const bfr* __restrict__ A, const bfr* __restrict__ Bt, int NB, int K, int m0, int n0, char* smem, f32x16 (&acc)[2][4]) {
;     ...
;   GA_LOAD(0);
;   GB_LOAD(0);
;   G_STORE(0);
;   GB_LOAD(1);
;   __syncthreads();
;   for (int kt = 0; kt < nk; ++kt) {
;     if (kt + 1 < nk) G_STORE(kt + 1);
;     if (kt + 2 < nk) {
;       GB_LOAD(kt + 2);
;       if ((kt & 1) == 0) GA_LOAD((kt >> 1) + 1);
;     }
;     const bfr* As = S0 + (kt & 1) * GSTAGE;
;     const bfr* Bs = As + 128 * 40;
; #pragma unroll
;     for (int ks = 0; ks < 2; ++ks) {
;       bf16x8 af[2], bfg[4];
; #pragma unroll
;       for (int i = 0; i < 2; ++i) af[i] = *(const bf16x8*)(As + (wr * 64 + i * 32 + r) * 40 + ks * 16 + hl * 8);
; #pragma unroll
;       for (int j = 0; j < 4; ++j) bfg[j] = *(const bf16x8*)(Bs + (wc * 128 + j * 32 + r) * 40 + ks * 16 + hl * 8);
; #pragma unroll
;       for (int i = 0; i < 2; ++i)
; #pragma unroll
;         for (int j = 0; j < 4; ++j) acc[i][j] = MFMA32(af[i], bfg[j], acc[i][j]);
;     }
;     __syncthreads();
.Lp19_loop:
	s_waitcnt vmcnt(6)
	s_barrier
	s_mul_i32 s74, s71, 0x6000
	s_add_u32 s75, s74, 0x2000
	s_cmp_eq_u32 s71, 2
	s_cselect_b32 s75, 0x10000, s75
	v_add_u32_e32 v184, s74, v179
	v_add_u32_e32 v186, s75, v182
	v_add_u32_e32 v185, s74, v180
	v_add_u32_e32 v187, s75, v183
	ds_read_b128 v[128:131], v184
	ds_read_b128 v[144:147], v186
	ds_read_b128 v[148:151], v186 offset:2048
	ds_read_b128 v[152:155], v186 offset:4096
	ds_read_b128 v[156:159], v186 offset:6144
	ds_read_b128 v[132:135], v184 offset:2048
	ds_read_b128 v[136:139], v185
	ds_read_b128 v[160:163], v187
	ds_read_b128 v[164:167], v187 offset:2048
	ds_read_b128 v[168:171], v187 offset:4096
	ds_read_b128 v[172:175], v187 offset:6144
	ds_read_b128 v[140:143], v185 offset:2048
	s_add_u32 s71, s71, 1
	s_cmp_eq_u32 s71, 3
	s_cselect_b32 s71, 0, s71
	s_waitcnt lgkmcnt(10)
	v_mfma_f32_32x32x16_bf16 v[112:127], v[128:131], v[144:147], v[112:127]
	s_mul_i32 s74, s70, 0x6000
	s_add_u32 s75, s74, s68
	s_mov_b32 m0, s75
	s_add_u32 s76, s74, 0x2000
	s_cmp_eq_u32 s70, 2
	s_cselect_b32 s76, 0x10000, s76
	global_load_lds_dwordx4 v176, s[64:65]
	s_waitcnt lgkmcnt(9)
	v_mfma_f32_32x32x16_bf16 v[96:111], v[128:131], v[148:151], v[96:111]
	s_add_u32 m0, s75, 0x400
	s_add_u32 s76, s76, s69
	global_load_lds_dwordx4 v177, s[64:65]
	s_waitcnt lgkmcnt(8)
	v_mfma_f32_32x32x16_bf16 v[80:95], v[128:131], v[152:155], v[80:95]
	s_mov_b32 m0, s76
	s_add_u32 s64, s64, 64
	s_addc_u32 s65, s65, 0
	global_load_lds_dwordx4 v178, s[66:67]
	s_waitcnt lgkmcnt(7)
	v_mfma_f32_32x32x16_bf16 v[64:79], v[128:131], v[156:159], v[64:79]
	global_load_lds_dwordx4 v178, s[66:67] offset:1024
	s_waitcnt lgkmcnt(6)
	v_mfma_f32_32x32x16_bf16 v[48:63], v[132:135], v[144:147], v[48:63]
	global_load_lds_dwordx4 v178, s[66:67] offset:2048
	v_mfma_f32_32x32x16_bf16 v[32:47], v[132:135], v[148:151], v[32:47]
	global_load_lds_dwordx4 v178, s[66:67] offset:3072
	s_add_u32 s66, s66, 0x10000
	s_addc_u32 s67, s67, 0
	v_mfma_f32_32x32x16_bf16 v[16:31], v[132:135], v[152:155], v[16:31]
	s_add_u32 s70, s70, 1
	s_cmp_eq_u32 s70, 3
	s_cselect_b32 s70, 0, s70
	v_mfma_f32_32x32x16_bf16 v[0:15], v[132:135], v[156:159], v[0:15]
	s_waitcnt lgkmcnt(4)
	v_mfma_f32_32x32x16_bf16 v[112:127], v[136:139], v[160:163], v[112:127]
	s_waitcnt lgkmcnt(3)
	v_mfma_f32_32x32x16_bf16 v[96:111], v[136:139], v[164:167], v[96:111]
	s_waitcnt lgkmcnt(2)
	v_mfma_f32_32x32x16_bf16 v[80:95], v[136:139], v[168:171], v[80:95]
	s_waitcnt lgkmcnt(1)
	v_mfma_f32_32x32x16_bf16 v[64:79], v[136:139], v[172:175], v[64:79]
	s_waitcnt lgkmcnt(0)
	v_mfma_f32_32x32x16_bf16 v[48:63], v[140:143], v[160:163], v[48:63]
	v_mfma_f32_32x32x16_bf16 v[32:47], v[140:143], v[164:167], v[32:47]
	v_mfma_f32_32x32x16_bf16 v[16:31], v[140:143], v[168:171], v[16:31]
	v_mfma_f32_32x32x16_bf16 v[0:15], v[140:143], v[172:175], v[0:15]
	s_add_u32 s72, s72, 1
	s_cmp_lt_u32 s72, 30
	s_cbranch_scc1 .Lp19_loop
	s_waitcnt vmcnt(6)
	s_barrier
	s_mul_i32 s74, s71, 0x6000
	s_add_u32 s75, s74, 0x2000
	s_cmp_eq_u32 s71, 2
	s_cselect_b32 s75, 0x10000, s75
	v_add_u32_e32 v184, s74, v179
	v_add_u32_e32 v186, s75, v182
	v_add_u32_e32 v185, s74, v180
	v_add_u32_e32 v187, s75, v183
	ds_read_b128 v[128:131], v184
	ds_read_b128 v[144:147], v186
	ds_read_b128 v[148:151], v186 offset:2048
	ds_read_b128 v[152:155], v186 offset:4096
	ds_read_b128 v[156:159], v186 offset:6144
	ds_read_b128 v[132:135], v184 offset:2048
	ds_read_b128 v[136:139], v185
	ds_read_b128 v[160:163], v187
	ds_read_b128 v[164:167], v187 offset:2048
	ds_read_b128 v[168:171], v187 offset:4096
	ds_read_b128 v[172:175], v187 offset:6144
	ds_read_b128 v[140:143], v185 offset:2048
	s_add_u32 s71, s71, 1
	s_cmp_eq_u32 s71, 3
	s_cselect_b32 s71, 0, s71
	s_waitcnt lgkmcnt(10)
	v_mfma_f32_32x32x16_bf16 v[112:127], v[128:131], v[144:147], v[112:127]
	s_waitcnt lgkmcnt(9)
	v_mfma_f32_32x32x16_bf16 v[96:111], v[128:131], v[148:151], v[96:111]
	s_waitcnt lgkmcnt(8)
	v_mfma_f32_32x32x16_bf16 v[80:95], v[128:131], v[152:155], v[80:95]
	s_waitcnt lgkmcnt(7)
	v_mfma_f32_32x32x16_bf16 v[64:79], v[128:131], v[156:159], v[64:79]
	s_waitcnt lgkmcnt(6)
	v_mfma_f32_32x32x16_bf16 v[48:63], v[132:135], v[144:147], v[48:63]
	v_mfma_f32_32x32x16_bf16 v[32:47], v[132:135], v[148:151], v[32:47]
	v_mfma_f32_32x32x16_bf16 v[16:31], v[132:135], v[152:155], v[16:31]
	v_mfma_f32_32x32x16_bf16 v[0:15], v[132:135], v[156:159], v[0:15]
	s_waitcnt lgkmcnt(4)
	v_mfma_f32_32x32x16_bf16 v[112:127], v[136:139], v[160:163], v[112:127]
	s_waitcnt lgkmcnt(3)
	v_mfma_f32_32x32x16_bf16 v[96:111], v[136:139], v[164:167], v[96:111]
	s_waitcnt lgkmcnt(2)
	v_mfma_f32_32x32x16_bf16 v[80:95], v[136:139], v[168:171], v[80:95]
	s_waitcnt lgkmcnt(1)
	v_mfma_f32_32x32x16_bf16 v[64:79], v[136:139], v[172:175], v[64:79]
	s_waitcnt lgkmcnt(0)
	v_mfma_f32_32x32x16_bf16 v[48:63], v[140:143], v[160:163], v[48:63]
	v_mfma_f32_32x32x16_bf16 v[32:47], v[140:143], v[164:167], v[32:47]
	v_mfma_f32_32x32x16_bf16 v[16:31], v[140:143], v[168:171], v[16:31]
	v_mfma_f32_32x32x16_bf16 v[0:15], v[140:143], v[172:175], v[0:15]
	s_waitcnt vmcnt(0)
	s_barrier
; #define MFMA32(a, b, c) __builtin_amdgcn_mfma_f32_32x32x16_bf16((a), (b), (c), 0, 0, 0)
; DI int crow(int reg, int h) { return (reg & 3) + 8 * (reg >> 2) + 4 * h; }
; template <int lda>
; DI void gemm_mainloop(const bfr* __restrict__ A, const bfr* __restrict__ Bt, int NB, int K, int m0, int n0, char* smem, f32x16 (&acc)[2][4]) {
;     ...
;     const bfr* As = S0 + (kt & 1) * GSTAGE;
;     const bfr* Bs = As + 128 * 40;
; #pragma unroll
;     for (int ks = 0; ks < 2; ++ks) {
;       bf16x8 af[2], bfg[4];
; #pragma unroll
;       for (int i = 0; i < 2; ++i) af[i] = *(const bf16x8*)(As + (wr * 64 + i * 32 + r) * 40 + ks * 16 + hl * 8);
; #pragma unroll
;       for (int j = 0; j < 4; ++j) bfg[j] = *(const bf16x8*)(Bs + (wc * 128 + j * 32 + r) * 40 + ks * 16 + hl * 8);
; #pragma unroll
;       for (int i = 0; i < 2; ++i)
; #pragma unroll
;         for (int j = 0; j < 4; ++j) acc[i][j] = MFMA32(af[i], bfg[j], acc[i][j]);
;     }
; template <bool FIRST, bool HAS_H>
; DI void phase_gemm_resid(const Params& p, const bfr* A, const bfr* Wt, const float* gnext, float* ss, char* smem) {
;     ...
;     int tid2 = threadIdx.x;
;     asm volatile("" : "+v"(tid2));
;     const int lane = tid2 & 63, wid = tid2 >> 6, wr = wid >> 1, wc = wid & 1, r = lane & 31, hl = lane >> 5;
;     const float* xsrc = FIRST ? p.x_prompt : X;
;     const int rbase = m0 + wr * 64 + 4 * hl, cbase = n0 + wc * 128 + r;
; #pragma unroll
;     for (int i = 0; i < 2; ++i) {
; #pragma unroll
;       for (int qh = 0; qh < 2; ++qh) {
;         float rs[8];
; #pragma unroll
;         for (int q = 0; q < 8; ++q) rs[q] = 0.f;
; #pragma unroll
;         for (int jh = 0; jh < 2; ++jh) {
;           float xo[2][8];
; #pragma unroll
;           for (int jj = 0; jj < 2; ++jj)
; #pragma unroll
;             for (int q = 0; q < 8; ++q)
;               xo[jj][q] = xsrc[(rbase + i * 32 + crow(qh * 8 + q, 0)) * 1024 + cbase + (jh * 2 + jj) * 32];
	s_mul_i32 s74, s71, 0x6000
	s_add_u32 s75, s74, 0x2000
	s_cmp_eq_u32 s71, 2
	s_cselect_b32 s75, 0x10000, s75
	v_add_u32_e32 v184, s74, v179
	v_add_u32_e32 v186, s75, v182
	v_add_u32_e32 v185, s74, v180
	v_add_u32_e32 v187, s75, v183
	ds_read_b128 v[128:131], v184
	ds_read_b128 v[144:147], v186
	ds_read_b128 v[148:151], v186 offset:2048
	ds_read_b128 v[152:155], v186 offset:4096
	ds_read_b128 v[156:159], v186 offset:6144
	ds_read_b128 v[132:135], v184 offset:2048
	ds_read_b128 v[136:139], v185
	ds_read_b128 v[160:163], v187
	ds_read_b128 v[164:167], v187 offset:2048
	ds_read_b128 v[168:171], v187 offset:4096
	ds_read_b128 v[172:175], v187 offset:6144
	ds_read_b128 v[140:143], v185 offset:2048
	s_add_u32 s71, s71, 1
	s_cmp_eq_u32 s71, 3
	s_cselect_b32 s71, 0, s71
	s_waitcnt lgkmcnt(10)
	v_mfma_f32_32x32x16_bf16 v[112:127], v[128:131], v[144:147], v[112:127]
	s_waitcnt lgkmcnt(9)
	v_mfma_f32_32x32x16_bf16 v[96:111], v[128:131], v[148:151], v[96:111]
	s_waitcnt lgkmcnt(8)
	v_mfma_f32_32x32x16_bf16 v[80:95], v[128:131], v[152:155], v[80:95]
	s_waitcnt lgkmcnt(7)
	v_mfma_f32_32x32x16_bf16 v[64:79], v[128:131], v[156:159], v[64:79]
	s_waitcnt lgkmcnt(6)
	v_mfma_f32_32x32x16_bf16 v[48:63], v[132:135], v[144:147], v[48:63]
	v_mfma_f32_32x32x16_bf16 v[32:47], v[132:135], v[148:151], v[32:47]
	v_mfma_f32_32x32x16_bf16 v[16:31], v[132:135], v[152:155], v[16:31]
	v_mfma_f32_32x32x16_bf16 v[0:15], v[132:135], v[156:159], v[0:15]
	s_waitcnt lgkmcnt(4)
	v_mfma_f32_32x32x16_bf16 v[112:127], v[136:139], v[160:163], v[112:127]
	s_waitcnt lgkmcnt(3)
	v_mfma_f32_32x32x16_bf16 v[96:111], v[136:139], v[164:167], v[96:111]
	s_waitcnt lgkmcnt(2)
	v_mfma_f32_32x32x16_bf16 v[80:95], v[136:139], v[168:171], v[80:95]
	s_waitcnt lgkmcnt(1)
	v_mfma_f32_32x32x16_bf16 v[64:79], v[136:139], v[172:175], v[64:79]
	s_waitcnt lgkmcnt(0)
	v_mfma_f32_32x32x16_bf16 v[48:63], v[140:143], v[160:163], v[48:63]
	v_mfma_f32_32x32x16_bf16 v[32:47], v[140:143], v[164:167], v[32:47]
	v_mfma_f32_32x32x16_bf16 v[16:31], v[140:143], v[168:171], v[16:31]
	v_mfma_f32_32x32x16_bf16 v[0:15], v[140:143], v[172:175], v[0:15]
	s_nop 7
	v_readlane_b32 s64, v188, 0
	v_readlane_b32 s65, v188, 1
	v_readlane_b32 s66, v188, 2
	v_readlane_b32 s67, v188, 3
	v_readlane_b32 s68, v188, 4
	v_readlane_b32 s69, v188, 5
	v_readlane_b32 s70, v188, 6
	v_readlane_b32 s71, v188, 7
	v_readlane_b32 s72, v188, 8
	v_readlane_b32 s73, v188, 9
	v_readlane_b32 s74, v188, 10
	v_readlane_b32 s75, v188, 11
	v_readlane_b32 s76, v188, 12
	v_readlane_b32 s77, v188, 13
	v_readlane_b32 s78, v188, 14
	v_readlane_b32 s79, v188, 15
	s_nop 7
	s_waitcnt vmcnt(1)
	s_nop 0
	s_nop 0
	s_nop 0
	s_waitcnt vmcnt(0)
	s_nop 0
	v_add_u32_e32 v136, v169, v171
	s_nop 0
	v_add_u32_e32 v180, v169, v170
	s_nop 0
	s_nop 0
	s_nop 0
	s_nop 0
	s_nop 0
	s_nop 0
	s_nop 0
	s_nop 0
	s_nop 0
	s_nop 0
	s_nop 0
	s_waitcnt lgkmcnt(0)
	s_nop 0
	s_nop 0
	s_nop 0
	s_nop 0
	s_nop 0
	s_nop 0
	s_nop 0
	s_nop 0
	s_nop 0
	s_nop 0
	s_nop 0
	s_nop 0
	s_nop 0
	s_nop 0
	s_nop 0
	s_nop 0
	s_nop 0
	s_nop 0
	v_mov_b32_e32 v180, v196
	s_waitcnt lgkmcnt(0)
	s_nop 0
	s_nop 0
	v_ashrrev_i32_e32 v182, 1, v180
	v_and_b32_e32 v182, 0xffffffc0, v182
	v_add_u32_e32 v182, s59, v182
	v_lshrrev_b32_e32 v183, 3, v180
	v_and_b32_e32 v185, 31, v180
	v_and_or_b32 v184, v183, 4, v182
	v_lshlrev_b32_e32 v180, 1, v180
	v_and_b32_e32 v180, 0x80, v180
	v_lshlrev_b32_e32 v186, 10, v184
	v_or3_b32 v180, s58, v180, v185
	v_or_b32_e32 v197, 0x400, v186
	v_or_b32_e32 v199, 0x800, v186
	s_nop 0
	v_or_b32_e32 v204, v186, v180
	v_or_b32_e32 v206, v197, v180
	v_ashrrev_i32_e32 v205, 31, v204
	v_ashrrev_i32_e32 v207, 31, v206
	v_or_b32_e32 v187, 32, v180
	v_lshl_add_u64 v[182:183], v[204:205], 2, s[8:9]
	v_lshl_add_u64 v[206:207], v[206:207], 2, s[8:9]
	s_nop 0
	v_or_b32_e32 v212, v199, v180
	v_ashrrev_i32_e32 v213, 31, v212
	v_lshl_add_u64 v[212:213], v[212:213], 2, s[8:9]
	v_or_b32_e32 v224, 0xc00, v186
	v_or_b32_e32 v225, 0x2000, v186
	v_or_b32_e32 v214, v197, v187
	global_load_dword v216, v[182:183], off
	global_load_dword v217, v[206:207], off
	global_load_dword v218, v[212:213], off
	s_nop 0
	v_ashrrev_i32_e32 v205, 31, v186
	v_or_b32_e32 v206, v224, v180
	v_or_b32_e32 v212, v225, v180
	v_ashrrev_i32_e32 v215, 31, v214
	v_lshl_add_u64 v[204:205], v[204:205], 2, s[8:9]
	v_ashrrev_i32_e32 v207, 31, v206
	v_ashrrev_i32_e32 v213, 31, v212
	s_nop 0
	v_lshl_add_u64 v[214:215], v[214:215], 2, s[8:9]
	global_load_dword v219, v[204:205], off offset:128
	v_lshl_add_u64 v[206:207], v[206:207], 2, s[8:9]
	global_load_dword v214, v[214:215], off
	s_nop 0
	s_nop 0
	v_or_b32_e32 v188, v199, v187
	v_ashrrev_i32_e32 v189, 31, v188
	v_lshl_add_u64 v[188:189], v[188:189], 2, s[8:9]
	global_load_dword v215, v[188:189], off
	v_lshl_add_u64 v[188:189], v[212:213], 2, s[8:9]
	global_load_dword v206, v[206:207], off
	s_nop 0
	global_load_dword v207, v[188:189], off
	v_or_b32_e32 v188, v224, v187
	v_or_b32_e32 v190, v225, v187
	v_ashrrev_i32_e32 v189, 31, v188
	v_ashrrev_i32_e32 v191, 31, v190
	s_nop 0
	v_or_b32_e32 v192, 0x2400, v186
	v_lshl_add_u64 v[188:189], v[188:189], 2, s[8:9]
	v_lshl_add_u64 v[190:191], v[190:191], 2, s[8:9]
	global_load_dword v193, v[188:189], off
	v_or_b32_e32 v195, 0x2800, v186
	s_nop 0
	global_load_dword v200, v[190:191], off
	v_or_b32_e32 v188, v192, v180
	v_or_b32_e32 v190, v192, v187
	v_ashrrev_i32_e32 v189, 31, v188
	v_ashrrev_i32_e32 v191, 31, v190
	v_lshl_add_u64 v[188:189], v[188:189], 2, s[8:9]
	v_lshl_add_u64 v[190:191], v[190:191], 2, s[8:9]
	global_load_dword v194, v[188:189], off
	v_or_b32_e32 v201, 0x2c00, v186
	global_load_dword v190, v[190:191], off
	v_or_b32_e32 v188, v195, v180
	v_ashrrev_i32_e32 v189, 31, v188
	v_lshl_add_u64 v[188:189], v[188:189], 2, s[8:9]
	global_load_dword v191, v[188:189], off
	v_or_b32_e32 v188, v201, v180
	v_ashrrev_i32_e32 v189, 31, v188
	v_lshl_add_u64 v[188:189], v[188:189], 2, s[8:9]
	global_load_dword v202, v[188:189], off
	v_or_b32_e32 v188, v195, v187
	v_ashrrev_i32_e32 v189, 31, v188
	v_lshl_add_u64 v[188:189], v[188:189], 2, s[8:9]
	global_load_dword v203, v[188:189], off
	v_or_b32_e32 v188, v201, v187
	v_ashrrev_i32_e32 v189, 31, v188
	v_lshl_add_u64 v[188:189], v[188:189], 2, s[8:9]
	global_load_dword v212, v[188:189], off
	s_nop 0
	s_nop 0
	s_nop 0
	s_waitcnt vmcnt(15)
; DI bfr f2bf(float a) { return (bfr)(pack2(a, 0.f) & 0xffffu); }
; DI int crow(int reg, int h) { return (reg & 3) + 8 * (reg >> 2) + 4 * h; }
; template <bool FIRST, bool HAS_H>
; DI void phase_gemm_resid(const Params& p, const bfr* A, const bfr* Wt, const float* gnext, float* ss, char* smem) {
;     ...
; #pragma unroll
;     for (int i = 0; i < 2; ++i) {
; #pragma unroll
;       for (int qh = 0; qh < 2; ++qh) {
;         float rs[8];
; #pragma unroll
;         for (int q = 0; q < 8; ++q) rs[q] = 0.f;
; #pragma unroll
;         for (int jh = 0; jh < 2; ++jh) {
;           float xo[2][8];
; #pragma unroll
;           for (int jj = 0; jj < 2; ++jj)
; #pragma unroll
;             for (int q = 0; q < 8; ++q)
;               xo[jj][q] = xsrc[(rbase + i * 32 + crow(qh * 8 + q, 0)) * 1024 + cbase + (jh * 2 + jj) * 32];
; #pragma unroll
;           for (int q = 0; q < 8; ++q) {
;             const int o = (rbase + i * 32 + crow(qh * 8 + q, 0)) * 1024 + cbase;
; #pragma unroll
;             for (int jj = 0; jj < 2; ++jj) {
;               const int j = jh * 2 + jj;
;               const float xn = xo[jj][q] + acc[i][j][qh * 8 + q];
;               X[o + j * 32] = xn;
;               if (HAS_H) Hn[o + j * 32] = f2bf(xn * gnext[cbase + j * 32]);
;               rs[q] += xn * xn;
;             }
;           }
;         }
; #pragma unroll
;         for (int q = 0; q < 8; ++q) rs[q] = half32_sum_hi(rs[q]);
	s_nop 9
	v_add_f32_e32 v213, v112, v216
	v_add_co_u32_e32 v112, vcc, s23, v182
	s_waitcnt vmcnt(14)
	v_add_f32_e32 v217, v113, v217
	v_addc_co_u32_e32 v113, vcc, 0, v183, vcc
	v_add_co_u32_e32 v188, vcc, s24, v182
	s_nop 0
	s_nop 0
	v_addc_co_u32_e32 v189, vcc, 0, v183, vcc
	global_store_dword v[182:183], v213, off
	global_store_dword v[188:189], v217, off offset:-4096
	s_waitcnt vmcnt(11)
	v_add_f32_e32 v206, v115, v206
	s_nop 0
	v_add_f32_e32 v209, v114, v218
	v_add_co_u32_e32 v114, vcc, s25, v182
	s_nop 2
	v_add_f32_e32 v210, v98, v215
	v_addc_co_u32_e32 v115, vcc, 0, v183, vcc
	v_or_b32_e32 v98, 64, v180
	s_nop 0
	v_add_co_u32_e32 v172, vcc, s33, v182
	v_add_f32_e32 v216, v96, v219
	s_nop 0
	v_addc_co_u32_e32 v173, vcc, 0, v183, vcc
	v_add_co_u32_e32 v174, vcc, s36, v182
	s_nop 0
	s_nop 0
	v_addc_co_u32_e32 v175, vcc, 0, v183, vcc
	s_waitcnt vmcnt(10)
	v_add_f32_e32 v207, v116, v207
	v_or_b32_e32 v96, v197, v98
	v_add_f32_e32 v208, v97, v214
	s_waitcnt vmcnt(9)
	v_add_f32_e32 v193, v99, v193
	v_ashrrev_i32_e32 v97, 31, v96
	s_nop 0
	global_store_dword v[182:183], v216, off offset:128
	global_store_dword v[112:113], v208, off offset:128
	global_store_dword v[188:189], v209, off
	global_store_dword v[188:189], v210, off offset:128
	global_store_dword v[114:115], v206, off
	global_store_dword v[114:115], v193, off offset:128
	global_store_dword v[174:175], v207, off offset:-4096
	s_nop 0
	s_waitcnt vmcnt(15)
	v_add_f32_e32 v164, v100, v200
	v_add_co_u32_e32 v100, vcc, s37, v182
	s_waitcnt vmcnt(13)
	v_add_f32_e32 v166, v101, v190
	v_addc_co_u32_e32 v101, vcc, 0, v183, vcc
	s_waitcnt vmcnt(12)
	v_add_f32_e32 v167, v118, v191
	s_nop 0
	v_add_co_u32_e32 v116, vcc, s38, v182
	s_waitcnt vmcnt(10)
	v_add_f32_e32 v168, v102, v203
	v_or_b32_e32 v102, v199, v98
	v_or_b32_e32 v118, v224, v98
	v_add_f32_e32 v165, v117, v194
	v_addc_co_u32_e32 v117, vcc, 0, v183, vcc
	s_nop 0
	v_add_f32_e32 v160, v119, v202
	s_waitcnt vmcnt(9)
	v_add_f32_e32 v161, v103, v212
	v_ashrrev_i32_e32 v103, 31, v102
	v_ashrrev_i32_e32 v119, 31, v118
	global_store_dword v[172:173], v164, off offset:128
	global_store_dword v[174:175], v165, off
	global_store_dword v[174:175], v166, off offset:128
	s_nop 0
	v_or_b32_e32 v152, v225, v98
	v_or_b32_e32 v154, v192, v98
	v_ashrrev_i32_e32 v153, 31, v152
	v_ashrrev_i32_e32 v155, 31, v154
	v_or_b32_e32 v156, v195, v98
	global_store_dword v[116:117], v167, off offset:-4096
	global_store_dword v[100:101], v168, off offset:128
	global_store_dword v[116:117], v160, off
	global_store_dword v[116:117], v161, off offset:128
	v_lshl_add_u64 v[96:97], v[96:97], 2, s[8:9]
	v_lshl_add_u64 v[102:103], v[102:103], 2, s[8:9]
	v_lshl_add_u64 v[118:119], v[118:119], 2, s[8:9]
	v_lshl_add_u64 v[152:153], v[152:153], 2, s[8:9]
	v_lshl_add_u64 v[154:155], v[154:155], 2, s[8:9]
	v_ashrrev_i32_e32 v157, 31, v156
	v_or_b32_e32 v99, 0x60, v180
	v_lshl_add_u64 v[156:157], v[156:157], 2, s[8:9]
	global_load_dword v158, v[204:205], off offset:256
	global_load_dword v159, v[96:97], off
	global_load_dword v162, v[102:103], off
	s_nop 0
	global_load_dword v118, v[118:119], off
	s_nop 0
	global_load_dword v119, v[152:153], off
	s_nop 0
	global_load_dword v152, v[154:155], off
	global_load_dword v153, v[156:157], off
	s_nop 0
	global_load_dword v154, v[204:205], off offset:384
	v_or_b32_e32 v96, v197, v99
	v_or_b32_e32 v102, v192, v99
	v_ashrrev_i32_e32 v97, 31, v96
	v_ashrrev_i32_e32 v103, 31, v102
	v_lshl_add_u64 v[96:97], v[96:97], 2, s[8:9]
	v_lshl_add_u64 v[102:103], v[102:103], 2, s[8:9]
	s_nop 0
	v_cmp_eq_u32_e32 vcc, 31, v185
	v_ashrrev_i32_e32 v185, 31, v184
	s_nop 0
	global_load_dword v148, v[96:97], off
	s_waitcnt vmcnt(8)
	s_nop 6
	v_add_f32_e32 v80, v80, v158
	s_nop 0
	global_load_dword v142, v[102:103], off
	v_or_b32_e32 v96, v199, v99
	v_ashrrev_i32_e32 v97, 31, v96
	v_lshl_add_u64 v[96:97], v[96:97], 2, s[8:9]
	global_load_dword v149, v[96:97], off
	v_or_b32_e32 v96, v224, v99
	v_ashrrev_i32_e32 v97, 31, v96
	v_lshl_add_u64 v[96:97], v[96:97], 2, s[8:9]
	global_load_dword v140, v[96:97], off
	v_or_b32_e32 v96, v225, v99
	v_ashrrev_i32_e32 v97, 31, v96
	v_lshl_add_u64 v[96:97], v[96:97], 2, s[8:9]
	global_load_dword v141, v[96:97], off
	v_or_b32_e32 v96, v201, v98
	v_or_b32_e32 v102, v195, v99
	v_ashrrev_i32_e32 v97, 31, v96
	v_ashrrev_i32_e32 v103, 31, v102
	v_lshl_add_u64 v[96:97], v[96:97], 2, s[8:9]
	v_lshl_add_u64 v[102:103], v[102:103], 2, s[8:9]
	global_load_dword v102, v[102:103], off
	s_nop 0
	global_load_dword v103, v[96:97], off
	v_or_b32_e32 v96, v201, v99
	v_ashrrev_i32_e32 v97, 31, v96
	v_lshl_add_u64 v[96:97], v[96:97], 2, s[8:9]
	s_nop 0
	global_load_dword v136, v[96:97], off
	s_waitcnt vmcnt(8)
	v_add_f32_e32 v64, v64, v154
	global_store_dword v[182:183], v64, off offset:384
	global_store_dword v[182:183], v80, off offset:256
	v_lshl_add_u64 v[96:97], v[184:185], 2, s[10:11]
	s_nop 0
	s_nop 0
	v_mul_f32_e32 v128, v216, v216
	v_fmac_f32_e32 v128, v213, v213
	v_mul_f32_e32 v129, v208, v208
	v_fmac_f32_e32 v128, v80, v80
	v_fmac_f32_e32 v129, v217, v217
	v_fmac_f32_e32 v128, v64, v64
	v_add_f32_e32 v64, v81, v159
	v_mul_f32_e32 v130, v210, v210
	global_store_dword v[112:113], v64, off offset:256
	v_fmac_f32_e32 v129, v64, v64
	s_waitcnt vmcnt(10)
	v_add_f32_e32 v64, v65, v148
	v_fmac_f32_e32 v130, v209, v209
	global_store_dword v[112:113], v64, off offset:384
	v_fmac_f32_e32 v129, v64, v64
	v_add_f32_e32 v64, v82, v162
	v_mul_f32_e32 v131, v193, v193
	global_store_dword v[188:189], v64, off offset:256
	v_fmac_f32_e32 v130, v64, v64
	v_fmac_f32_e32 v131, v206, v206
	v_mul_f32_e32 v132, v164, v164
	v_fmac_f32_e32 v132, v207, v207
	v_mul_f32_e32 v133, v166, v166
	v_fmac_f32_e32 v133, v165, v165
	v_mul_f32_e32 v134, v168, v168
	v_fmac_f32_e32 v134, v167, v167
	v_mul_f32_e32 v135, v161, v161
	v_fmac_f32_e32 v135, v160, v160
	v_mov_b32_e32 v65, 0
	v_mov_b32_e32 v81, 0
	s_waitcnt vmcnt(10)
; DI bfr f2bf(float a) { return (bfr)(pack2(a, 0.f) & 0xffffu); }
; #define DPPF(v, ctrl, rmask) __builtin_bit_cast(float, __builtin_amdgcn_update_dpp(0, __builtin_bit_cast(int, (v)), (ctrl), (rmask), 0xf, false))
; DI int crow(int reg, int h) { return (reg & 3) + 8 * (reg >> 2) + 4 * h; }
; DI float row16_sum(float v) {
;   v += DPPF(v, 0xB1, 0xf);
;   v += DPPF(v, 0x4E, 0xf);
;   v += DPPF(v, 0x141, 0xf);
;   v += DPPF(v, 0x140, 0xf);
;   return v;
; }
; DI float half32_sum_hi(float v) {
;   v = row16_sum(v);
;   v += DPPF(v, 0x142, 0xa);
;   return v;
; template <bool FIRST, bool HAS_H>
; DI void phase_gemm_resid(const Params& p, const bfr* A, const bfr* Wt, const float* gnext, float* ss, char* smem) {
;     ...
;           for (int q = 0; q < 8; ++q) {
;             const int o = (rbase + i * 32 + crow(qh * 8 + q, 0)) * 1024 + cbase;
; #pragma unroll
;             for (int jj = 0; jj < 2; ++jj) {
;               const int j = jh * 2 + jj;
;               const float xn = xo[jj][q] + acc[i][j][qh * 8 + q];
;               X[o + j * 32] = xn;
;               if (HAS_H) Hn[o + j * 32] = f2bf(xn * gnext[cbase + j * 32]);
;               rs[q] += xn * xn;
;             }
;           }
;         }
; #pragma unroll
;         for (int q = 0; q < 8; ++q) rs[q] = half32_sum_hi(rs[q]);
;         if (r == 31) {
; #pragma unroll
;           for (int q = 0; q < 8; ++q) unsafeAtomicAdd(ss + rbase + i * 32 + crow(qh * 8 + q, 0), rs[q]);
;         }
	v_add_f32_e32 v64, v66, v149
	global_store_dword v[188:189], v64, off offset:384
	v_fmac_f32_e32 v130, v64, v64
	v_add_f32_e32 v64, v83, v118
	global_store_dword v[114:115], v64, off offset:256
	v_fmac_f32_e32 v131, v64, v64
	s_waitcnt vmcnt(11)
	v_add_f32_e32 v64, v67, v140
	global_store_dword v[114:115], v64, off offset:384
	v_fmac_f32_e32 v131, v64, v64
	v_add_f32_e32 v64, v84, v119
	global_store_dword v[172:173], v64, off offset:256
	v_fmac_f32_e32 v132, v64, v64
	s_waitcnt vmcnt(12)
	v_add_f32_e32 v64, v68, v141
	global_store_dword v[172:173], v64, off offset:384
	v_fmac_f32_e32 v132, v64, v64
	v_add_f32_e32 v64, v85, v152
	global_store_dword v[174:175], v64, off offset:256
	v_fmac_f32_e32 v133, v64, v64
	v_add_f32_e32 v64, v69, v142
	global_store_dword v[174:175], v64, off offset:384
	v_fmac_f32_e32 v133, v64, v64
	v_add_f32_e32 v64, v86, v153
	global_store_dword v[100:101], v64, off offset:256
	v_fmac_f32_e32 v134, v64, v64
	s_waitcnt vmcnt(15)
	v_add_f32_e32 v64, v70, v102
	global_store_dword v[100:101], v64, off offset:384
	v_fmac_f32_e32 v134, v64, v64
	s_waitcnt vmcnt(15)
	v_add_f32_e32 v64, v87, v103
	global_store_dword v[116:117], v64, off offset:256
	v_fmac_f32_e32 v135, v64, v64
	s_waitcnt vmcnt(15)
	v_add_f32_e32 v64, v71, v136
	v_fmac_f32_e32 v135, v64, v64
	global_store_dword v[116:117], v64, off offset:384
	v_add_f32_dpp v64, v128, v128 quad_perm:[1,0,3,2] row_mask:0xf bank_mask:0xf bound_ctrl:1
	v_add_f32_dpp v66, v129, v129 quad_perm:[1,0,3,2] row_mask:0xf bank_mask:0xf bound_ctrl:1
	v_add_f32_dpp v68, v130, v130 quad_perm:[1,0,3,2] row_mask:0xf bank_mask:0xf bound_ctrl:1
	v_add_f32_dpp v70, v131, v131 quad_perm:[1,0,3,2] row_mask:0xf bank_mask:0xf bound_ctrl:1
	v_add_f32_dpp v80, v132, v132 quad_perm:[1,0,3,2] row_mask:0xf bank_mask:0xf bound_ctrl:1
	v_add_f32_dpp v82, v133, v133 quad_perm:[1,0,3,2] row_mask:0xf bank_mask:0xf bound_ctrl:1
	v_add_f32_dpp v84, v134, v134 quad_perm:[1,0,3,2] row_mask:0xf bank_mask:0xf bound_ctrl:1
	v_add_f32_dpp v86, v135, v135 quad_perm:[1,0,3,2] row_mask:0xf bank_mask:0xf bound_ctrl:1
	v_add_f32_dpp v64, v64, v64 quad_perm:[2,3,0,1] row_mask:0xf bank_mask:0xf bound_ctrl:1
	v_add_f32_dpp v66, v66, v66 quad_perm:[2,3,0,1] row_mask:0xf bank_mask:0xf bound_ctrl:1
	v_add_f32_dpp v68, v68, v68 quad_perm:[2,3,0,1] row_mask:0xf bank_mask:0xf bound_ctrl:1
	v_add_f32_dpp v70, v70, v70 quad_perm:[2,3,0,1] row_mask:0xf bank_mask:0xf bound_ctrl:1
	v_add_f32_dpp v80, v80, v80 quad_perm:[2,3,0,1] row_mask:0xf bank_mask:0xf bound_ctrl:1
	v_add_f32_dpp v82, v82, v82 quad_perm:[2,3,0,1] row_mask:0xf bank_mask:0xf bound_ctrl:1
	v_add_f32_dpp v84, v84, v84 quad_perm:[2,3,0,1] row_mask:0xf bank_mask:0xf bound_ctrl:1
	v_add_f32_dpp v86, v86, v86 quad_perm:[2,3,0,1] row_mask:0xf bank_mask:0xf bound_ctrl:1
	v_add_f32_dpp v64, v64, v64 row_half_mirror row_mask:0xf bank_mask:0xf bound_ctrl:1
	v_add_f32_dpp v66, v66, v66 row_half_mirror row_mask:0xf bank_mask:0xf bound_ctrl:1
	v_add_f32_dpp v68, v68, v68 row_half_mirror row_mask:0xf bank_mask:0xf bound_ctrl:1
	v_add_f32_dpp v70, v70, v70 row_half_mirror row_mask:0xf bank_mask:0xf bound_ctrl:1
	v_add_f32_dpp v80, v80, v80 row_half_mirror row_mask:0xf bank_mask:0xf bound_ctrl:1
	v_add_f32_dpp v82, v82, v82 row_half_mirror row_mask:0xf bank_mask:0xf bound_ctrl:1
	v_add_f32_dpp v84, v84, v84 row_half_mirror row_mask:0xf bank_mask:0xf bound_ctrl:1
	v_add_f32_dpp v86, v86, v86 row_half_mirror row_mask:0xf bank_mask:0xf bound_ctrl:1
	v_add_f32_dpp v64, v64, v64 row_mirror row_mask:0xf bank_mask:0xf bound_ctrl:1
	v_add_f32_dpp v66, v66, v66 row_mirror row_mask:0xf bank_mask:0xf bound_ctrl:1
	v_mov_b32_e32 v67, 0
	v_add_f32_dpp v68, v68, v68 row_mirror row_mask:0xf bank_mask:0xf bound_ctrl:1
	v_mov_b32_e32 v69, 0
	v_add_f32_dpp v70, v70, v70 row_mirror row_mask:0xf bank_mask:0xf bound_ctrl:1
	v_mov_b32_e32 v71, 0
	v_add_f32_dpp v80, v80, v80 row_mirror row_mask:0xf bank_mask:0xf bound_ctrl:1
	v_add_f32_dpp v82, v82, v82 row_mirror row_mask:0xf bank_mask:0xf bound_ctrl:1
	v_mov_b32_e32 v83, 0
	v_add_f32_dpp v84, v84, v84 row_mirror row_mask:0xf bank_mask:0xf bound_ctrl:1
	v_mov_b32_e32 v85, 0
	v_add_f32_dpp v86, v86, v86 row_mirror row_mask:0xf bank_mask:0xf bound_ctrl:1
	v_mov_b32_e32 v87, 0
	v_mov_b32_dpp v65, v64 row_bcast:15 row_mask:0xa bank_mask:0xf
	v_mov_b32_dpp v67, v66 row_bcast:15 row_mask:0xa bank_mask:0xf
	v_mov_b32_dpp v69, v68 row_bcast:15 row_mask:0xa bank_mask:0xf
	v_mov_b32_dpp v71, v70 row_bcast:15 row_mask:0xa bank_mask:0xf
	v_mov_b32_dpp v81, v80 row_bcast:15 row_mask:0xa bank_mask:0xf
	v_mov_b32_dpp v83, v82 row_bcast:15 row_mask:0xa bank_mask:0xf
	v_mov_b32_dpp v85, v84 row_bcast:15 row_mask:0xa bank_mask:0xf
	v_mov_b32_dpp v87, v86 row_bcast:15 row_mask:0xa bank_mask:0xf
	s_and_saveexec_b64 s[4:5], vcc
	s_cbranch_execz .LBB0_1734
	v_add_f32_e32 v64, v64, v65
	v_add_f32_e32 v86, v86, v87
	v_add_f32_e32 v84, v84, v85
	v_add_f32_e32 v82, v82, v83
	v_add_f32_e32 v80, v80, v81
	v_add_f32_e32 v70, v70, v71
	v_add_f32_e32 v68, v68, v69
	v_add_f32_e32 v66, v66, v67
	global_atomic_add_f32 v[96:97], v64, off
	global_atomic_add_f32 v[96:97], v66, off offset:4
	global_atomic_add_f32 v[96:97], v68, off offset:8
	global_atomic_add_f32 v[96:97], v70, off offset:12
	global_atomic_add_f32 v[96:97], v80, off offset:32
	global_atomic_add_f32 v[96:97], v82, off offset:36
	global_atomic_add_f32 v[96:97], v84, off offset:40
	global_atomic_add_f32 v[96:97], v86, off offset:44
